# v55 + GEMM phases: one static s_setprio 1 for waves 4-7 instead of per-segment priority flips (72 flips removed)
# speedup vs baseline: 1.0066x; 1.0066x over previous
.LBB0_261:
	s_cmp_lt_i32 s92, 3
	s_cselect_b64 s[0:1], -1, 0
	s_waitcnt lgkmcnt(0)
	s_add_u32 s54, s38, 0x596c400
	s_addc_u32 s55, s39, 0
	s_and_b64 s[0:1], s[0:1], s[2:3]
	s_andn2_b64 vcc, exec, s[0:1]
	s_cbranch_vccnz .LBB0_274
	v_mov_b32_e32 v11, v184
	s_cmpk_gt_i32 s33, 0x77f
	v_readfirstlane_b32 s28, v11
	s_cbranch_scc1 .LBB0_274
	v_lshlrev_b32_e32 v1, 4, v11
	v_add_u32_e32 v2, 0x2000, v1
	v_ashrrev_i32_e32 v3, 31, v2
	v_lshrrev_b32_e32 v3, 22, v3
	v_add_u32_e32 v3, v2, v3
	v_ashrrev_i32_e32 v10, 10, v3
	v_mul_i32_i24_e32 v3, 0x400, v10
	v_sub_u32_e32 v2, v2, v3
	v_lshrrev_b32_e32 v3, 4, v2
	v_bitop3_b32 v2, v3, v2, 32 bitop3:0x6c
	v_ashrrev_i32_e32 v3, 31, v2
	v_lshrrev_b32_e32 v3, 26, v3
	v_add_u32_e32 v3, v2, v3
	v_lshlrev_b32_e32 v4, 3, v10
	v_ashrrev_i32_e32 v12, 6, v3
	v_and_b32_e32 v4, -16, v4
	v_add_u32_e32 v4, v12, v4
	v_and_b32_e32 v5, 3, v12
	s_mov_b32 s2, 0xfffe0
	v_lshrrev_b32_e32 v6, 2, v4
	v_lshlrev_b32_e32 v7, 1, v4
	v_and_b32_e32 v3, 0xc0, v3
	v_and_or_b32 v5, v4, s2, v5
	v_and_b32_e32 v6, 4, v6
	v_and_b32_e32 v7, 24, v7
	v_sub_u32_e32 v2, v2, v3
	v_mov_b32_e32 v3, 1
	v_or3_b32 v5, v5, v6, v7
	v_lshlrev_b32_e32 v6, 5, v10
	v_ashrrev_i16_sdwa v2, v3, sext(v2) dst_sel:DWORD dst_unused:UNUSED_PAD src0_sel:DWORD src1_sel:BYTE_0
	v_and_b32_e32 v6, 32, v6
	v_bfe_i32 v13, v2, 0, 16
	v_add_lshl_u32 v2, v6, v13, 1
	v_lshl_add_u32 v130, v5, 12, v2
	v_lshl_add_u32 v132, v4, 12, v2
	v_bfe_i32 v2, v11, 27, 1
	v_lshrrev_b32_e32 v2, 22, v2
	v_add_u32_e32 v2, v1, v2
	v_and_b32_e32 v2, 0xfffffc00, v2
	v_sub_u32_e32 v1, v1, v2
	v_lshrrev_b32_e32 v2, 4, v1
	v_ashrrev_i32_e32 v4, 31, v11
	v_bitop3_b32 v1, v2, v1, 32 bitop3:0x6c
	v_lshrrev_b32_e32 v4, 26, v4
	v_ashrrev_i32_e32 v2, 31, v1
	v_add_u32_e32 v4, v11, v4
	v_lshrrev_b32_e32 v2, 26, v2
	v_ashrrev_i32_e32 v15, 6, v4
	v_add_u32_e32 v2, v1, v2
	v_lshlrev_b32_e32 v4, 3, v15
	v_ashrrev_i32_e32 v14, 6, v2
	v_and_b32_e32 v4, -16, v4
	v_add_u32_e32 v4, v14, v4
	v_and_b32_e32 v5, 3, v14
	s_ashr_i32 s30, s33, 31
	v_and_or_b32 v5, v4, s2, v5
	s_lshr_b32 s2, s30, 29
	s_add_i32 s2, s33, s2
	s_ashr_i32 s4, s28, 6
	s_ashr_i32 s5, s2, 3
	s_and_b32 s2, s2, -8
	s_ashr_i32 s3, s28, 8
	s_lshl_b32 s29, s4, 10
	s_sub_i32 s2, s33, s2
	s_cmp_lt_i32 s2, 0
	s_movk_i32 s31, 0xf1
	s_cselect_b32 s6, s31, 0xf0
	s_mul_i32 s2, s2, s6
	s_add_i32 s2, s2, s5
	s_mul_hi_i32 s5, s2, 0x88888889
	s_add_i32 s5, s5, s2
	s_lshr_b32 s6, s5, 31
	s_ashr_i32 s5, s5, 6
	s_add_i32 s5, s5, s6
	s_lshl_b32 s6, s5, 3
	s_mulk_i32 s5, 0x78
	s_sub_i32 s5, s2, s5
	s_bfe_i32 s2, s5, 0x80000
	s_bfe_u32 s2, s2, 0x3000c
	s_add_i32 s7, s5, s2
	s_bfe_i32 s2, s7, 0x80000
	s_and_b32 s7, s7, 0xf8
	s_sub_i32 s5, s5, s7
	s_sext_i32_i16 s2, s2
	s_sext_i32_i8 s5, s5
	v_lshrrev_b32_e32 v6, 2, v4
	v_lshlrev_b32_e32 v7, 1, v4
	v_and_b32_e32 v2, 0xc0, v2
	s_lshr_b32 s2, s2, 3
	s_add_i32 s20, s6, s5
	v_and_b32_e32 v6, 4, v6
	v_and_b32_e32 v7, 24, v7
	v_sub_u32_e32 v1, v1, v2
	s_ashr_i32 s21, s20, 31
	s_bfe_i64 s[8:9], s[2:3], 0x100000
	v_or3_b32 v5, v5, v6, v7
	v_lshlrev_b32_e32 v6, 5, v15
	v_ashrrev_i16_sdwa v1, v3, sext(v1) dst_sel:DWORD dst_unused:UNUSED_PAD src0_sel:DWORD src1_sel:BYTE_0
	s_lshl_b64 s[6:7], s[20:21], 20
	s_lshl_b64 s[8:9], s[8:9], 20
	v_and_b32_e32 v6, 32, v6
	v_bfe_i32 v16, v1, 0, 16
	s_add_u32 s24, s38, s8
	v_add_lshl_u32 v1, v6, v16, 1
	s_addc_u32 s25, s39, s9
	s_add_i32 s21, s29, 0
	v_lshl_add_u32 v134, v5, 12, v1
	s_add_i32 m0, s21, 0x10000
	v_lshl_add_u32 v136, v4, 12, v1
	global_load_lds_dwordx4 v134, s[24:25]
	s_add_i32 m0, s21, 0x12000
	s_add_u32 s22, s88, s6
	global_load_lds_dwordx4 v130, s[24:25]
	s_addc_u32 s23, s89, s7
	s_mov_b32 m0, s21
	s_add_i32 s34, s21, 0x2000
	global_load_lds_dwordx4 v136, s[22:23]
	s_mov_b32 m0, s34
	s_add_u32 s6, s24, 0x80000
	global_load_lds_dwordx4 v132, s[22:23]
	s_addc_u32 s7, s25, 0
	s_add_i32 m0, s21, 0x14000
	v_mov_b32_e32 v135, 0
	global_load_lds_dwordx4 v134, s[6:7]
	s_add_i32 m0, s21, 0x16000
	v_mov_b32_e32 v131, v135
	global_load_lds_dwordx4 v130, s[6:7]
	s_add_u32 s6, s22, 0x80000
	s_addc_u32 s7, s23, 0
	s_add_i32 s35, s21, 0x4000
	s_mov_b32 m0, s35
	s_add_i32 s36, s21, 0x6000
	global_load_lds_dwordx4 v136, s[6:7]
	s_mov_b32 m0, s36
	v_mov_b32_e32 v137, v135
	global_load_lds_dwordx4 v132, s[6:7]
	v_mov_b32_e32 v133, v135
	s_mov_b32 s37, 0
	v_lshl_add_u64 v[8:9], s[24:25], 0, v[134:135]
	v_lshl_add_u64 v[6:7], s[24:25], 0, v[130:131]
	v_lshl_add_u64 v[4:5], s[22:23], 0, v[136:137]
	s_cmp_lg_u32 s3, 1
	v_lshl_add_u64 v[2:3], s[22:23], 0, v[132:133]
	s_cbranch_scc1 .LBB0_265
	s_setprio 1
	s_barrier

.LBB0_268:
	s_ashr_i32 s9, s8, 31
	v_cmp_lt_i64_e32 vcc, s[16:17], v[142:143]
	s_lshl_b64 s[16:17], s[8:9], 20
	s_add_u32 s16, s88, s16
	s_addc_u32 s17, s89, s17
	s_and_b64 s[18:19], vcc, exec
	s_cselect_b32 s9, s17, s23
	s_cselect_b32 s53, s16, s22
	s_ashr_i32 s7, s6, 31
	s_lshl_b64 s[18:19], s[6:7], 20
	s_add_u32 s18, s38, s18
	s_addc_u32 s19, s39, s19
	s_and_b64 s[26:27], vcc, exec
	s_cselect_b32 s7, s19, s25
	s_cselect_b32 s58, s18, s24
	s_add_u32 s22, s22, 0x80080
	s_addc_u32 s23, s23, 0
	s_add_u32 s59, s24, 0x100
	v_mov_b32_e32 v2, 0
	s_addc_u32 s60, s25, 0
	s_mov_b32 s61, -2
	v_mov_b32_e32 v3, v2
	v_mov_b32_e32 v4, v2
	v_mov_b32_e32 v5, v2
	v_mov_b32_e32 v6, v2
	v_mov_b32_e32 v7, v2
	v_mov_b32_e32 v8, v2
	v_mov_b32_e32 v9, v2
	v_mov_b32_e32 v10, v2
	v_mov_b32_e32 v11, v2
	v_mov_b32_e32 v12, v2
	v_mov_b32_e32 v13, v2
	v_mov_b32_e32 v18, v2
	v_mov_b32_e32 v19, v2
	v_mov_b32_e32 v20, v2
	v_mov_b32_e32 v21, v2
	v_mov_b32_e32 v26, v2
	v_mov_b32_e32 v27, v2
	v_mov_b32_e32 v28, v2
	v_mov_b32_e32 v29, v2
	v_mov_b32_e32 v34, v2
	v_mov_b32_e32 v35, v2
	v_mov_b32_e32 v36, v2
	v_mov_b32_e32 v37, v2
	v_mov_b32_e32 v42, v2
	v_mov_b32_e32 v43, v2
	v_mov_b32_e32 v44, v2
	v_mov_b32_e32 v45, v2
	v_mov_b32_e32 v50, v2
	v_mov_b32_e32 v51, v2
	v_mov_b32_e32 v52, v2
	v_mov_b32_e32 v53, v2
	v_mov_b32_e32 v14, v2
	v_mov_b32_e32 v15, v2
	v_mov_b32_e32 v16, v2
	v_mov_b32_e32 v17, v2
	v_mov_b32_e32 v22, v2
	v_mov_b32_e32 v23, v2
	v_mov_b32_e32 v24, v2
	v_mov_b32_e32 v25, v2
	v_mov_b32_e32 v30, v2
	v_mov_b32_e32 v31, v2
	v_mov_b32_e32 v32, v2
	v_mov_b32_e32 v33, v2
	v_mov_b32_e32 v38, v2
	v_mov_b32_e32 v39, v2
	v_mov_b32_e32 v40, v2
	v_mov_b32_e32 v41, v2
	v_mov_b32_e32 v46, v2
	v_mov_b32_e32 v47, v2
	v_mov_b32_e32 v48, v2
	v_mov_b32_e32 v49, v2
	v_mov_b32_e32 v54, v2
	v_mov_b32_e32 v55, v2
	v_mov_b32_e32 v56, v2
	v_mov_b32_e32 v57, v2
	v_mov_b32_e32 v58, v2
	v_mov_b32_e32 v59, v2
	v_mov_b32_e32 v60, v2
	v_mov_b32_e32 v61, v2
	v_mov_b32_e32 v62, v2
	v_mov_b32_e32 v63, v2
	v_mov_b32_e32 v64, v2
	v_mov_b32_e32 v65, v2
	v_mov_b32_e32 v66, v2
	v_mov_b32_e32 v67, v2
	v_mov_b32_e32 v68, v2
	v_mov_b32_e32 v69, v2
	v_mov_b32_e32 v70, v2
	v_mov_b32_e32 v71, v2
	v_mov_b32_e32 v72, v2
	v_mov_b32_e32 v73, v2
	v_mov_b32_e32 v74, v2
	v_mov_b32_e32 v75, v2
	v_mov_b32_e32 v76, v2
	v_mov_b32_e32 v77, v2
	v_mov_b32_e32 v82, v2
	v_mov_b32_e32 v83, v2
	v_mov_b32_e32 v84, v2
	v_mov_b32_e32 v85, v2
	v_mov_b32_e32 v90, v2
	v_mov_b32_e32 v91, v2
	v_mov_b32_e32 v92, v2
	v_mov_b32_e32 v93, v2
	v_mov_b32_e32 v98, v2
	v_mov_b32_e32 v99, v2
	v_mov_b32_e32 v100, v2
	v_mov_b32_e32 v101, v2
	v_mov_b32_e32 v106, v2
	v_mov_b32_e32 v107, v2
	v_mov_b32_e32 v108, v2
	v_mov_b32_e32 v109, v2
	v_mov_b32_e32 v114, v2
	v_mov_b32_e32 v115, v2
	v_mov_b32_e32 v116, v2
	v_mov_b32_e32 v117, v2
	v_mov_b32_e32 v78, v2
	v_mov_b32_e32 v79, v2
	v_mov_b32_e32 v80, v2
	v_mov_b32_e32 v81, v2
	v_mov_b32_e32 v86, v2
	v_mov_b32_e32 v87, v2
	v_mov_b32_e32 v88, v2
	v_mov_b32_e32 v89, v2
	v_mov_b32_e32 v94, v2
	v_mov_b32_e32 v95, v2
	v_mov_b32_e32 v96, v2
	v_mov_b32_e32 v97, v2
	v_mov_b32_e32 v102, v2
	v_mov_b32_e32 v103, v2
	v_mov_b32_e32 v104, v2
	v_mov_b32_e32 v105, v2
	v_mov_b32_e32 v110, v2
	v_mov_b32_e32 v111, v2
	v_mov_b32_e32 v112, v2
	v_mov_b32_e32 v113, v2
	v_mov_b32_e32 v118, v2
	v_mov_b32_e32 v119, v2
	v_mov_b32_e32 v120, v2
	v_mov_b32_e32 v121, v2
	v_mov_b32_e32 v122, v2
	v_mov_b32_e32 v123, v2
	v_mov_b32_e32 v124, v2
	v_mov_b32_e32 v125, v2
	v_mov_b32_e32 v126, v2
	v_mov_b32_e32 v127, v2
	v_mov_b32_e32 v128, v2
	v_mov_b32_e32 v129, v2
	s_cmp_eq_u32 s98, 0
	s_cbranch_scc1 .LBB0_269
	ds_read_b128 v[146:149], v152
	ds_read_b128 v[156:159], v152 offset:1024
	ds_read_b128 v[160:163], v152 offset:2048
	ds_read_b128 v[164:167], v152 offset:3072
	s_add_u32 s24, s22, 0xfff80080
	s_addc_u32 s25, s23, -1
	s_cmp_eq_u32 s61, 28
	s_cselect_b32 s27, s9, s25
	s_cselect_b32 s26, s53, s24
	s_cselect_b32 s25, s7, s60
	s_cselect_b32 s24, s58, s59
	s_add_i32 m0, s21, 0xc000
	ds_read_b128 v[168:171], v153
	ds_read_b128 v[172:175], v153 offset:1024
	ds_read_b128 v[176:179], v153 offset:2048
	ds_read_b128 v[180:183], v153 offset:3072
	ds_read_b128 v[186:189], v153 offset:4096
	ds_read_b128 v[190:193], v153 offset:5120
	ds_read_b128 v[194:197], v153 offset:6144
	ds_read_b128 v[198:201], v153 offset:7168
	ds_read_b128 v[202:205], v154
	ds_read_b128 v[206:209], v154 offset:1024
	ds_read_b128 v[210:213], v154 offset:2048
	ds_read_b128 v[214:217], v154 offset:3072
	global_load_lds_dwordx4 v138, s[22:23]
	s_add_i32 m0, s21, 0xe000
	s_nop 0
	global_load_lds_dwordx4 v140, s[22:23]
	s_waitcnt vmcnt(24)
	s_waitcnt lgkmcnt(0)
	s_barrier
	v_mfma_f32_16x16x32_bf16 v[126:129], v[146:149], v[168:171], v[126:129]
	v_mfma_f32_16x16x32_bf16 v[122:125], v[160:163], v[168:171], v[122:125]
	v_mfma_f32_16x16x32_bf16 v[118:121], v[146:149], v[176:179], v[118:121]
	v_mfma_f32_16x16x32_bf16 v[110:113], v[160:163], v[176:179], v[110:113]
	v_mfma_f32_16x16x32_bf16 v[102:105], v[146:149], v[186:189], v[102:105]
	v_mfma_f32_16x16x32_bf16 v[94:97], v[160:163], v[186:189], v[94:97]
	v_mfma_f32_16x16x32_bf16 v[86:89], v[146:149], v[194:197], v[86:89]
	v_mfma_f32_16x16x32_bf16 v[78:81], v[160:163], v[194:197], v[78:81]
	v_mfma_f32_16x16x32_bf16 v[126:129], v[156:159], v[172:175], v[126:129]
	v_mfma_f32_16x16x32_bf16 v[122:125], v[164:167], v[172:175], v[122:125]
	v_mfma_f32_16x16x32_bf16 v[118:121], v[156:159], v[180:183], v[118:121]
	v_mfma_f32_16x16x32_bf16 v[110:113], v[164:167], v[180:183], v[110:113]
	v_mfma_f32_16x16x32_bf16 v[102:105], v[156:159], v[190:193], v[102:105]
	v_mfma_f32_16x16x32_bf16 v[94:97], v[164:167], v[190:193], v[94:97]
	v_mfma_f32_16x16x32_bf16 v[86:89], v[156:159], v[198:201], v[86:89]
	v_mfma_f32_16x16x32_bf16 v[78:81], v[164:167], v[198:201], v[78:81]
	v_mfma_f32_16x16x32_bf16 v[114:117], v[202:205], v[168:171], v[114:117]
	v_mfma_f32_16x16x32_bf16 v[106:109], v[210:213], v[168:171], v[106:109]
	v_mfma_f32_16x16x32_bf16 v[98:101], v[202:205], v[176:179], v[98:101]
	v_mfma_f32_16x16x32_bf16 v[90:93], v[210:213], v[176:179], v[90:93]
	v_mfma_f32_16x16x32_bf16 v[82:85], v[202:205], v[186:189], v[82:85]
	v_mfma_f32_16x16x32_bf16 v[74:77], v[210:213], v[186:189], v[74:77]
	v_mfma_f32_16x16x32_bf16 v[70:73], v[202:205], v[194:197], v[70:73]
	v_mfma_f32_16x16x32_bf16 v[66:69], v[210:213], v[194:197], v[66:69]
	v_mfma_f32_16x16x32_bf16 v[114:117], v[206:209], v[172:175], v[114:117]
	v_mfma_f32_16x16x32_bf16 v[106:109], v[214:217], v[172:175], v[106:109]
	v_mfma_f32_16x16x32_bf16 v[98:101], v[206:209], v[180:183], v[98:101]
	v_mfma_f32_16x16x32_bf16 v[90:93], v[214:217], v[180:183], v[90:93]
	v_mfma_f32_16x16x32_bf16 v[82:85], v[206:209], v[190:193], v[82:85]
	v_mfma_f32_16x16x32_bf16 v[74:77], v[214:217], v[190:193], v[74:77]
	v_mfma_f32_16x16x32_bf16 v[70:73], v[206:209], v[198:201], v[70:73]
	v_mfma_f32_16x16x32_bf16 v[66:69], v[214:217], v[198:201], v[66:69]
	s_barrier
	s_add_i32 s68, s45, s29
	v_lshl_add_u64 v[218:219], s[24:25], 0, v[134:135]
	s_mov_b32 m0, s68
	global_load_lds_dwordx4 v134, s[24:25]
	v_lshl_add_u64 v[220:221], s[24:25], 0, v[130:131]
	s_add_i32 m0, s68, 0x2000
	s_nop 0
	global_load_lds_dwordx4 v130, s[24:25]
	s_mov_b32 m0, s21
	v_lshl_add_u64 v[222:223], s[26:27], 0, v[136:137]
	ds_read_b128 v[168:171], v153 offset:16384
	ds_read_b128 v[172:175], v153 offset:17408
	ds_read_b128 v[176:179], v153 offset:18432
	ds_read_b128 v[180:183], v153 offset:19456
	ds_read_b128 v[186:189], v153 offset:20480
	ds_read_b128 v[190:193], v153 offset:21504
	ds_read_b128 v[194:197], v153 offset:22528
	ds_read_b128 v[198:201], v153 offset:23552
	global_load_lds_dwordx4 v136, s[26:27]
	v_lshl_add_u64 v[224:225], s[26:27], 0, v[132:133]
	s_mov_b32 m0, s34
	s_nop 0
	global_load_lds_dwordx4 v132, s[26:27]
	s_waitcnt vmcnt(22)
	s_waitcnt lgkmcnt(0)
	s_barrier
	v_mfma_f32_16x16x32_bf16 v[62:65], v[146:149], v[168:171], v[62:65]
	v_mfma_f32_16x16x32_bf16 v[58:61], v[160:163], v[168:171], v[58:61]
	v_mfma_f32_16x16x32_bf16 v[54:57], v[146:149], v[176:179], v[54:57]
	v_mfma_f32_16x16x32_bf16 v[46:49], v[160:163], v[176:179], v[46:49]
	v_mfma_f32_16x16x32_bf16 v[38:41], v[146:149], v[186:189], v[38:41]
	v_mfma_f32_16x16x32_bf16 v[30:33], v[160:163], v[186:189], v[30:33]
	v_mfma_f32_16x16x32_bf16 v[22:25], v[146:149], v[194:197], v[22:25]
	v_mfma_f32_16x16x32_bf16 v[14:17], v[160:163], v[194:197], v[14:17]
	v_mfma_f32_16x16x32_bf16 v[62:65], v[156:159], v[172:175], v[62:65]
	v_mfma_f32_16x16x32_bf16 v[58:61], v[164:167], v[172:175], v[58:61]
	v_mfma_f32_16x16x32_bf16 v[54:57], v[156:159], v[180:183], v[54:57]
	v_mfma_f32_16x16x32_bf16 v[46:49], v[164:167], v[180:183], v[46:49]
	v_mfma_f32_16x16x32_bf16 v[38:41], v[156:159], v[190:193], v[38:41]
	v_mfma_f32_16x16x32_bf16 v[30:33], v[164:167], v[190:193], v[30:33]
	v_mfma_f32_16x16x32_bf16 v[22:25], v[156:159], v[198:201], v[22:25]
	v_mfma_f32_16x16x32_bf16 v[14:17], v[164:167], v[198:201], v[14:17]
	v_mfma_f32_16x16x32_bf16 v[50:53], v[202:205], v[168:171], v[50:53]
	v_mfma_f32_16x16x32_bf16 v[42:45], v[210:213], v[168:171], v[42:45]
	v_mfma_f32_16x16x32_bf16 v[34:37], v[202:205], v[176:179], v[34:37]
	v_mfma_f32_16x16x32_bf16 v[26:29], v[210:213], v[176:179], v[26:29]
	v_mfma_f32_16x16x32_bf16 v[18:21], v[202:205], v[186:189], v[18:21]
	v_mfma_f32_16x16x32_bf16 v[10:13], v[210:213], v[186:189], v[10:13]
	v_mfma_f32_16x16x32_bf16 v[6:9], v[202:205], v[194:197], v[6:9]
	v_mfma_f32_16x16x32_bf16 v[2:5], v[210:213], v[194:197], v[2:5]
	v_mfma_f32_16x16x32_bf16 v[50:53], v[206:209], v[172:175], v[50:53]
	v_mfma_f32_16x16x32_bf16 v[42:45], v[214:217], v[172:175], v[42:45]
	v_mfma_f32_16x16x32_bf16 v[34:37], v[206:209], v[180:183], v[34:37]
	v_mfma_f32_16x16x32_bf16 v[26:29], v[214:217], v[180:183], v[26:29]
	v_mfma_f32_16x16x32_bf16 v[18:21], v[206:209], v[190:193], v[18:21]
	v_mfma_f32_16x16x32_bf16 v[10:13], v[214:217], v[190:193], v[10:13]
	v_mfma_f32_16x16x32_bf16 v[6:9], v[206:209], v[198:201], v[6:9]
	v_mfma_f32_16x16x32_bf16 v[2:5], v[214:217], v[198:201], v[2:5]
	s_barrier
	s_add_u32 s68, s24, 0x80000
	s_addc_u32 s69, s25, 0
	s_add_i32 s70, s46, s29
	s_mov_b32 m0, s70
	s_nop 0
	global_load_lds_dwordx4 v134, s[68:69]
	s_add_i32 m0, s70, 0x2000
	s_nop 0
	global_load_lds_dwordx4 v130, s[68:69]
	s_add_i32 s68, 0, 0x18000
	v_add_u32_e32 v155, s68, v150
	ds_read_b128 v[146:149], v155
	ds_read_b128 v[156:159], v155 offset:1024
	ds_read_b128 v[160:163], v155 offset:2048
	ds_read_b128 v[164:167], v155 offset:3072
	s_add_u32 s26, s26, 0x80000
	s_addc_u32 s27, s27, 0
	s_mov_b32 m0, s35
	ds_read_b128 v[168:171], v153 offset:32768
	ds_read_b128 v[172:175], v153 offset:33792
	ds_read_b128 v[176:179], v153 offset:34816
	ds_read_b128 v[180:183], v153 offset:35840
	ds_read_b128 v[186:189], v153 offset:36864
	ds_read_b128 v[190:193], v153 offset:37888
	ds_read_b128 v[194:197], v153 offset:38912
	ds_read_b128 v[198:201], v153 offset:39936
	v_add_u32_e32 v214, 0x1c000, v150
	ds_read_b128 v[202:205], v214
	ds_read_b128 v[206:209], v214 offset:1024
	ds_read_b128 v[210:213], v214 offset:2048
	ds_read_b128 v[214:217], v214 offset:3072
	global_load_lds_dwordx4 v136, s[26:27]
	s_mov_b32 m0, s36
	s_nop 0
	global_load_lds_dwordx4 v132, s[26:27]
	s_waitcnt vmcnt(8)
	s_waitcnt lgkmcnt(0)
	s_barrier
	v_mfma_f32_16x16x32_bf16 v[126:129], v[146:149], v[168:171], v[126:129]
	v_mfma_f32_16x16x32_bf16 v[122:125], v[160:163], v[168:171], v[122:125]
	v_mfma_f32_16x16x32_bf16 v[118:121], v[146:149], v[176:179], v[118:121]
	v_mfma_f32_16x16x32_bf16 v[110:113], v[160:163], v[176:179], v[110:113]
	v_mfma_f32_16x16x32_bf16 v[102:105], v[146:149], v[186:189], v[102:105]
	v_mfma_f32_16x16x32_bf16 v[94:97], v[160:163], v[186:189], v[94:97]
	v_mfma_f32_16x16x32_bf16 v[86:89], v[146:149], v[194:197], v[86:89]
	v_mfma_f32_16x16x32_bf16 v[78:81], v[160:163], v[194:197], v[78:81]
	v_mfma_f32_16x16x32_bf16 v[126:129], v[156:159], v[172:175], v[126:129]
	v_mfma_f32_16x16x32_bf16 v[122:125], v[164:167], v[172:175], v[122:125]
	v_mfma_f32_16x16x32_bf16 v[118:121], v[156:159], v[180:183], v[118:121]
	v_mfma_f32_16x16x32_bf16 v[110:113], v[164:167], v[180:183], v[110:113]
	v_mfma_f32_16x16x32_bf16 v[102:105], v[156:159], v[190:193], v[102:105]
	v_mfma_f32_16x16x32_bf16 v[94:97], v[164:167], v[190:193], v[94:97]
	v_mfma_f32_16x16x32_bf16 v[86:89], v[156:159], v[198:201], v[86:89]
	v_mfma_f32_16x16x32_bf16 v[78:81], v[164:167], v[198:201], v[78:81]
	v_mfma_f32_16x16x32_bf16 v[114:117], v[202:205], v[168:171], v[114:117]
	v_mfma_f32_16x16x32_bf16 v[106:109], v[210:213], v[168:171], v[106:109]
	v_mfma_f32_16x16x32_bf16 v[98:101], v[202:205], v[176:179], v[98:101]
	v_mfma_f32_16x16x32_bf16 v[90:93], v[210:213], v[176:179], v[90:93]
	v_mfma_f32_16x16x32_bf16 v[82:85], v[202:205], v[186:189], v[82:85]
	v_mfma_f32_16x16x32_bf16 v[74:77], v[210:213], v[186:189], v[74:77]
	v_mfma_f32_16x16x32_bf16 v[70:73], v[202:205], v[194:197], v[70:73]
	v_mfma_f32_16x16x32_bf16 v[66:69], v[210:213], v[194:197], v[66:69]
	v_mfma_f32_16x16x32_bf16 v[114:117], v[206:209], v[172:175], v[114:117]
	v_mfma_f32_16x16x32_bf16 v[106:109], v[214:217], v[172:175], v[106:109]
	v_mfma_f32_16x16x32_bf16 v[98:101], v[206:209], v[180:183], v[98:101]
	v_mfma_f32_16x16x32_bf16 v[90:93], v[214:217], v[180:183], v[90:93]
	v_mfma_f32_16x16x32_bf16 v[82:85], v[206:209], v[190:193], v[82:85]
	v_mfma_f32_16x16x32_bf16 v[74:77], v[214:217], v[190:193], v[74:77]
	v_mfma_f32_16x16x32_bf16 v[70:73], v[206:209], v[198:201], v[70:73]
	v_mfma_f32_16x16x32_bf16 v[66:69], v[214:217], v[198:201], v[66:69]
	s_barrier
	s_add_i32 s26, 0, 0x1c000
	s_add_i32 s27, s68, s29
	v_lshl_add_u64 v[218:219], v[218:219], 0, s[4:5]
	s_mov_b32 m0, s27
	global_load_lds_dwordx4 v[218:219], off
	v_lshl_add_u64 v[218:219], v[220:221], 0, s[4:5]
	s_add_i32 m0, s27, 0x2000
	s_nop 0
	global_load_lds_dwordx4 v[218:219], off
	s_mov_b32 m0, s41
	v_lshl_add_u64 v[218:219], v[222:223], 0, s[4:5]
	ds_read_b128 v[168:171], v153 offset:49152
	ds_read_b128 v[172:175], v153 offset:50176
	ds_read_b128 v[176:179], v153 offset:51200
	ds_read_b128 v[180:183], v153 offset:52224
	ds_read_b128 v[186:189], v153 offset:53248
	ds_read_b128 v[190:193], v153 offset:54272
	ds_read_b128 v[194:197], v153 offset:55296
	ds_read_b128 v[198:201], v153 offset:56320
	global_load_lds_dwordx4 v[218:219], off
	v_lshl_add_u64 v[218:219], v[224:225], 0, s[4:5]
	s_mov_b32 m0, s42
	s_nop 0
	global_load_lds_dwordx4 v[218:219], off
	s_add_u32 s24, s24, 0x80080
	s_addc_u32 s25, s25, 0
	s_add_i32 s26, s26, s29
	s_mov_b32 m0, s26
	s_nop 0
	global_load_lds_dwordx4 v134, s[24:25]
	s_add_i32 m0, s26, 0x2000
	s_nop 0
	global_load_lds_dwordx4 v130, s[24:25]
	s_waitcnt vmcnt(8)
	s_waitcnt lgkmcnt(0)
	s_barrier
	v_mfma_f32_16x16x32_bf16 v[62:65], v[146:149], v[168:171], v[62:65]
	v_mfma_f32_16x16x32_bf16 v[58:61], v[160:163], v[168:171], v[58:61]
	v_mfma_f32_16x16x32_bf16 v[54:57], v[146:149], v[176:179], v[54:57]
	v_mfma_f32_16x16x32_bf16 v[46:49], v[160:163], v[176:179], v[46:49]
	v_mfma_f32_16x16x32_bf16 v[38:41], v[146:149], v[186:189], v[38:41]
	v_mfma_f32_16x16x32_bf16 v[30:33], v[160:163], v[186:189], v[30:33]
	v_mfma_f32_16x16x32_bf16 v[22:25], v[146:149], v[194:197], v[22:25]
	v_mfma_f32_16x16x32_bf16 v[14:17], v[160:163], v[194:197], v[14:17]
	v_mfma_f32_16x16x32_bf16 v[62:65], v[156:159], v[172:175], v[62:65]
	v_mfma_f32_16x16x32_bf16 v[58:61], v[164:167], v[172:175], v[58:61]
	v_mfma_f32_16x16x32_bf16 v[54:57], v[156:159], v[180:183], v[54:57]
	v_mfma_f32_16x16x32_bf16 v[46:49], v[164:167], v[180:183], v[46:49]
	v_mfma_f32_16x16x32_bf16 v[38:41], v[156:159], v[190:193], v[38:41]
	v_mfma_f32_16x16x32_bf16 v[30:33], v[164:167], v[190:193], v[30:33]
	v_mfma_f32_16x16x32_bf16 v[22:25], v[156:159], v[198:201], v[22:25]
	v_mfma_f32_16x16x32_bf16 v[14:17], v[164:167], v[198:201], v[14:17]
	v_mfma_f32_16x16x32_bf16 v[50:53], v[202:205], v[168:171], v[50:53]
	v_mfma_f32_16x16x32_bf16 v[42:45], v[210:213], v[168:171], v[42:45]
	v_mfma_f32_16x16x32_bf16 v[34:37], v[202:205], v[176:179], v[34:37]
	v_mfma_f32_16x16x32_bf16 v[26:29], v[210:213], v[176:179], v[26:29]
	v_mfma_f32_16x16x32_bf16 v[18:21], v[202:205], v[186:189], v[18:21]
	v_mfma_f32_16x16x32_bf16 v[10:13], v[210:213], v[186:189], v[10:13]
	v_mfma_f32_16x16x32_bf16 v[6:9], v[202:205], v[194:197], v[6:9]
	v_mfma_f32_16x16x32_bf16 v[2:5], v[210:213], v[194:197], v[2:5]
	v_mfma_f32_16x16x32_bf16 v[50:53], v[206:209], v[172:175], v[50:53]
	v_mfma_f32_16x16x32_bf16 v[42:45], v[214:217], v[172:175], v[42:45]
	v_mfma_f32_16x16x32_bf16 v[34:37], v[206:209], v[180:183], v[34:37]
	v_mfma_f32_16x16x32_bf16 v[26:29], v[214:217], v[180:183], v[26:29]
	v_mfma_f32_16x16x32_bf16 v[18:21], v[206:209], v[190:193], v[18:21]
	v_mfma_f32_16x16x32_bf16 v[10:13], v[214:217], v[190:193], v[10:13]
	v_mfma_f32_16x16x32_bf16 v[6:9], v[206:209], v[198:201], v[6:9]
	v_mfma_f32_16x16x32_bf16 v[2:5], v[214:217], v[198:201], v[2:5]
	s_add_i32 s61, s61, 2
	s_add_u32 s22, s22, 0x100
	s_addc_u32 s23, s23, 0
	s_add_u32 s59, s59, 0x100
	s_addc_u32 s60, s60, 0
	s_cmp_gt_u32 s61, 29
	s_barrier
	s_cbranch_scc1 .Lgemm_epi_0
.LBB0_269:
	ds_read_b128 v[146:149], v152
	ds_read_b128 v[156:159], v152 offset:1024
	ds_read_b128 v[160:163], v152 offset:2048
	ds_read_b128 v[164:167], v152 offset:3072
	s_add_u32 s24, s22, 0xfff80080
	s_addc_u32 s25, s23, -1
	s_cmp_eq_u32 s61, 28
	s_cselect_b32 s27, s9, s25
	s_cselect_b32 s26, s53, s24
	s_cselect_b32 s25, s7, s60
	s_cselect_b32 s24, s58, s59
	s_add_i32 m0, s21, 0xc000
	ds_read_b128 v[168:171], v153
	ds_read_b128 v[172:175], v153 offset:1024
	ds_read_b128 v[176:179], v153 offset:2048
	ds_read_b128 v[180:183], v153 offset:3072
	ds_read_b128 v[186:189], v153 offset:4096
	ds_read_b128 v[190:193], v153 offset:5120
	ds_read_b128 v[194:197], v153 offset:6144
	ds_read_b128 v[198:201], v153 offset:7168
	ds_read_b128 v[202:205], v154
	ds_read_b128 v[206:209], v154 offset:1024
	ds_read_b128 v[210:213], v154 offset:2048
	ds_read_b128 v[214:217], v154 offset:3072
	global_load_lds_dwordx4 v138, s[22:23]
	s_add_i32 m0, s21, 0xe000
	s_nop 0
	global_load_lds_dwordx4 v140, s[22:23]
	s_waitcnt vmcnt(8)
	s_waitcnt lgkmcnt(0)
	s_barrier
	v_mfma_f32_16x16x32_bf16 v[126:129], v[146:149], v[168:171], v[126:129]
	v_mfma_f32_16x16x32_bf16 v[122:125], v[160:163], v[168:171], v[122:125]
	v_mfma_f32_16x16x32_bf16 v[118:121], v[146:149], v[176:179], v[118:121]
	v_mfma_f32_16x16x32_bf16 v[110:113], v[160:163], v[176:179], v[110:113]
	v_mfma_f32_16x16x32_bf16 v[102:105], v[146:149], v[186:189], v[102:105]
	v_mfma_f32_16x16x32_bf16 v[94:97], v[160:163], v[186:189], v[94:97]
	v_mfma_f32_16x16x32_bf16 v[86:89], v[146:149], v[194:197], v[86:89]
	v_mfma_f32_16x16x32_bf16 v[78:81], v[160:163], v[194:197], v[78:81]
	v_mfma_f32_16x16x32_bf16 v[126:129], v[156:159], v[172:175], v[126:129]
	v_mfma_f32_16x16x32_bf16 v[122:125], v[164:167], v[172:175], v[122:125]
	v_mfma_f32_16x16x32_bf16 v[118:121], v[156:159], v[180:183], v[118:121]
	v_mfma_f32_16x16x32_bf16 v[110:113], v[164:167], v[180:183], v[110:113]
	v_mfma_f32_16x16x32_bf16 v[102:105], v[156:159], v[190:193], v[102:105]
	v_mfma_f32_16x16x32_bf16 v[94:97], v[164:167], v[190:193], v[94:97]
	v_mfma_f32_16x16x32_bf16 v[86:89], v[156:159], v[198:201], v[86:89]
	v_mfma_f32_16x16x32_bf16 v[78:81], v[164:167], v[198:201], v[78:81]
	v_mfma_f32_16x16x32_bf16 v[114:117], v[202:205], v[168:171], v[114:117]
	v_mfma_f32_16x16x32_bf16 v[106:109], v[210:213], v[168:171], v[106:109]
	v_mfma_f32_16x16x32_bf16 v[98:101], v[202:205], v[176:179], v[98:101]
	v_mfma_f32_16x16x32_bf16 v[90:93], v[210:213], v[176:179], v[90:93]
	v_mfma_f32_16x16x32_bf16 v[82:85], v[202:205], v[186:189], v[82:85]
	v_mfma_f32_16x16x32_bf16 v[74:77], v[210:213], v[186:189], v[74:77]
	v_mfma_f32_16x16x32_bf16 v[70:73], v[202:205], v[194:197], v[70:73]
	v_mfma_f32_16x16x32_bf16 v[66:69], v[210:213], v[194:197], v[66:69]
	v_mfma_f32_16x16x32_bf16 v[114:117], v[206:209], v[172:175], v[114:117]
	v_mfma_f32_16x16x32_bf16 v[106:109], v[214:217], v[172:175], v[106:109]
	v_mfma_f32_16x16x32_bf16 v[98:101], v[206:209], v[180:183], v[98:101]
	v_mfma_f32_16x16x32_bf16 v[90:93], v[214:217], v[180:183], v[90:93]
	v_mfma_f32_16x16x32_bf16 v[82:85], v[206:209], v[190:193], v[82:85]
	v_mfma_f32_16x16x32_bf16 v[74:77], v[214:217], v[190:193], v[74:77]
	v_mfma_f32_16x16x32_bf16 v[70:73], v[206:209], v[198:201], v[70:73]
	v_mfma_f32_16x16x32_bf16 v[66:69], v[214:217], v[198:201], v[66:69]
	s_barrier
	s_add_i32 s68, s45, s29
	v_lshl_add_u64 v[218:219], s[24:25], 0, v[134:135]
	s_mov_b32 m0, s68
	global_load_lds_dwordx4 v134, s[24:25]
	v_lshl_add_u64 v[220:221], s[24:25], 0, v[130:131]
	s_add_i32 m0, s68, 0x2000
	s_nop 0
	global_load_lds_dwordx4 v130, s[24:25]
	s_mov_b32 m0, s21
	v_lshl_add_u64 v[222:223], s[26:27], 0, v[136:137]
	ds_read_b128 v[168:171], v153 offset:16384
	ds_read_b128 v[172:175], v153 offset:17408
	ds_read_b128 v[176:179], v153 offset:18432
	ds_read_b128 v[180:183], v153 offset:19456
	ds_read_b128 v[186:189], v153 offset:20480
	ds_read_b128 v[190:193], v153 offset:21504
	ds_read_b128 v[194:197], v153 offset:22528
	ds_read_b128 v[198:201], v153 offset:23552
	global_load_lds_dwordx4 v136, s[26:27]
	v_lshl_add_u64 v[224:225], s[26:27], 0, v[132:133]
	s_mov_b32 m0, s34
	s_nop 0
	global_load_lds_dwordx4 v132, s[26:27]
	s_waitcnt vmcnt(6)
	s_waitcnt lgkmcnt(0)
	s_barrier
	v_mfma_f32_16x16x32_bf16 v[62:65], v[146:149], v[168:171], v[62:65]
	v_mfma_f32_16x16x32_bf16 v[58:61], v[160:163], v[168:171], v[58:61]
	v_mfma_f32_16x16x32_bf16 v[54:57], v[146:149], v[176:179], v[54:57]
	v_mfma_f32_16x16x32_bf16 v[46:49], v[160:163], v[176:179], v[46:49]
	v_mfma_f32_16x16x32_bf16 v[38:41], v[146:149], v[186:189], v[38:41]
	v_mfma_f32_16x16x32_bf16 v[30:33], v[160:163], v[186:189], v[30:33]
	v_mfma_f32_16x16x32_bf16 v[22:25], v[146:149], v[194:197], v[22:25]
	v_mfma_f32_16x16x32_bf16 v[14:17], v[160:163], v[194:197], v[14:17]
	v_mfma_f32_16x16x32_bf16 v[62:65], v[156:159], v[172:175], v[62:65]
	v_mfma_f32_16x16x32_bf16 v[58:61], v[164:167], v[172:175], v[58:61]
	v_mfma_f32_16x16x32_bf16 v[54:57], v[156:159], v[180:183], v[54:57]
	v_mfma_f32_16x16x32_bf16 v[46:49], v[164:167], v[180:183], v[46:49]
	v_mfma_f32_16x16x32_bf16 v[38:41], v[156:159], v[190:193], v[38:41]
	v_mfma_f32_16x16x32_bf16 v[30:33], v[164:167], v[190:193], v[30:33]
	v_mfma_f32_16x16x32_bf16 v[22:25], v[156:159], v[198:201], v[22:25]
	v_mfma_f32_16x16x32_bf16 v[14:17], v[164:167], v[198:201], v[14:17]
	v_mfma_f32_16x16x32_bf16 v[50:53], v[202:205], v[168:171], v[50:53]
	v_mfma_f32_16x16x32_bf16 v[42:45], v[210:213], v[168:171], v[42:45]
	v_mfma_f32_16x16x32_bf16 v[34:37], v[202:205], v[176:179], v[34:37]
	v_mfma_f32_16x16x32_bf16 v[26:29], v[210:213], v[176:179], v[26:29]
	v_mfma_f32_16x16x32_bf16 v[18:21], v[202:205], v[186:189], v[18:21]
	v_mfma_f32_16x16x32_bf16 v[10:13], v[210:213], v[186:189], v[10:13]
	v_mfma_f32_16x16x32_bf16 v[6:9], v[202:205], v[194:197], v[6:9]
	v_mfma_f32_16x16x32_bf16 v[2:5], v[210:213], v[194:197], v[2:5]
	v_mfma_f32_16x16x32_bf16 v[50:53], v[206:209], v[172:175], v[50:53]
	v_mfma_f32_16x16x32_bf16 v[42:45], v[214:217], v[172:175], v[42:45]
	v_mfma_f32_16x16x32_bf16 v[34:37], v[206:209], v[180:183], v[34:37]
	v_mfma_f32_16x16x32_bf16 v[26:29], v[214:217], v[180:183], v[26:29]
	v_mfma_f32_16x16x32_bf16 v[18:21], v[206:209], v[190:193], v[18:21]
	v_mfma_f32_16x16x32_bf16 v[10:13], v[214:217], v[190:193], v[10:13]
	v_mfma_f32_16x16x32_bf16 v[6:9], v[206:209], v[198:201], v[6:9]
	v_mfma_f32_16x16x32_bf16 v[2:5], v[214:217], v[198:201], v[2:5]
	s_barrier
	s_add_u32 s68, s24, 0x80000
	s_addc_u32 s69, s25, 0
	s_add_i32 s70, s46, s29
	s_mov_b32 m0, s70
	s_nop 0
	global_load_lds_dwordx4 v134, s[68:69]
	s_add_i32 m0, s70, 0x2000
	s_nop 0
	global_load_lds_dwordx4 v130, s[68:69]
	s_add_i32 s68, 0, 0x18000
	v_add_u32_e32 v155, s68, v150
	ds_read_b128 v[146:149], v155
	ds_read_b128 v[156:159], v155 offset:1024
	ds_read_b128 v[160:163], v155 offset:2048
	ds_read_b128 v[164:167], v155 offset:3072
	s_add_u32 s26, s26, 0x80000
	s_addc_u32 s27, s27, 0
	s_mov_b32 m0, s35
	ds_read_b128 v[168:171], v153 offset:32768
	ds_read_b128 v[172:175], v153 offset:33792
	ds_read_b128 v[176:179], v153 offset:34816
	ds_read_b128 v[180:183], v153 offset:35840
	ds_read_b128 v[186:189], v153 offset:36864
	ds_read_b128 v[190:193], v153 offset:37888
	ds_read_b128 v[194:197], v153 offset:38912
	ds_read_b128 v[198:201], v153 offset:39936
	v_add_u32_e32 v214, 0x1c000, v150
	ds_read_b128 v[202:205], v214
	ds_read_b128 v[206:209], v214 offset:1024
	ds_read_b128 v[210:213], v214 offset:2048
	ds_read_b128 v[214:217], v214 offset:3072
	global_load_lds_dwordx4 v136, s[26:27]
	s_mov_b32 m0, s36
	s_nop 0
	global_load_lds_dwordx4 v132, s[26:27]
	s_waitcnt vmcnt(8)
	s_waitcnt lgkmcnt(0)
	s_barrier
	v_mfma_f32_16x16x32_bf16 v[126:129], v[146:149], v[168:171], v[126:129]
	v_mfma_f32_16x16x32_bf16 v[122:125], v[160:163], v[168:171], v[122:125]
	v_mfma_f32_16x16x32_bf16 v[118:121], v[146:149], v[176:179], v[118:121]
	v_mfma_f32_16x16x32_bf16 v[110:113], v[160:163], v[176:179], v[110:113]
	v_mfma_f32_16x16x32_bf16 v[102:105], v[146:149], v[186:189], v[102:105]
	v_mfma_f32_16x16x32_bf16 v[94:97], v[160:163], v[186:189], v[94:97]
	v_mfma_f32_16x16x32_bf16 v[86:89], v[146:149], v[194:197], v[86:89]
	v_mfma_f32_16x16x32_bf16 v[78:81], v[160:163], v[194:197], v[78:81]
	v_mfma_f32_16x16x32_bf16 v[126:129], v[156:159], v[172:175], v[126:129]
	v_mfma_f32_16x16x32_bf16 v[122:125], v[164:167], v[172:175], v[122:125]
	v_mfma_f32_16x16x32_bf16 v[118:121], v[156:159], v[180:183], v[118:121]
	v_mfma_f32_16x16x32_bf16 v[110:113], v[164:167], v[180:183], v[110:113]
	v_mfma_f32_16x16x32_bf16 v[102:105], v[156:159], v[190:193], v[102:105]
	v_mfma_f32_16x16x32_bf16 v[94:97], v[164:167], v[190:193], v[94:97]
	v_mfma_f32_16x16x32_bf16 v[86:89], v[156:159], v[198:201], v[86:89]
	v_mfma_f32_16x16x32_bf16 v[78:81], v[164:167], v[198:201], v[78:81]
	v_mfma_f32_16x16x32_bf16 v[114:117], v[202:205], v[168:171], v[114:117]
	v_mfma_f32_16x16x32_bf16 v[106:109], v[210:213], v[168:171], v[106:109]
	v_mfma_f32_16x16x32_bf16 v[98:101], v[202:205], v[176:179], v[98:101]
	v_mfma_f32_16x16x32_bf16 v[90:93], v[210:213], v[176:179], v[90:93]
	v_mfma_f32_16x16x32_bf16 v[82:85], v[202:205], v[186:189], v[82:85]
	v_mfma_f32_16x16x32_bf16 v[74:77], v[210:213], v[186:189], v[74:77]
	v_mfma_f32_16x16x32_bf16 v[70:73], v[202:205], v[194:197], v[70:73]
	v_mfma_f32_16x16x32_bf16 v[66:69], v[210:213], v[194:197], v[66:69]
	v_mfma_f32_16x16x32_bf16 v[114:117], v[206:209], v[172:175], v[114:117]
	v_mfma_f32_16x16x32_bf16 v[106:109], v[214:217], v[172:175], v[106:109]
	v_mfma_f32_16x16x32_bf16 v[98:101], v[206:209], v[180:183], v[98:101]
	v_mfma_f32_16x16x32_bf16 v[90:93], v[214:217], v[180:183], v[90:93]
	v_mfma_f32_16x16x32_bf16 v[82:85], v[206:209], v[190:193], v[82:85]
	v_mfma_f32_16x16x32_bf16 v[74:77], v[214:217], v[190:193], v[74:77]
	v_mfma_f32_16x16x32_bf16 v[70:73], v[206:209], v[198:201], v[70:73]
	v_mfma_f32_16x16x32_bf16 v[66:69], v[214:217], v[198:201], v[66:69]
	s_barrier
	s_add_i32 s26, 0, 0x1c000
	s_add_i32 s27, s68, s29
	v_lshl_add_u64 v[218:219], v[218:219], 0, s[4:5]
	s_mov_b32 m0, s27
	global_load_lds_dwordx4 v[218:219], off
	v_lshl_add_u64 v[218:219], v[220:221], 0, s[4:5]
	s_add_i32 m0, s27, 0x2000
	s_nop 0
	global_load_lds_dwordx4 v[218:219], off
	s_mov_b32 m0, s41
	v_lshl_add_u64 v[218:219], v[222:223], 0, s[4:5]
	ds_read_b128 v[168:171], v153 offset:49152
	ds_read_b128 v[172:175], v153 offset:50176
	ds_read_b128 v[176:179], v153 offset:51200
	ds_read_b128 v[180:183], v153 offset:52224
	ds_read_b128 v[186:189], v153 offset:53248
	ds_read_b128 v[190:193], v153 offset:54272
	ds_read_b128 v[194:197], v153 offset:55296
	ds_read_b128 v[198:201], v153 offset:56320
	global_load_lds_dwordx4 v[218:219], off
	v_lshl_add_u64 v[218:219], v[224:225], 0, s[4:5]
	s_mov_b32 m0, s42
	s_nop 0
	global_load_lds_dwordx4 v[218:219], off
	s_add_u32 s24, s24, 0x80080
	s_addc_u32 s25, s25, 0
	s_add_i32 s26, s26, s29
	s_mov_b32 m0, s26
	s_nop 0
	global_load_lds_dwordx4 v134, s[24:25]
	s_add_i32 m0, s26, 0x2000
	s_nop 0
	global_load_lds_dwordx4 v130, s[24:25]
	s_waitcnt vmcnt(8)
	s_waitcnt lgkmcnt(0)
	s_barrier
	v_mfma_f32_16x16x32_bf16 v[62:65], v[146:149], v[168:171], v[62:65]
	v_mfma_f32_16x16x32_bf16 v[58:61], v[160:163], v[168:171], v[58:61]
	v_mfma_f32_16x16x32_bf16 v[54:57], v[146:149], v[176:179], v[54:57]
	v_mfma_f32_16x16x32_bf16 v[46:49], v[160:163], v[176:179], v[46:49]
	v_mfma_f32_16x16x32_bf16 v[38:41], v[146:149], v[186:189], v[38:41]
	v_mfma_f32_16x16x32_bf16 v[30:33], v[160:163], v[186:189], v[30:33]
	v_mfma_f32_16x16x32_bf16 v[22:25], v[146:149], v[194:197], v[22:25]
	v_mfma_f32_16x16x32_bf16 v[14:17], v[160:163], v[194:197], v[14:17]
	v_mfma_f32_16x16x32_bf16 v[62:65], v[156:159], v[172:175], v[62:65]
	v_mfma_f32_16x16x32_bf16 v[58:61], v[164:167], v[172:175], v[58:61]
	v_mfma_f32_16x16x32_bf16 v[54:57], v[156:159], v[180:183], v[54:57]
	v_mfma_f32_16x16x32_bf16 v[46:49], v[164:167], v[180:183], v[46:49]
	v_mfma_f32_16x16x32_bf16 v[38:41], v[156:159], v[190:193], v[38:41]
	v_mfma_f32_16x16x32_bf16 v[30:33], v[164:167], v[190:193], v[30:33]
	v_mfma_f32_16x16x32_bf16 v[22:25], v[156:159], v[198:201], v[22:25]
	v_mfma_f32_16x16x32_bf16 v[14:17], v[164:167], v[198:201], v[14:17]
	v_mfma_f32_16x16x32_bf16 v[50:53], v[202:205], v[168:171], v[50:53]
	v_mfma_f32_16x16x32_bf16 v[42:45], v[210:213], v[168:171], v[42:45]
	v_mfma_f32_16x16x32_bf16 v[34:37], v[202:205], v[176:179], v[34:37]
	v_mfma_f32_16x16x32_bf16 v[26:29], v[210:213], v[176:179], v[26:29]
	v_mfma_f32_16x16x32_bf16 v[18:21], v[202:205], v[186:189], v[18:21]
	v_mfma_f32_16x16x32_bf16 v[10:13], v[210:213], v[186:189], v[10:13]
	v_mfma_f32_16x16x32_bf16 v[6:9], v[202:205], v[194:197], v[6:9]
	v_mfma_f32_16x16x32_bf16 v[2:5], v[210:213], v[194:197], v[2:5]
	v_mfma_f32_16x16x32_bf16 v[50:53], v[206:209], v[172:175], v[50:53]
	v_mfma_f32_16x16x32_bf16 v[42:45], v[214:217], v[172:175], v[42:45]
	v_mfma_f32_16x16x32_bf16 v[34:37], v[206:209], v[180:183], v[34:37]
	v_mfma_f32_16x16x32_bf16 v[26:29], v[214:217], v[180:183], v[26:29]
	v_mfma_f32_16x16x32_bf16 v[18:21], v[206:209], v[190:193], v[18:21]
	v_mfma_f32_16x16x32_bf16 v[10:13], v[214:217], v[190:193], v[10:13]
	v_mfma_f32_16x16x32_bf16 v[6:9], v[206:209], v[198:201], v[6:9]
	v_mfma_f32_16x16x32_bf16 v[2:5], v[214:217], v[198:201], v[2:5]
	s_add_i32 s61, s61, 2
	s_add_u32 s22, s22, 0x100
	s_addc_u32 s23, s23, 0
	s_add_u32 s59, s59, 0x100
	s_addc_u32 s60, s60, 0
	s_cmp_gt_u32 s61, 29
	s_barrier
	s_cbranch_scc0 .LBB0_269

.LBB0_273:
	s_setprio 0
	s_barrier

.LBB0_445:
	v_ashrrev_i32_e32 v2, 31, v10
	v_lshrrev_b32_e32 v2, 26, v2
	v_add_u32_e32 v2, v10, v2
	v_ashrrev_i32_e32 v11, 6, v2
	v_bfe_i32 v2, v10, 27, 1
	v_lshlrev_b32_e32 v1, 4, v10
	v_lshrrev_b32_e32 v2, 22, v2
	v_add_u32_e32 v2, v1, v2
	v_and_b32_e32 v2, 0xfffffc00, v2
	v_sub_u32_e32 v2, v1, v2
	v_lshrrev_b32_e32 v3, 4, v2
	v_bitop3_b32 v2, v3, v2, 32 bitop3:0x6c
	v_ashrrev_i32_e32 v4, 31, v2
	v_lshrrev_b32_e32 v4, 26, v4
	v_add_u32_e32 v4, v2, v4
	v_lshlrev_b32_e32 v3, 3, v11
	v_ashrrev_i32_e32 v13, 6, v4
	v_and_b32_e32 v4, 0xc0, v4
	v_and_b32_e32 v3, -16, v3
	v_sub_u32_e32 v2, v2, v4
	v_mov_b32_e32 v4, 1
	s_ashr_i32 s2, s4, 3
	v_add_u32_e32 v3, v13, v3
	v_lshlrev_b32_e32 v5, 5, v11
	v_ashrrev_i16_sdwa v2, v4, sext(v2) dst_sel:DWORD dst_unused:UNUSED_PAD src0_sel:DWORD src1_sel:BYTE_0
	s_add_u32 s41, s38, 0x596dc00
	v_and_b32_e32 v12, 32, v5
	v_bfe_i32 v14, v2, 0, 16
	v_lshlrev_b32_e32 v5, 1, v3
	v_lshrrev_b32_e32 v6, 2, v3
	v_and_b32_e32 v7, 3, v13
	s_mov_b32 s5, 0x3fffe0
	s_movk_i32 s3, 0xf00
	s_addc_u32 s42, s39, 0
	v_add_u32_e32 v2, v12, v14
	v_and_b32_e32 v5, 24, v5
	v_and_b32_e32 v6, 4, v6
	v_and_or_b32 v7, v3, s5, v7
	v_mul_lo_u32 v3, v3, s3
	s_add_u32 s43, s38, 0xf00000
	v_or3_b32 v5, v7, v6, v5
	v_add_lshl_u32 v130, v2, v3, 1
	v_lshlrev_b32_e32 v2, 1, v2
	v_add_u32_e32 v1, 0x2000, v1
	s_addc_u32 s44, s39, 0
	v_lshl_add_u32 v132, v5, 10, v2
	v_ashrrev_i32_e32 v2, 31, v1
	s_add_i32 s2, s6, s2
	v_lshrrev_b32_e32 v2, 22, v2
	s_ashr_i32 s6, s2, 31
	v_add_u32_e32 v2, v1, v2
	s_lshr_b32 s6, s6, 26
	v_ashrrev_i32_e32 v15, 10, v2
	s_add_i32 s6, s2, s6
	v_mul_i32_i24_e32 v2, 0x400, v15
	s_ashr_i32 s7, s6, 6
	s_and_b32 s6, s6, 0xffc0
	v_sub_u32_e32 v1, v1, v2
	s_sub_i32 s6, s2, s6
	v_lshrrev_b32_e32 v2, 4, v1
	s_bfe_i32 s2, s6, 0x80000
	v_bitop3_b32 v1, v2, v1, 32 bitop3:0x6c
	s_bfe_u32 s2, s2, 0x3000c
	v_ashrrev_i32_e32 v3, 31, v1
	s_add_i32 s8, s6, s2
	v_lshrrev_b32_e32 v3, 26, v3
	s_bfe_i32 s2, s8, 0x80000
	s_and_b32 s8, s8, 0xf8
	v_lshlrev_b32_e32 v2, 3, v15
	v_add_u32_e32 v3, v1, v3
	s_sext_i32_i16 s2, s2
	s_sub_i32 s6, s6, s8
	v_and_b32_e32 v2, -16, v2
	v_ashrrev_i32_e32 v16, 6, v3
	v_lshlrev_b32_e32 v5, 5, v15
	s_lshl_b32 s7, s7, 3
	s_lshr_b32 s2, s2, 3
	s_sext_i32_i8 s6, s6
	s_ashr_i32 s4, s36, 6
	v_add_u32_e32 v2, v16, v2
	v_and_b32_e32 v17, 32, v5
	v_and_b32_e32 v3, 0xc0, v3
	v_and_b32_e32 v5, 3, v16
	s_add_i32 s69, s7, s6
	s_bfe_i64 s[6:7], s[2:3], 0x100000
	v_sub_u32_e32 v1, v1, v3
	v_and_or_b32 v5, v2, s5, v5
	s_ashr_i32 s5, s36, 8
	s_lshl_b32 s45, s4, 10
	s_lshl_b64 s[6:7], s[6:7], 18
	v_ashrrev_i16_sdwa v1, v4, sext(v1) dst_sel:DWORD dst_unused:UNUSED_PAD src0_sel:DWORD src1_sel:BYTE_0
	s_add_u32 s30, s43, s6
	v_bfe_i32 v18, v1, 0, 16
	v_lshlrev_b32_e32 v3, 1, v2
	v_lshrrev_b32_e32 v4, 2, v2
	s_addc_u32 s31, s44, s7
	s_add_i32 s46, s45, 0
	v_add_u32_e32 v1, v17, v18
	v_and_b32_e32 v3, 24, v3
	v_and_b32_e32 v4, 4, v4
	v_mul_lo_u32 v2, v2, s3
	s_add_i32 m0, s46, 0x10000
	v_or3_b32 v3, v5, v4, v3
	v_add_lshl_u32 v134, v1, v2, 1
	v_lshlrev_b32_e32 v1, 1, v1
	s_mul_i32 s9, s69, 0x1e0000
	global_load_lds_dwordx4 v132, s[30:31]
	s_add_i32 m0, s46, 0x12000
	v_lshl_add_u32 v136, v3, 10, v1
	s_mul_hi_i32 s8, s69, 0x1e0000
	s_add_u32 s28, s41, s9
	global_load_lds_dwordx4 v136, s[30:31]
	s_addc_u32 s29, s42, s8
	s_mov_b32 m0, s46
	s_add_i32 s47, s46, 0x2000
	global_load_lds_dwordx4 v130, s[28:29]
	s_mov_b32 m0, s47
	s_add_u32 s6, s30, 0x20000
	global_load_lds_dwordx4 v134, s[28:29]
	s_addc_u32 s7, s31, 0
	s_add_i32 m0, s46, 0x14000
	v_mov_b32_e32 v133, 0
	global_load_lds_dwordx4 v132, s[6:7]
	s_add_i32 m0, s46, 0x16000
	v_mov_b32_e32 v137, v133
	global_load_lds_dwordx4 v136, s[6:7]
	s_add_u32 s6, s28, 0xf0000
	s_addc_u32 s7, s29, 0
	s_add_i32 s50, s46, 0x4000
	s_mov_b32 m0, s50
	s_add_i32 s51, s46, 0x6000
	global_load_lds_dwordx4 v130, s[6:7]
	s_mov_b32 m0, s51
	v_mov_b32_e32 v131, v133
	global_load_lds_dwordx4 v134, s[6:7]
	v_mov_b32_e32 v135, v133
	s_mov_b32 s52, 0
	v_lshl_add_u64 v[8:9], s[30:31], 0, v[132:133]
	v_lshl_add_u64 v[6:7], s[30:31], 0, v[136:137]
	v_lshl_add_u64 v[4:5], s[28:29], 0, v[130:131]
	s_cmp_lg_u32 s5, 1
	v_lshl_add_u64 v[2:3], s[28:29], 0, v[134:135]
	s_cbranch_scc1 .LBB0_447
	s_setprio 1
	s_barrier

.LBB0_456:
	s_ashr_i32 s23, s22, 31
	s_lshl_b64 s[26:27], s[22:23], 18
	s_add_u32 s26, s43, s26
	s_addc_u32 s27, s44, s27
	s_and_b64 s[4:5], s[4:5], exec
	s_cselect_b32 s23, s27, s31
	s_cselect_b32 s78, s26, s30
	s_add_u32 s79, s30, 0x100
	v_mov_b32_e32 v2, 0
	s_addc_u32 s80, s31, 0
	s_mov_b32 s81, -2
	v_mov_b32_e32 v3, v2
	v_mov_b32_e32 v4, v2
	v_mov_b32_e32 v5, v2
	v_mov_b32_e32 v6, v2
	v_mov_b32_e32 v7, v2
	v_mov_b32_e32 v8, v2
	v_mov_b32_e32 v9, v2
	v_mov_b32_e32 v10, v2
	v_mov_b32_e32 v11, v2
	v_mov_b32_e32 v12, v2
	v_mov_b32_e32 v13, v2
	v_mov_b32_e32 v18, v2
	v_mov_b32_e32 v19, v2
	v_mov_b32_e32 v20, v2
	v_mov_b32_e32 v21, v2
	v_mov_b32_e32 v26, v2
	v_mov_b32_e32 v27, v2
	v_mov_b32_e32 v28, v2
	v_mov_b32_e32 v29, v2
	v_mov_b32_e32 v34, v2
	v_mov_b32_e32 v35, v2
	v_mov_b32_e32 v36, v2
	v_mov_b32_e32 v37, v2
	v_mov_b32_e32 v42, v2
	v_mov_b32_e32 v43, v2
	v_mov_b32_e32 v44, v2
	v_mov_b32_e32 v45, v2
	v_mov_b32_e32 v50, v2
	v_mov_b32_e32 v51, v2
	v_mov_b32_e32 v52, v2
	v_mov_b32_e32 v53, v2
	v_mov_b32_e32 v14, v2
	v_mov_b32_e32 v15, v2
	v_mov_b32_e32 v16, v2
	v_mov_b32_e32 v17, v2
	v_mov_b32_e32 v22, v2
	v_mov_b32_e32 v23, v2
	v_mov_b32_e32 v24, v2
	v_mov_b32_e32 v25, v2
	v_mov_b32_e32 v30, v2
	v_mov_b32_e32 v31, v2
	v_mov_b32_e32 v32, v2
	v_mov_b32_e32 v33, v2
	v_mov_b32_e32 v38, v2
	v_mov_b32_e32 v39, v2
	v_mov_b32_e32 v40, v2
	v_mov_b32_e32 v41, v2
	v_mov_b32_e32 v46, v2
	v_mov_b32_e32 v47, v2
	v_mov_b32_e32 v48, v2
	v_mov_b32_e32 v49, v2
	v_mov_b32_e32 v54, v2
	v_mov_b32_e32 v55, v2
	v_mov_b32_e32 v56, v2
	v_mov_b32_e32 v57, v2
	v_mov_b32_e32 v58, v2
	v_mov_b32_e32 v59, v2
	v_mov_b32_e32 v60, v2
	v_mov_b32_e32 v61, v2
	v_mov_b32_e32 v62, v2
	v_mov_b32_e32 v63, v2
	v_mov_b32_e32 v64, v2
	v_mov_b32_e32 v65, v2
	v_mov_b32_e32 v66, v2
	v_mov_b32_e32 v67, v2
	v_mov_b32_e32 v68, v2
	v_mov_b32_e32 v69, v2
	v_mov_b32_e32 v70, v2
	v_mov_b32_e32 v71, v2
	v_mov_b32_e32 v72, v2
	v_mov_b32_e32 v73, v2
	v_mov_b32_e32 v78, v2
	v_mov_b32_e32 v79, v2
	v_mov_b32_e32 v80, v2
	v_mov_b32_e32 v81, v2
	v_mov_b32_e32 v86, v2
	v_mov_b32_e32 v87, v2
	v_mov_b32_e32 v88, v2
	v_mov_b32_e32 v89, v2
	v_mov_b32_e32 v94, v2
	v_mov_b32_e32 v95, v2
	v_mov_b32_e32 v96, v2
	v_mov_b32_e32 v97, v2
	v_mov_b32_e32 v102, v2
	v_mov_b32_e32 v103, v2
	v_mov_b32_e32 v104, v2
	v_mov_b32_e32 v105, v2
	v_mov_b32_e32 v110, v2
	v_mov_b32_e32 v111, v2
	v_mov_b32_e32 v112, v2
	v_mov_b32_e32 v113, v2
	v_mov_b32_e32 v118, v2
	v_mov_b32_e32 v119, v2
	v_mov_b32_e32 v120, v2
	v_mov_b32_e32 v121, v2
	v_mov_b32_e32 v74, v2
	v_mov_b32_e32 v75, v2
	v_mov_b32_e32 v76, v2
	v_mov_b32_e32 v77, v2
	v_mov_b32_e32 v82, v2
	v_mov_b32_e32 v83, v2
	v_mov_b32_e32 v84, v2
	v_mov_b32_e32 v85, v2
	v_mov_b32_e32 v90, v2
	v_mov_b32_e32 v91, v2
	v_mov_b32_e32 v92, v2
	v_mov_b32_e32 v93, v2
	v_mov_b32_e32 v98, v2
	v_mov_b32_e32 v99, v2
	v_mov_b32_e32 v100, v2
	v_mov_b32_e32 v101, v2
	v_mov_b32_e32 v106, v2
	v_mov_b32_e32 v107, v2
	v_mov_b32_e32 v108, v2
	v_mov_b32_e32 v109, v2
	v_mov_b32_e32 v114, v2
	v_mov_b32_e32 v115, v2
	v_mov_b32_e32 v116, v2
	v_mov_b32_e32 v117, v2
	v_mov_b32_e32 v122, v2
	v_mov_b32_e32 v123, v2
	v_mov_b32_e32 v124, v2
	v_mov_b32_e32 v125, v2
	v_mov_b32_e32 v126, v2
	v_mov_b32_e32 v127, v2
	v_mov_b32_e32 v128, v2
	v_mov_b32_e32 v129, v2
	s_cmp_eq_u32 s98, 0
	s_cbranch_scc1 .LBB0_457
	ds_read_b128 v[154:157], v150
	ds_read_b128 v[158:161], v150 offset:1024
	ds_read_b128 v[162:165], v150 offset:2048
	ds_read_b128 v[166:169], v150 offset:3072
	s_add_u32 s4, s28, 0x100
	s_addc_u32 s5, s29, 0
	s_cmp_eq_u32 s81, 4
	s_cselect_b32 s35, s25, s5
	s_cselect_b32 s34, s24, s4
	s_cselect_b32 s31, s23, s80
	s_cselect_b32 s30, s78, s79
	v_lshl_add_u64 v[146:147], s[28:29], 0, v[138:139]
	s_add_i32 m0, s46, 0xc000
	ds_read_b128 v[170:173], v151
	ds_read_b128 v[174:177], v151 offset:1024
	ds_read_b128 v[178:181], v151 offset:2048
	ds_read_b128 v[186:189], v151 offset:3072
	ds_read_b128 v[190:193], v151 offset:4096
	ds_read_b128 v[194:197], v151 offset:5120
	ds_read_b128 v[198:201], v151 offset:6144
	ds_read_b128 v[202:205], v151 offset:7168
	global_load_lds_dwordx4 v[146:147], off
	v_lshl_add_u64 v[146:147], s[28:29], 0, v[140:141]
	s_add_i32 m0, s46, 0xe000
	s_nop 0
	global_load_lds_dwordx4 v[146:147], off
	ds_read_b128 v[206:209], v152
	ds_read_b128 v[210:213], v152 offset:1024
	ds_read_b128 v[214:217], v152 offset:2048
	ds_read_b128 v[218:221], v152 offset:3072
	s_waitcnt vmcnt(24)
	s_waitcnt lgkmcnt(0)
	s_barrier
	v_mfma_f32_16x16x32_bf16 v[126:129], v[154:157], v[170:173], v[126:129]
	v_mfma_f32_16x16x32_bf16 v[122:125], v[162:165], v[170:173], v[122:125]
	v_mfma_f32_16x16x32_bf16 v[114:117], v[154:157], v[178:181], v[114:117]
	v_mfma_f32_16x16x32_bf16 v[106:109], v[162:165], v[178:181], v[106:109]
	v_mfma_f32_16x16x32_bf16 v[98:101], v[154:157], v[190:193], v[98:101]
	v_mfma_f32_16x16x32_bf16 v[90:93], v[162:165], v[190:193], v[90:93]
	v_mfma_f32_16x16x32_bf16 v[82:85], v[154:157], v[198:201], v[82:85]
	v_mfma_f32_16x16x32_bf16 v[74:77], v[162:165], v[198:201], v[74:77]
	v_mfma_f32_16x16x32_bf16 v[126:129], v[158:161], v[174:177], v[126:129]
	v_mfma_f32_16x16x32_bf16 v[122:125], v[166:169], v[174:177], v[122:125]
	v_mfma_f32_16x16x32_bf16 v[114:117], v[158:161], v[186:189], v[114:117]
	v_mfma_f32_16x16x32_bf16 v[106:109], v[166:169], v[186:189], v[106:109]
	v_mfma_f32_16x16x32_bf16 v[98:101], v[158:161], v[194:197], v[98:101]
	v_mfma_f32_16x16x32_bf16 v[90:93], v[166:169], v[194:197], v[90:93]
	v_mfma_f32_16x16x32_bf16 v[82:85], v[158:161], v[202:205], v[82:85]
	v_mfma_f32_16x16x32_bf16 v[74:77], v[166:169], v[202:205], v[74:77]
	v_mfma_f32_16x16x32_bf16 v[118:121], v[206:209], v[170:173], v[118:121]
	v_mfma_f32_16x16x32_bf16 v[110:113], v[214:217], v[170:173], v[110:113]
	v_mfma_f32_16x16x32_bf16 v[102:105], v[206:209], v[178:181], v[102:105]
	v_mfma_f32_16x16x32_bf16 v[94:97], v[214:217], v[178:181], v[94:97]
	v_mfma_f32_16x16x32_bf16 v[86:89], v[206:209], v[190:193], v[86:89]
	v_mfma_f32_16x16x32_bf16 v[78:81], v[214:217], v[190:193], v[78:81]
	v_mfma_f32_16x16x32_bf16 v[70:73], v[206:209], v[198:201], v[70:73]
	v_mfma_f32_16x16x32_bf16 v[66:69], v[214:217], v[198:201], v[66:69]
	v_mfma_f32_16x16x32_bf16 v[118:121], v[210:213], v[174:177], v[118:121]
	v_mfma_f32_16x16x32_bf16 v[110:113], v[218:221], v[174:177], v[110:113]
	v_mfma_f32_16x16x32_bf16 v[102:105], v[210:213], v[186:189], v[102:105]
	v_mfma_f32_16x16x32_bf16 v[94:97], v[218:221], v[186:189], v[94:97]
	v_mfma_f32_16x16x32_bf16 v[86:89], v[210:213], v[194:197], v[86:89]
	v_mfma_f32_16x16x32_bf16 v[78:81], v[218:221], v[194:197], v[78:81]
	v_mfma_f32_16x16x32_bf16 v[70:73], v[210:213], v[202:205], v[70:73]
	v_mfma_f32_16x16x32_bf16 v[66:69], v[218:221], v[202:205], v[66:69]
	s_barrier
	s_add_i32 s28, s61, s45
	v_lshl_add_u64 v[146:147], s[30:31], 0, v[132:133]
	s_mov_b32 m0, s28
	global_load_lds_dwordx4 v132, s[30:31]
	v_lshl_add_u64 v[182:183], s[30:31], 0, v[136:137]
	s_add_i32 m0, s28, 0x2000
	s_nop 0
	global_load_lds_dwordx4 v136, s[30:31]
	s_mov_b32 m0, s46
	v_lshl_add_u64 v[222:223], s[34:35], 0, v[130:131]
	ds_read_b128 v[170:173], v151 offset:16384
	ds_read_b128 v[174:177], v151 offset:17408
	ds_read_b128 v[178:181], v151 offset:18432
	ds_read_b128 v[186:189], v151 offset:19456
	ds_read_b128 v[190:193], v151 offset:20480
	ds_read_b128 v[194:197], v151 offset:21504
	ds_read_b128 v[198:201], v151 offset:22528
	ds_read_b128 v[202:205], v151 offset:23552
	global_load_lds_dwordx4 v130, s[34:35]
	v_lshl_add_u64 v[224:225], s[34:35], 0, v[134:135]
	s_mov_b32 m0, s47
	s_nop 0
	global_load_lds_dwordx4 v134, s[34:35]
	s_waitcnt vmcnt(22)
	s_waitcnt lgkmcnt(0)
	s_barrier
	v_mfma_f32_16x16x32_bf16 v[62:65], v[154:157], v[170:173], v[62:65]
	v_mfma_f32_16x16x32_bf16 v[58:61], v[162:165], v[170:173], v[58:61]
	v_mfma_f32_16x16x32_bf16 v[54:57], v[154:157], v[178:181], v[54:57]
	v_mfma_f32_16x16x32_bf16 v[46:49], v[162:165], v[178:181], v[46:49]
	v_mfma_f32_16x16x32_bf16 v[38:41], v[154:157], v[190:193], v[38:41]
	v_mfma_f32_16x16x32_bf16 v[30:33], v[162:165], v[190:193], v[30:33]
	v_mfma_f32_16x16x32_bf16 v[22:25], v[154:157], v[198:201], v[22:25]
	v_mfma_f32_16x16x32_bf16 v[14:17], v[162:165], v[198:201], v[14:17]
	v_mfma_f32_16x16x32_bf16 v[62:65], v[158:161], v[174:177], v[62:65]
	v_mfma_f32_16x16x32_bf16 v[58:61], v[166:169], v[174:177], v[58:61]
	v_mfma_f32_16x16x32_bf16 v[54:57], v[158:161], v[186:189], v[54:57]
	v_mfma_f32_16x16x32_bf16 v[46:49], v[166:169], v[186:189], v[46:49]
	v_mfma_f32_16x16x32_bf16 v[38:41], v[158:161], v[194:197], v[38:41]
	v_mfma_f32_16x16x32_bf16 v[30:33], v[166:169], v[194:197], v[30:33]
	v_mfma_f32_16x16x32_bf16 v[22:25], v[158:161], v[202:205], v[22:25]
	v_mfma_f32_16x16x32_bf16 v[14:17], v[166:169], v[202:205], v[14:17]
	v_mfma_f32_16x16x32_bf16 v[50:53], v[206:209], v[170:173], v[50:53]
	v_mfma_f32_16x16x32_bf16 v[42:45], v[214:217], v[170:173], v[42:45]
	v_mfma_f32_16x16x32_bf16 v[34:37], v[206:209], v[178:181], v[34:37]
	v_mfma_f32_16x16x32_bf16 v[26:29], v[214:217], v[178:181], v[26:29]
	v_mfma_f32_16x16x32_bf16 v[18:21], v[206:209], v[190:193], v[18:21]
	v_mfma_f32_16x16x32_bf16 v[10:13], v[214:217], v[190:193], v[10:13]
	v_mfma_f32_16x16x32_bf16 v[6:9], v[206:209], v[198:201], v[6:9]
	v_mfma_f32_16x16x32_bf16 v[2:5], v[214:217], v[198:201], v[2:5]
	v_mfma_f32_16x16x32_bf16 v[50:53], v[210:213], v[174:177], v[50:53]
	v_mfma_f32_16x16x32_bf16 v[42:45], v[218:221], v[174:177], v[42:45]
	v_mfma_f32_16x16x32_bf16 v[34:37], v[210:213], v[186:189], v[34:37]
	v_mfma_f32_16x16x32_bf16 v[26:29], v[218:221], v[186:189], v[26:29]
	v_mfma_f32_16x16x32_bf16 v[18:21], v[210:213], v[194:197], v[18:21]
	v_mfma_f32_16x16x32_bf16 v[10:13], v[218:221], v[194:197], v[10:13]
	v_mfma_f32_16x16x32_bf16 v[6:9], v[210:213], v[202:205], v[6:9]
	v_mfma_f32_16x16x32_bf16 v[2:5], v[218:221], v[202:205], v[2:5]
	s_barrier
	s_add_u32 s28, s30, 0x20000
	s_addc_u32 s29, s31, 0
	s_add_i32 s82, s71, s45
	s_mov_b32 m0, s82
	s_nop 0
	global_load_lds_dwordx4 v132, s[28:29]
	s_add_i32 m0, s82, 0x2000
	s_nop 0
	global_load_lds_dwordx4 v136, s[28:29]
	s_add_i32 s82, 0, 0x18000
	v_add_u32_e32 v153, s82, v148
	ds_read_b128 v[154:157], v153
	ds_read_b128 v[158:161], v153 offset:1024
	ds_read_b128 v[162:165], v153 offset:2048
	ds_read_b128 v[166:169], v153 offset:3072
	s_add_u32 s28, s34, 0xf0000
	s_addc_u32 s29, s35, 0
	s_mov_b32 m0, s50
	ds_read_b128 v[170:173], v151 offset:32768
	ds_read_b128 v[174:177], v151 offset:33792
	ds_read_b128 v[178:181], v151 offset:34816
	ds_read_b128 v[186:189], v151 offset:35840
	ds_read_b128 v[190:193], v151 offset:36864
	ds_read_b128 v[194:197], v151 offset:37888
	ds_read_b128 v[198:201], v151 offset:38912
	ds_read_b128 v[202:205], v151 offset:39936
	v_add_u32_e32 v218, 0x1c000, v148
	ds_read_b128 v[206:209], v218
	ds_read_b128 v[210:213], v218 offset:1024
	ds_read_b128 v[214:217], v218 offset:2048
	ds_read_b128 v[218:221], v218 offset:3072
	global_load_lds_dwordx4 v130, s[28:29]
	s_mov_b32 m0, s51
	s_nop 0
	global_load_lds_dwordx4 v134, s[28:29]
	s_waitcnt vmcnt(8)
	s_waitcnt lgkmcnt(0)
	s_barrier
	v_mfma_f32_16x16x32_bf16 v[126:129], v[154:157], v[170:173], v[126:129]
	v_mfma_f32_16x16x32_bf16 v[122:125], v[162:165], v[170:173], v[122:125]
	v_mfma_f32_16x16x32_bf16 v[114:117], v[154:157], v[178:181], v[114:117]
	v_mfma_f32_16x16x32_bf16 v[106:109], v[162:165], v[178:181], v[106:109]
	v_mfma_f32_16x16x32_bf16 v[98:101], v[154:157], v[190:193], v[98:101]
	v_mfma_f32_16x16x32_bf16 v[90:93], v[162:165], v[190:193], v[90:93]
	v_mfma_f32_16x16x32_bf16 v[82:85], v[154:157], v[198:201], v[82:85]
	v_mfma_f32_16x16x32_bf16 v[74:77], v[162:165], v[198:201], v[74:77]
	v_mfma_f32_16x16x32_bf16 v[126:129], v[158:161], v[174:177], v[126:129]
	v_mfma_f32_16x16x32_bf16 v[122:125], v[166:169], v[174:177], v[122:125]
	v_mfma_f32_16x16x32_bf16 v[114:117], v[158:161], v[186:189], v[114:117]
	v_mfma_f32_16x16x32_bf16 v[106:109], v[166:169], v[186:189], v[106:109]
	v_mfma_f32_16x16x32_bf16 v[98:101], v[158:161], v[194:197], v[98:101]
	v_mfma_f32_16x16x32_bf16 v[90:93], v[166:169], v[194:197], v[90:93]
	v_mfma_f32_16x16x32_bf16 v[82:85], v[158:161], v[202:205], v[82:85]
	v_mfma_f32_16x16x32_bf16 v[74:77], v[166:169], v[202:205], v[74:77]
	v_mfma_f32_16x16x32_bf16 v[118:121], v[206:209], v[170:173], v[118:121]
	v_mfma_f32_16x16x32_bf16 v[110:113], v[214:217], v[170:173], v[110:113]
	v_mfma_f32_16x16x32_bf16 v[102:105], v[206:209], v[178:181], v[102:105]
	v_mfma_f32_16x16x32_bf16 v[94:97], v[214:217], v[178:181], v[94:97]
	v_mfma_f32_16x16x32_bf16 v[86:89], v[206:209], v[190:193], v[86:89]
	v_mfma_f32_16x16x32_bf16 v[78:81], v[214:217], v[190:193], v[78:81]
	v_mfma_f32_16x16x32_bf16 v[70:73], v[206:209], v[198:201], v[70:73]
	v_mfma_f32_16x16x32_bf16 v[66:69], v[214:217], v[198:201], v[66:69]
	v_mfma_f32_16x16x32_bf16 v[118:121], v[210:213], v[174:177], v[118:121]
	v_mfma_f32_16x16x32_bf16 v[110:113], v[218:221], v[174:177], v[110:113]
	v_mfma_f32_16x16x32_bf16 v[102:105], v[210:213], v[186:189], v[102:105]
	v_mfma_f32_16x16x32_bf16 v[94:97], v[218:221], v[186:189], v[94:97]
	v_mfma_f32_16x16x32_bf16 v[86:89], v[210:213], v[194:197], v[86:89]
	v_mfma_f32_16x16x32_bf16 v[78:81], v[218:221], v[194:197], v[78:81]
	v_mfma_f32_16x16x32_bf16 v[70:73], v[210:213], v[202:205], v[70:73]
	v_mfma_f32_16x16x32_bf16 v[66:69], v[218:221], v[202:205], v[66:69]
	s_barrier
	s_add_i32 s34, 0, 0x1c000
	s_add_i32 s28, s82, s45
	v_lshl_add_u64 v[146:147], v[146:147], 0, s[6:7]
	s_mov_b32 m0, s28
	global_load_lds_dwordx4 v[146:147], off
	v_lshl_add_u64 v[146:147], v[182:183], 0, s[6:7]
	s_add_i32 m0, s28, 0x2000
	s_nop 0
	global_load_lds_dwordx4 v[146:147], off
	s_mov_b32 m0, s53
	v_lshl_add_u64 v[146:147], v[222:223], 0, s[6:7]
	ds_read_b128 v[170:173], v151 offset:49152
	ds_read_b128 v[174:177], v151 offset:50176
	ds_read_b128 v[178:181], v151 offset:51200
	ds_read_b128 v[186:189], v151 offset:52224
	ds_read_b128 v[190:193], v151 offset:53248
	ds_read_b128 v[194:197], v151 offset:54272
	ds_read_b128 v[198:201], v151 offset:55296
	ds_read_b128 v[202:205], v151 offset:56320
	global_load_lds_dwordx4 v[146:147], off
	v_lshl_add_u64 v[146:147], v[224:225], 0, s[6:7]
	s_mov_b32 m0, s58
	s_nop 0
	global_load_lds_dwordx4 v[146:147], off
	s_add_u32 s28, s30, 0x20080
	s_addc_u32 s29, s31, 0
	s_add_i32 s30, s34, s45
	s_mov_b32 m0, s30
	s_nop 0
	global_load_lds_dwordx4 v132, s[28:29]
	s_add_i32 m0, s30, 0x2000
	s_nop 0
	global_load_lds_dwordx4 v136, s[28:29]
	s_waitcnt vmcnt(8)
	s_waitcnt lgkmcnt(0)
	s_barrier
	v_mfma_f32_16x16x32_bf16 v[62:65], v[154:157], v[170:173], v[62:65]
	v_mfma_f32_16x16x32_bf16 v[58:61], v[162:165], v[170:173], v[58:61]
	v_mfma_f32_16x16x32_bf16 v[54:57], v[154:157], v[178:181], v[54:57]
	v_mfma_f32_16x16x32_bf16 v[46:49], v[162:165], v[178:181], v[46:49]
	v_mfma_f32_16x16x32_bf16 v[38:41], v[154:157], v[190:193], v[38:41]
	v_mfma_f32_16x16x32_bf16 v[30:33], v[162:165], v[190:193], v[30:33]
	v_mfma_f32_16x16x32_bf16 v[22:25], v[154:157], v[198:201], v[22:25]
	v_mfma_f32_16x16x32_bf16 v[14:17], v[162:165], v[198:201], v[14:17]
	v_mfma_f32_16x16x32_bf16 v[62:65], v[158:161], v[174:177], v[62:65]
	v_mfma_f32_16x16x32_bf16 v[58:61], v[166:169], v[174:177], v[58:61]
	v_mfma_f32_16x16x32_bf16 v[54:57], v[158:161], v[186:189], v[54:57]
	v_mfma_f32_16x16x32_bf16 v[46:49], v[166:169], v[186:189], v[46:49]
	v_mfma_f32_16x16x32_bf16 v[38:41], v[158:161], v[194:197], v[38:41]
	v_mfma_f32_16x16x32_bf16 v[30:33], v[166:169], v[194:197], v[30:33]
	v_mfma_f32_16x16x32_bf16 v[22:25], v[158:161], v[202:205], v[22:25]
	v_mfma_f32_16x16x32_bf16 v[14:17], v[166:169], v[202:205], v[14:17]
	v_mfma_f32_16x16x32_bf16 v[50:53], v[206:209], v[170:173], v[50:53]
	v_mfma_f32_16x16x32_bf16 v[42:45], v[214:217], v[170:173], v[42:45]
	v_mfma_f32_16x16x32_bf16 v[34:37], v[206:209], v[178:181], v[34:37]
	v_mfma_f32_16x16x32_bf16 v[26:29], v[214:217], v[178:181], v[26:29]
	v_mfma_f32_16x16x32_bf16 v[18:21], v[206:209], v[190:193], v[18:21]
	v_mfma_f32_16x16x32_bf16 v[10:13], v[214:217], v[190:193], v[10:13]
	v_mfma_f32_16x16x32_bf16 v[6:9], v[206:209], v[198:201], v[6:9]
	v_mfma_f32_16x16x32_bf16 v[2:5], v[214:217], v[198:201], v[2:5]
	v_mfma_f32_16x16x32_bf16 v[50:53], v[210:213], v[174:177], v[50:53]
	v_mfma_f32_16x16x32_bf16 v[42:45], v[218:221], v[174:177], v[42:45]
	v_mfma_f32_16x16x32_bf16 v[34:37], v[210:213], v[186:189], v[34:37]
	v_mfma_f32_16x16x32_bf16 v[26:29], v[218:221], v[186:189], v[26:29]
	v_mfma_f32_16x16x32_bf16 v[18:21], v[210:213], v[194:197], v[18:21]
	v_mfma_f32_16x16x32_bf16 v[10:13], v[218:221], v[194:197], v[10:13]
	v_mfma_f32_16x16x32_bf16 v[6:9], v[210:213], v[202:205], v[6:9]
	v_mfma_f32_16x16x32_bf16 v[2:5], v[218:221], v[202:205], v[2:5]
	s_add_i32 s81, s81, 2
	s_add_u32 s79, s79, 0x100
	s_addc_u32 s80, s80, 0
	s_cmp_gt_u32 s81, 5
	s_mov_b64 s[28:29], s[4:5]
	s_barrier
	s_cbranch_scc1 .Lgemm_epi_1
.LBB0_457:
	ds_read_b128 v[154:157], v150
	ds_read_b128 v[158:161], v150 offset:1024
	ds_read_b128 v[162:165], v150 offset:2048
	ds_read_b128 v[166:169], v150 offset:3072
	s_add_u32 s4, s28, 0x100
	s_addc_u32 s5, s29, 0
	s_cmp_eq_u32 s81, 4
	s_cselect_b32 s35, s25, s5
	s_cselect_b32 s34, s24, s4
	s_cselect_b32 s31, s23, s80
	s_cselect_b32 s30, s78, s79
	v_lshl_add_u64 v[146:147], s[28:29], 0, v[138:139]
	s_add_i32 m0, s46, 0xc000
	ds_read_b128 v[170:173], v151
	ds_read_b128 v[174:177], v151 offset:1024
	ds_read_b128 v[178:181], v151 offset:2048
	ds_read_b128 v[186:189], v151 offset:3072
	ds_read_b128 v[190:193], v151 offset:4096
	ds_read_b128 v[194:197], v151 offset:5120
	ds_read_b128 v[198:201], v151 offset:6144
	ds_read_b128 v[202:205], v151 offset:7168
	global_load_lds_dwordx4 v[146:147], off
	v_lshl_add_u64 v[146:147], s[28:29], 0, v[140:141]
	s_add_i32 m0, s46, 0xe000
	s_nop 0
	global_load_lds_dwordx4 v[146:147], off
	ds_read_b128 v[206:209], v152
	ds_read_b128 v[210:213], v152 offset:1024
	ds_read_b128 v[214:217], v152 offset:2048
	ds_read_b128 v[218:221], v152 offset:3072
	s_waitcnt vmcnt(8)
	s_waitcnt lgkmcnt(0)
	s_barrier
	v_mfma_f32_16x16x32_bf16 v[126:129], v[154:157], v[170:173], v[126:129]
	v_mfma_f32_16x16x32_bf16 v[122:125], v[162:165], v[170:173], v[122:125]
	v_mfma_f32_16x16x32_bf16 v[114:117], v[154:157], v[178:181], v[114:117]
	v_mfma_f32_16x16x32_bf16 v[106:109], v[162:165], v[178:181], v[106:109]
	v_mfma_f32_16x16x32_bf16 v[98:101], v[154:157], v[190:193], v[98:101]
	v_mfma_f32_16x16x32_bf16 v[90:93], v[162:165], v[190:193], v[90:93]
	v_mfma_f32_16x16x32_bf16 v[82:85], v[154:157], v[198:201], v[82:85]
	v_mfma_f32_16x16x32_bf16 v[74:77], v[162:165], v[198:201], v[74:77]
	v_mfma_f32_16x16x32_bf16 v[126:129], v[158:161], v[174:177], v[126:129]
	v_mfma_f32_16x16x32_bf16 v[122:125], v[166:169], v[174:177], v[122:125]
	v_mfma_f32_16x16x32_bf16 v[114:117], v[158:161], v[186:189], v[114:117]
	v_mfma_f32_16x16x32_bf16 v[106:109], v[166:169], v[186:189], v[106:109]
	v_mfma_f32_16x16x32_bf16 v[98:101], v[158:161], v[194:197], v[98:101]
	v_mfma_f32_16x16x32_bf16 v[90:93], v[166:169], v[194:197], v[90:93]
	v_mfma_f32_16x16x32_bf16 v[82:85], v[158:161], v[202:205], v[82:85]
	v_mfma_f32_16x16x32_bf16 v[74:77], v[166:169], v[202:205], v[74:77]
	v_mfma_f32_16x16x32_bf16 v[118:121], v[206:209], v[170:173], v[118:121]
	v_mfma_f32_16x16x32_bf16 v[110:113], v[214:217], v[170:173], v[110:113]
	v_mfma_f32_16x16x32_bf16 v[102:105], v[206:209], v[178:181], v[102:105]
	v_mfma_f32_16x16x32_bf16 v[94:97], v[214:217], v[178:181], v[94:97]
	v_mfma_f32_16x16x32_bf16 v[86:89], v[206:209], v[190:193], v[86:89]
	v_mfma_f32_16x16x32_bf16 v[78:81], v[214:217], v[190:193], v[78:81]
	v_mfma_f32_16x16x32_bf16 v[70:73], v[206:209], v[198:201], v[70:73]
	v_mfma_f32_16x16x32_bf16 v[66:69], v[214:217], v[198:201], v[66:69]
	v_mfma_f32_16x16x32_bf16 v[118:121], v[210:213], v[174:177], v[118:121]
	v_mfma_f32_16x16x32_bf16 v[110:113], v[218:221], v[174:177], v[110:113]
	v_mfma_f32_16x16x32_bf16 v[102:105], v[210:213], v[186:189], v[102:105]
	v_mfma_f32_16x16x32_bf16 v[94:97], v[218:221], v[186:189], v[94:97]
	v_mfma_f32_16x16x32_bf16 v[86:89], v[210:213], v[194:197], v[86:89]
	v_mfma_f32_16x16x32_bf16 v[78:81], v[218:221], v[194:197], v[78:81]
	v_mfma_f32_16x16x32_bf16 v[70:73], v[210:213], v[202:205], v[70:73]
	v_mfma_f32_16x16x32_bf16 v[66:69], v[218:221], v[202:205], v[66:69]
	s_barrier
	s_add_i32 s28, s61, s45
	v_lshl_add_u64 v[146:147], s[30:31], 0, v[132:133]
	s_mov_b32 m0, s28
	global_load_lds_dwordx4 v132, s[30:31]
	v_lshl_add_u64 v[182:183], s[30:31], 0, v[136:137]
	s_add_i32 m0, s28, 0x2000
	s_nop 0
	global_load_lds_dwordx4 v136, s[30:31]
	s_mov_b32 m0, s46
	v_lshl_add_u64 v[222:223], s[34:35], 0, v[130:131]
	ds_read_b128 v[170:173], v151 offset:16384
	ds_read_b128 v[174:177], v151 offset:17408
	ds_read_b128 v[178:181], v151 offset:18432
	ds_read_b128 v[186:189], v151 offset:19456
	ds_read_b128 v[190:193], v151 offset:20480
	ds_read_b128 v[194:197], v151 offset:21504
	ds_read_b128 v[198:201], v151 offset:22528
	ds_read_b128 v[202:205], v151 offset:23552
	global_load_lds_dwordx4 v130, s[34:35]
	v_lshl_add_u64 v[224:225], s[34:35], 0, v[134:135]
	s_mov_b32 m0, s47
	s_nop 0
	global_load_lds_dwordx4 v134, s[34:35]
	s_waitcnt vmcnt(6)
	s_waitcnt lgkmcnt(0)
	s_barrier
	v_mfma_f32_16x16x32_bf16 v[62:65], v[154:157], v[170:173], v[62:65]
	v_mfma_f32_16x16x32_bf16 v[58:61], v[162:165], v[170:173], v[58:61]
	v_mfma_f32_16x16x32_bf16 v[54:57], v[154:157], v[178:181], v[54:57]
	v_mfma_f32_16x16x32_bf16 v[46:49], v[162:165], v[178:181], v[46:49]
	v_mfma_f32_16x16x32_bf16 v[38:41], v[154:157], v[190:193], v[38:41]
	v_mfma_f32_16x16x32_bf16 v[30:33], v[162:165], v[190:193], v[30:33]
	v_mfma_f32_16x16x32_bf16 v[22:25], v[154:157], v[198:201], v[22:25]
	v_mfma_f32_16x16x32_bf16 v[14:17], v[162:165], v[198:201], v[14:17]
	v_mfma_f32_16x16x32_bf16 v[62:65], v[158:161], v[174:177], v[62:65]
	v_mfma_f32_16x16x32_bf16 v[58:61], v[166:169], v[174:177], v[58:61]
	v_mfma_f32_16x16x32_bf16 v[54:57], v[158:161], v[186:189], v[54:57]
	v_mfma_f32_16x16x32_bf16 v[46:49], v[166:169], v[186:189], v[46:49]
	v_mfma_f32_16x16x32_bf16 v[38:41], v[158:161], v[194:197], v[38:41]
	v_mfma_f32_16x16x32_bf16 v[30:33], v[166:169], v[194:197], v[30:33]
	v_mfma_f32_16x16x32_bf16 v[22:25], v[158:161], v[202:205], v[22:25]
	v_mfma_f32_16x16x32_bf16 v[14:17], v[166:169], v[202:205], v[14:17]
	v_mfma_f32_16x16x32_bf16 v[50:53], v[206:209], v[170:173], v[50:53]
	v_mfma_f32_16x16x32_bf16 v[42:45], v[214:217], v[170:173], v[42:45]
	v_mfma_f32_16x16x32_bf16 v[34:37], v[206:209], v[178:181], v[34:37]
	v_mfma_f32_16x16x32_bf16 v[26:29], v[214:217], v[178:181], v[26:29]
	v_mfma_f32_16x16x32_bf16 v[18:21], v[206:209], v[190:193], v[18:21]
	v_mfma_f32_16x16x32_bf16 v[10:13], v[214:217], v[190:193], v[10:13]
	v_mfma_f32_16x16x32_bf16 v[6:9], v[206:209], v[198:201], v[6:9]
	v_mfma_f32_16x16x32_bf16 v[2:5], v[214:217], v[198:201], v[2:5]
	v_mfma_f32_16x16x32_bf16 v[50:53], v[210:213], v[174:177], v[50:53]
	v_mfma_f32_16x16x32_bf16 v[42:45], v[218:221], v[174:177], v[42:45]
	v_mfma_f32_16x16x32_bf16 v[34:37], v[210:213], v[186:189], v[34:37]
	v_mfma_f32_16x16x32_bf16 v[26:29], v[218:221], v[186:189], v[26:29]
	v_mfma_f32_16x16x32_bf16 v[18:21], v[210:213], v[194:197], v[18:21]
	v_mfma_f32_16x16x32_bf16 v[10:13], v[218:221], v[194:197], v[10:13]
	v_mfma_f32_16x16x32_bf16 v[6:9], v[210:213], v[202:205], v[6:9]
	v_mfma_f32_16x16x32_bf16 v[2:5], v[218:221], v[202:205], v[2:5]
	s_barrier
	s_add_u32 s28, s30, 0x20000
	s_addc_u32 s29, s31, 0
	s_add_i32 s82, s71, s45
	s_mov_b32 m0, s82
	s_nop 0
	global_load_lds_dwordx4 v132, s[28:29]
	s_add_i32 m0, s82, 0x2000
	s_nop 0
	global_load_lds_dwordx4 v136, s[28:29]
	s_add_i32 s82, 0, 0x18000
	v_add_u32_e32 v153, s82, v148
	ds_read_b128 v[154:157], v153
	ds_read_b128 v[158:161], v153 offset:1024
	ds_read_b128 v[162:165], v153 offset:2048
	ds_read_b128 v[166:169], v153 offset:3072
	s_add_u32 s28, s34, 0xf0000
	s_addc_u32 s29, s35, 0
	s_mov_b32 m0, s50
	ds_read_b128 v[170:173], v151 offset:32768
	ds_read_b128 v[174:177], v151 offset:33792
	ds_read_b128 v[178:181], v151 offset:34816
	ds_read_b128 v[186:189], v151 offset:35840
	ds_read_b128 v[190:193], v151 offset:36864
	ds_read_b128 v[194:197], v151 offset:37888
	ds_read_b128 v[198:201], v151 offset:38912
	ds_read_b128 v[202:205], v151 offset:39936
	v_add_u32_e32 v218, 0x1c000, v148
	ds_read_b128 v[206:209], v218
	ds_read_b128 v[210:213], v218 offset:1024
	ds_read_b128 v[214:217], v218 offset:2048
	ds_read_b128 v[218:221], v218 offset:3072
	global_load_lds_dwordx4 v130, s[28:29]
	s_mov_b32 m0, s51
	s_nop 0
	global_load_lds_dwordx4 v134, s[28:29]
	s_waitcnt vmcnt(8)
	s_waitcnt lgkmcnt(0)
	s_barrier
	v_mfma_f32_16x16x32_bf16 v[126:129], v[154:157], v[170:173], v[126:129]
	v_mfma_f32_16x16x32_bf16 v[122:125], v[162:165], v[170:173], v[122:125]
	v_mfma_f32_16x16x32_bf16 v[114:117], v[154:157], v[178:181], v[114:117]
	v_mfma_f32_16x16x32_bf16 v[106:109], v[162:165], v[178:181], v[106:109]
	v_mfma_f32_16x16x32_bf16 v[98:101], v[154:157], v[190:193], v[98:101]
	v_mfma_f32_16x16x32_bf16 v[90:93], v[162:165], v[190:193], v[90:93]
	v_mfma_f32_16x16x32_bf16 v[82:85], v[154:157], v[198:201], v[82:85]
	v_mfma_f32_16x16x32_bf16 v[74:77], v[162:165], v[198:201], v[74:77]
	v_mfma_f32_16x16x32_bf16 v[126:129], v[158:161], v[174:177], v[126:129]
	v_mfma_f32_16x16x32_bf16 v[122:125], v[166:169], v[174:177], v[122:125]
	v_mfma_f32_16x16x32_bf16 v[114:117], v[158:161], v[186:189], v[114:117]
	v_mfma_f32_16x16x32_bf16 v[106:109], v[166:169], v[186:189], v[106:109]
	v_mfma_f32_16x16x32_bf16 v[98:101], v[158:161], v[194:197], v[98:101]
	v_mfma_f32_16x16x32_bf16 v[90:93], v[166:169], v[194:197], v[90:93]
	v_mfma_f32_16x16x32_bf16 v[82:85], v[158:161], v[202:205], v[82:85]
	v_mfma_f32_16x16x32_bf16 v[74:77], v[166:169], v[202:205], v[74:77]
	v_mfma_f32_16x16x32_bf16 v[118:121], v[206:209], v[170:173], v[118:121]
	v_mfma_f32_16x16x32_bf16 v[110:113], v[214:217], v[170:173], v[110:113]
	v_mfma_f32_16x16x32_bf16 v[102:105], v[206:209], v[178:181], v[102:105]
	v_mfma_f32_16x16x32_bf16 v[94:97], v[214:217], v[178:181], v[94:97]
	v_mfma_f32_16x16x32_bf16 v[86:89], v[206:209], v[190:193], v[86:89]
	v_mfma_f32_16x16x32_bf16 v[78:81], v[214:217], v[190:193], v[78:81]
	v_mfma_f32_16x16x32_bf16 v[70:73], v[206:209], v[198:201], v[70:73]
	v_mfma_f32_16x16x32_bf16 v[66:69], v[214:217], v[198:201], v[66:69]
	v_mfma_f32_16x16x32_bf16 v[118:121], v[210:213], v[174:177], v[118:121]
	v_mfma_f32_16x16x32_bf16 v[110:113], v[218:221], v[174:177], v[110:113]
	v_mfma_f32_16x16x32_bf16 v[102:105], v[210:213], v[186:189], v[102:105]
	v_mfma_f32_16x16x32_bf16 v[94:97], v[218:221], v[186:189], v[94:97]
	v_mfma_f32_16x16x32_bf16 v[86:89], v[210:213], v[194:197], v[86:89]
	v_mfma_f32_16x16x32_bf16 v[78:81], v[218:221], v[194:197], v[78:81]
	v_mfma_f32_16x16x32_bf16 v[70:73], v[210:213], v[202:205], v[70:73]
	v_mfma_f32_16x16x32_bf16 v[66:69], v[218:221], v[202:205], v[66:69]
	s_barrier
	s_add_i32 s34, 0, 0x1c000
	s_add_i32 s28, s82, s45
	v_lshl_add_u64 v[146:147], v[146:147], 0, s[6:7]
	s_mov_b32 m0, s28
	global_load_lds_dwordx4 v[146:147], off
	v_lshl_add_u64 v[146:147], v[182:183], 0, s[6:7]
	s_add_i32 m0, s28, 0x2000
	s_nop 0
	global_load_lds_dwordx4 v[146:147], off
	s_mov_b32 m0, s53
	v_lshl_add_u64 v[146:147], v[222:223], 0, s[6:7]
	ds_read_b128 v[170:173], v151 offset:49152
	ds_read_b128 v[174:177], v151 offset:50176
	ds_read_b128 v[178:181], v151 offset:51200
	ds_read_b128 v[186:189], v151 offset:52224
	ds_read_b128 v[190:193], v151 offset:53248
	ds_read_b128 v[194:197], v151 offset:54272
	ds_read_b128 v[198:201], v151 offset:55296
	ds_read_b128 v[202:205], v151 offset:56320
	global_load_lds_dwordx4 v[146:147], off
	v_lshl_add_u64 v[146:147], v[224:225], 0, s[6:7]
	s_mov_b32 m0, s58
	s_nop 0
	global_load_lds_dwordx4 v[146:147], off
	s_add_u32 s28, s30, 0x20080
	s_addc_u32 s29, s31, 0
	s_add_i32 s30, s34, s45
	s_mov_b32 m0, s30
	s_nop 0
	global_load_lds_dwordx4 v132, s[28:29]
	s_add_i32 m0, s30, 0x2000
	s_nop 0
	global_load_lds_dwordx4 v136, s[28:29]
	s_waitcnt vmcnt(8)
	s_waitcnt lgkmcnt(0)
	s_barrier
	v_mfma_f32_16x16x32_bf16 v[62:65], v[154:157], v[170:173], v[62:65]
	v_mfma_f32_16x16x32_bf16 v[58:61], v[162:165], v[170:173], v[58:61]
	v_mfma_f32_16x16x32_bf16 v[54:57], v[154:157], v[178:181], v[54:57]
	v_mfma_f32_16x16x32_bf16 v[46:49], v[162:165], v[178:181], v[46:49]
	v_mfma_f32_16x16x32_bf16 v[38:41], v[154:157], v[190:193], v[38:41]
	v_mfma_f32_16x16x32_bf16 v[30:33], v[162:165], v[190:193], v[30:33]
	v_mfma_f32_16x16x32_bf16 v[22:25], v[154:157], v[198:201], v[22:25]
	v_mfma_f32_16x16x32_bf16 v[14:17], v[162:165], v[198:201], v[14:17]
	v_mfma_f32_16x16x32_bf16 v[62:65], v[158:161], v[174:177], v[62:65]
	v_mfma_f32_16x16x32_bf16 v[58:61], v[166:169], v[174:177], v[58:61]
	v_mfma_f32_16x16x32_bf16 v[54:57], v[158:161], v[186:189], v[54:57]
	v_mfma_f32_16x16x32_bf16 v[46:49], v[166:169], v[186:189], v[46:49]
	v_mfma_f32_16x16x32_bf16 v[38:41], v[158:161], v[194:197], v[38:41]
	v_mfma_f32_16x16x32_bf16 v[30:33], v[166:169], v[194:197], v[30:33]
	v_mfma_f32_16x16x32_bf16 v[22:25], v[158:161], v[202:205], v[22:25]
	v_mfma_f32_16x16x32_bf16 v[14:17], v[166:169], v[202:205], v[14:17]
	v_mfma_f32_16x16x32_bf16 v[50:53], v[206:209], v[170:173], v[50:53]
	v_mfma_f32_16x16x32_bf16 v[42:45], v[214:217], v[170:173], v[42:45]
	v_mfma_f32_16x16x32_bf16 v[34:37], v[206:209], v[178:181], v[34:37]
	v_mfma_f32_16x16x32_bf16 v[26:29], v[214:217], v[178:181], v[26:29]
	v_mfma_f32_16x16x32_bf16 v[18:21], v[206:209], v[190:193], v[18:21]
	v_mfma_f32_16x16x32_bf16 v[10:13], v[214:217], v[190:193], v[10:13]
	v_mfma_f32_16x16x32_bf16 v[6:9], v[206:209], v[198:201], v[6:9]
	v_mfma_f32_16x16x32_bf16 v[2:5], v[214:217], v[198:201], v[2:5]
	v_mfma_f32_16x16x32_bf16 v[50:53], v[210:213], v[174:177], v[50:53]
	v_mfma_f32_16x16x32_bf16 v[42:45], v[218:221], v[174:177], v[42:45]
	v_mfma_f32_16x16x32_bf16 v[34:37], v[210:213], v[186:189], v[34:37]
	v_mfma_f32_16x16x32_bf16 v[26:29], v[218:221], v[186:189], v[26:29]
	v_mfma_f32_16x16x32_bf16 v[18:21], v[210:213], v[194:197], v[18:21]
	v_mfma_f32_16x16x32_bf16 v[10:13], v[218:221], v[194:197], v[10:13]
	v_mfma_f32_16x16x32_bf16 v[6:9], v[210:213], v[202:205], v[6:9]
	v_mfma_f32_16x16x32_bf16 v[2:5], v[218:221], v[202:205], v[2:5]
	s_add_i32 s81, s81, 2
	s_add_u32 s79, s79, 0x100
	s_addc_u32 s80, s80, 0
	s_cmp_gt_u32 s81, 5
	s_mov_b64 s[28:29], s[4:5]
	s_barrier
	s_cbranch_scc0 .LBB0_457

.LBB0_682:
	v_readlane_b32 s2, v253, 12
	v_readlane_b32 s3, v253, 13
	s_and_b64 vcc, exec, s[2:3]
	s_cbranch_vccnz .LBB0_716
	v_ashrrev_i32_e32 v2, 31, v10
	v_lshrrev_b32_e32 v2, 26, v2
	v_add_u32_e32 v2, v10, v2
	v_ashrrev_i32_e32 v11, 6, v2
	v_bfe_i32 v2, v10, 27, 1
	v_lshlrev_b32_e32 v1, 4, v10
	v_lshrrev_b32_e32 v2, 22, v2
	v_add_u32_e32 v2, v1, v2
	v_and_b32_e32 v2, 0xfffffc00, v2
	v_sub_u32_e32 v2, v1, v2
	v_lshrrev_b32_e32 v3, 4, v2
	v_bitop3_b32 v2, v3, v2, 32 bitop3:0x6c
	v_ashrrev_i32_e32 v4, 31, v2
	v_lshrrev_b32_e32 v4, 26, v4
	v_add_u32_e32 v4, v2, v4
	v_ashrrev_i32_e32 v13, 6, v4
	v_and_b32_e32 v4, 0xc0, v4
	v_lshlrev_b32_e32 v3, 3, v11
	v_sub_u32_e32 v2, v2, v4
	v_mov_b32_e32 v4, 1
	v_and_b32_e32 v3, -16, v3
	v_lshlrev_b32_e32 v5, 5, v11
	v_ashrrev_i16_sdwa v2, v4, sext(v2) dst_sel:DWORD dst_unused:UNUSED_PAD src0_sel:DWORD src1_sel:BYTE_0
	v_add_u32_e32 v3, v13, v3
	v_and_b32_e32 v12, 32, v5
	v_bfe_i32 v14, v2, 0, 16
	s_movk_i32 s6, 0xf00
	v_add_u32_e32 v2, v12, v14
	v_mul_lo_u32 v5, v3, s6
	v_lshlrev_b32_e32 v3, 12, v3
	v_add_u32_e32 v1, 0x2000, v1
	v_add_lshl_u32 v162, v2, v5, 1
	v_lshl_add_u32 v164, v2, 1, v3
	v_ashrrev_i32_e32 v2, 31, v1
	v_lshrrev_b32_e32 v2, 22, v2
	v_add_u32_e32 v2, v1, v2
	v_ashrrev_i32_e32 v15, 10, v2
	v_mul_i32_i24_e32 v2, 0x400, v15
	v_sub_u32_e32 v1, v1, v2
	v_lshrrev_b32_e32 v2, 4, v1
	v_bitop3_b32 v1, v2, v1, 32 bitop3:0x6c
	v_ashrrev_i32_e32 v3, 31, v1
	s_add_u32 s35, s38, 0x1100000
	v_lshrrev_b32_e32 v3, 26, v3
	s_addc_u32 s36, s39, 0
	v_add_u32_e32 v3, v1, v3
	s_ashr_i32 s5, s34, 6
	s_ashr_i32 s1, s0, 31
	s_ashr_i32 s4, s34, 8
	v_ashrrev_i32_e32 v16, 6, v3
	v_and_b32_e32 v3, 0xc0, v3
	s_lshl_b32 s37, s5, 10
	s_lshl_b64 s[2:3], s[0:1], 20
	v_lshlrev_b32_e32 v2, 3, v15
	v_sub_u32_e32 v1, v1, v3
	s_add_u32 s28, s35, s2
	v_and_b32_e32 v2, -16, v2
	v_lshlrev_b32_e32 v5, 5, v15
	v_ashrrev_i16_sdwa v1, v4, sext(v1) dst_sel:DWORD dst_unused:UNUSED_PAD src0_sel:DWORD src1_sel:BYTE_0
	s_addc_u32 s29, s36, s3
	s_add_i32 s41, s37, 0
	v_add_u32_e32 v2, v16, v2
	v_and_b32_e32 v17, 32, v5
	v_bfe_i32 v18, v1, 0, 16
	s_add_i32 m0, s41, 0x10000
	v_add_u32_e32 v1, v17, v18
	v_mul_lo_u32 v3, v2, s6
	v_lshlrev_b32_e32 v2, 12, v2
	s_mul_i32 s8, s52, 0x1e0000
	global_load_lds_dwordx4 v164, s[28:29]
	s_add_i32 m0, s41, 0x12000
	v_lshl_add_u32 v168, v1, 1, v2
	s_mul_hi_i32 s7, s52, 0x1e0000
	s_add_u32 s2, s54, s8
	global_load_lds_dwordx4 v168, s[28:29]
	s_addc_u32 s3, s55, s7
	s_mov_b32 m0, s41
	s_add_i32 s42, s41, 0x2000
	v_add_lshl_u32 v166, v1, v3, 1
	global_load_lds_dwordx4 v162, s[2:3]
	s_mov_b32 m0, s42
	s_add_u32 s8, s28, 0x80000
	global_load_lds_dwordx4 v166, s[2:3]
	s_addc_u32 s9, s29, 0
	s_add_i32 m0, s41, 0x14000
	v_mov_b32_e32 v165, 0
	global_load_lds_dwordx4 v164, s[8:9]
	s_add_i32 m0, s41, 0x16000
	v_mov_b32_e32 v169, v165
	global_load_lds_dwordx4 v168, s[8:9]
	s_add_u32 s8, s2, 0xf0000
	s_addc_u32 s9, s3, 0
	s_add_i32 s43, s41, 0x4000
	s_mov_b32 m0, s43
	s_add_i32 s44, s41, 0x6000
	global_load_lds_dwordx4 v162, s[8:9]
	s_mov_b32 m0, s44
	v_mov_b32_e32 v163, v165
	global_load_lds_dwordx4 v166, s[8:9]
	v_mov_b32_e32 v167, v165
	s_mov_b32 s45, 0
	v_lshl_add_u64 v[8:9], s[28:29], 0, v[164:165]
	v_lshl_add_u64 v[6:7], s[28:29], 0, v[168:169]
	v_lshl_add_u64 v[4:5], s[2:3], 0, v[162:163]
	v_lshl_add_u64 v[2:3], s[2:3], 0, v[166:167]
	s_cmp_lg_u32 s4, 1
	s_movk_i32 s46, 0x4000
	s_cbranch_scc1 .LBB0_685
	s_setprio 1
	s_barrier

.LBB0_696:
	ds_read_b128 v[82:85], v208
	ds_read_b128 v[86:89], v208 offset:1024
	ds_read_b128 v[94:97], v208 offset:2048
	ds_read_b128 v[102:105], v208 offset:3072
	s_add_u32 s8, s2, 0x100
	s_addc_u32 s9, s3, 0
	s_cmp_eq_u32 s68, 28
	s_cselect_b32 s31, s25, s9
	s_cselect_b32 s30, s24, s8
	s_cselect_b32 s29, s1, s63
	s_cselect_b32 s28, s23, s53
	v_lshl_add_u64 v[182:183], s[2:3], 0, v[170:171]
	s_add_i32 m0, s41, 0xc000
	ds_read_b128 v[146:149], v209
	ds_read_b128 v[150:153], v209 offset:1024
	ds_read_b128 v[154:157], v209 offset:2048
	ds_read_b128 v[158:161], v209 offset:3072
	ds_read_b128 v[178:181], v209 offset:4096
	ds_read_b128 v[186:189], v209 offset:5120
	ds_read_b128 v[190:193], v209 offset:6144
	ds_read_b128 v[194:197], v209 offset:7168
	global_load_lds_dwordx4 v[182:183], off
	v_lshl_add_u64 v[182:183], s[2:3], 0, v[172:173]
	s_add_i32 m0, s41, 0xe000
	s_nop 0
	global_load_lds_dwordx4 v[182:183], off
	ds_read_b128 v[198:201], v210
	ds_read_b128 v[202:205], v210 offset:1024
	ds_read_b128 v[212:215], v210 offset:2048
	ds_read_b128 v[216:219], v210 offset:3072
	s_waitcnt vmcnt(8)
	s_waitcnt lgkmcnt(0)
	s_barrier
	v_mfma_f32_16x16x32_bf16 v[142:145], v[82:85], v[146:149], v[142:145]
	v_mfma_f32_16x16x32_bf16 v[138:141], v[94:97], v[146:149], v[138:141]
	v_mfma_f32_16x16x32_bf16 v[126:129], v[82:85], v[154:157], v[126:129]
	v_mfma_f32_16x16x32_bf16 v[122:125], v[94:97], v[154:157], v[122:125]
	v_mfma_f32_16x16x32_bf16 v[110:113], v[82:85], v[178:181], v[110:113]
	v_mfma_f32_16x16x32_bf16 v[106:109], v[94:97], v[178:181], v[106:109]
	v_mfma_f32_16x16x32_bf16 v[78:81], v[82:85], v[190:193], v[78:81]
	v_mfma_f32_16x16x32_bf16 v[74:77], v[94:97], v[190:193], v[74:77]
	v_mfma_f32_16x16x32_bf16 v[142:145], v[86:89], v[150:153], v[142:145]
	v_mfma_f32_16x16x32_bf16 v[138:141], v[102:105], v[150:153], v[138:141]
	v_mfma_f32_16x16x32_bf16 v[126:129], v[86:89], v[158:161], v[126:129]
	v_mfma_f32_16x16x32_bf16 v[122:125], v[102:105], v[158:161], v[122:125]
	v_mfma_f32_16x16x32_bf16 v[110:113], v[86:89], v[186:189], v[110:113]
	v_mfma_f32_16x16x32_bf16 v[106:109], v[102:105], v[186:189], v[106:109]
	v_mfma_f32_16x16x32_bf16 v[78:81], v[86:89], v[194:197], v[78:81]
	v_mfma_f32_16x16x32_bf16 v[74:77], v[102:105], v[194:197], v[74:77]
	v_mfma_f32_16x16x32_bf16 v[134:137], v[198:201], v[146:149], v[134:137]
	v_mfma_f32_16x16x32_bf16 v[130:133], v[212:215], v[146:149], v[130:133]
	v_mfma_f32_16x16x32_bf16 v[118:121], v[198:201], v[154:157], v[118:121]
	v_mfma_f32_16x16x32_bf16 v[114:117], v[212:215], v[154:157], v[114:117]
	v_mfma_f32_16x16x32_bf16 v[98:101], v[198:201], v[178:181], v[98:101]
	v_mfma_f32_16x16x32_bf16 v[90:93], v[212:215], v[178:181], v[90:93]
	v_mfma_f32_16x16x32_bf16 v[70:73], v[198:201], v[190:193], v[70:73]
	v_mfma_f32_16x16x32_bf16 v[66:69], v[212:215], v[190:193], v[66:69]
	v_mfma_f32_16x16x32_bf16 v[134:137], v[202:205], v[150:153], v[134:137]
	v_mfma_f32_16x16x32_bf16 v[130:133], v[216:219], v[150:153], v[130:133]
	v_mfma_f32_16x16x32_bf16 v[118:121], v[202:205], v[158:161], v[118:121]
	v_mfma_f32_16x16x32_bf16 v[114:117], v[216:219], v[158:161], v[114:117]
	v_mfma_f32_16x16x32_bf16 v[98:101], v[202:205], v[186:189], v[98:101]
	v_mfma_f32_16x16x32_bf16 v[90:93], v[216:219], v[186:189], v[90:93]
	v_mfma_f32_16x16x32_bf16 v[70:73], v[202:205], v[194:197], v[70:73]
	v_mfma_f32_16x16x32_bf16 v[66:69], v[216:219], v[194:197], v[66:69]
	s_barrier
	s_add_i32 s2, s59, s37
	v_lshl_add_u64 v[182:183], s[28:29], 0, v[164:165]
	s_mov_b32 m0, s2
	global_load_lds_dwordx4 v164, s[28:29]
	v_lshl_add_u64 v[220:221], s[28:29], 0, v[168:169]
	s_add_i32 m0, s2, 0x2000
	s_nop 0
	global_load_lds_dwordx4 v168, s[28:29]
	s_mov_b32 m0, s41
	v_lshl_add_u64 v[222:223], s[30:31], 0, v[162:163]
	ds_read_b128 v[146:149], v209 offset:16384
	ds_read_b128 v[150:153], v209 offset:17408
	ds_read_b128 v[154:157], v209 offset:18432
	ds_read_b128 v[158:161], v209 offset:19456
	ds_read_b128 v[178:181], v209 offset:20480
	ds_read_b128 v[186:189], v209 offset:21504
	ds_read_b128 v[190:193], v209 offset:22528
	ds_read_b128 v[194:197], v209 offset:23552
	global_load_lds_dwordx4 v162, s[30:31]
	v_lshl_add_u64 v[224:225], s[30:31], 0, v[166:167]
	s_mov_b32 m0, s42
	s_nop 0
	global_load_lds_dwordx4 v166, s[30:31]
	s_waitcnt vmcnt(6)
	s_waitcnt lgkmcnt(0)
	s_barrier
	v_mfma_f32_16x16x32_bf16 v[62:65], v[82:85], v[146:149], v[62:65]
	v_mfma_f32_16x16x32_bf16 v[58:61], v[94:97], v[146:149], v[58:61]
	v_mfma_f32_16x16x32_bf16 v[46:49], v[82:85], v[154:157], v[46:49]
	v_mfma_f32_16x16x32_bf16 v[42:45], v[94:97], v[154:157], v[42:45]
	v_mfma_f32_16x16x32_bf16 v[30:33], v[82:85], v[178:181], v[30:33]
	v_mfma_f32_16x16x32_bf16 v[26:29], v[94:97], v[178:181], v[26:29]
	v_mfma_f32_16x16x32_bf16 v[14:17], v[82:85], v[190:193], v[14:17]
	v_mfma_f32_16x16x32_bf16 v[10:13], v[94:97], v[190:193], v[10:13]
	v_mfma_f32_16x16x32_bf16 v[62:65], v[86:89], v[150:153], v[62:65]
	v_mfma_f32_16x16x32_bf16 v[58:61], v[102:105], v[150:153], v[58:61]
	v_mfma_f32_16x16x32_bf16 v[46:49], v[86:89], v[158:161], v[46:49]
	v_mfma_f32_16x16x32_bf16 v[42:45], v[102:105], v[158:161], v[42:45]
	v_mfma_f32_16x16x32_bf16 v[30:33], v[86:89], v[186:189], v[30:33]
	v_mfma_f32_16x16x32_bf16 v[26:29], v[102:105], v[186:189], v[26:29]
	v_mfma_f32_16x16x32_bf16 v[14:17], v[86:89], v[194:197], v[14:17]
	v_mfma_f32_16x16x32_bf16 v[10:13], v[102:105], v[194:197], v[10:13]
	v_mfma_f32_16x16x32_bf16 v[54:57], v[198:201], v[146:149], v[54:57]
	v_mfma_f32_16x16x32_bf16 v[50:53], v[212:215], v[146:149], v[50:53]
	v_mfma_f32_16x16x32_bf16 v[38:41], v[198:201], v[154:157], v[38:41]
	v_mfma_f32_16x16x32_bf16 v[34:37], v[212:215], v[154:157], v[34:37]
	v_mfma_f32_16x16x32_bf16 v[22:25], v[198:201], v[178:181], v[22:25]
	v_mfma_f32_16x16x32_bf16 v[18:21], v[212:215], v[178:181], v[18:21]
	v_mfma_f32_16x16x32_bf16 v[6:9], v[198:201], v[190:193], v[6:9]
	v_mfma_f32_16x16x32_bf16 v[2:5], v[212:215], v[190:193], v[2:5]
	v_mfma_f32_16x16x32_bf16 v[54:57], v[202:205], v[150:153], v[54:57]
	v_mfma_f32_16x16x32_bf16 v[50:53], v[216:219], v[150:153], v[50:53]
	v_mfma_f32_16x16x32_bf16 v[38:41], v[202:205], v[158:161], v[38:41]
	v_mfma_f32_16x16x32_bf16 v[34:37], v[216:219], v[158:161], v[34:37]
	v_mfma_f32_16x16x32_bf16 v[22:25], v[202:205], v[186:189], v[22:25]
	v_mfma_f32_16x16x32_bf16 v[18:21], v[216:219], v[186:189], v[18:21]
	v_mfma_f32_16x16x32_bf16 v[6:9], v[202:205], v[194:197], v[6:9]
	v_mfma_f32_16x16x32_bf16 v[2:5], v[216:219], v[194:197], v[2:5]
	s_barrier
	s_add_u32 s2, s28, 0x80000
	s_addc_u32 s3, s29, 0
	s_add_i32 s69, s60, s37
	s_mov_b32 m0, s69
	s_nop 0
	global_load_lds_dwordx4 v164, s[2:3]
	s_add_i32 m0, s69, 0x2000
	s_nop 0
	global_load_lds_dwordx4 v168, s[2:3]
	s_add_i32 s69, 0, 0x18000
	v_add_u32_e32 v102, s69, v206
	ds_read_b128 v[82:85], v102
	ds_read_b128 v[86:89], v102 offset:1024
	ds_read_b128 v[94:97], v102 offset:2048
	ds_read_b128 v[102:105], v102 offset:3072
	s_add_u32 s2, s30, 0xf0000
	s_addc_u32 s3, s31, 0
	s_mov_b32 m0, s43
	ds_read_b128 v[146:149], v209 offset:32768
	ds_read_b128 v[150:153], v209 offset:33792
	ds_read_b128 v[154:157], v209 offset:34816
	ds_read_b128 v[158:161], v209 offset:35840
	ds_read_b128 v[178:181], v209 offset:36864
	ds_read_b128 v[186:189], v209 offset:37888
	ds_read_b128 v[190:193], v209 offset:38912
	ds_read_b128 v[194:197], v209 offset:39936
	v_add_u32_e32 v216, 0x1c000, v206
	ds_read_b128 v[198:201], v216
	ds_read_b128 v[202:205], v216 offset:1024
	ds_read_b128 v[212:215], v216 offset:2048
	ds_read_b128 v[216:219], v216 offset:3072
	global_load_lds_dwordx4 v162, s[2:3]
	s_mov_b32 m0, s44
	s_nop 0
	global_load_lds_dwordx4 v166, s[2:3]
	s_waitcnt vmcnt(8)
	s_waitcnt lgkmcnt(0)
	s_barrier
	v_mfma_f32_16x16x32_bf16 v[142:145], v[82:85], v[146:149], v[142:145]
	v_mfma_f32_16x16x32_bf16 v[138:141], v[94:97], v[146:149], v[138:141]
	v_mfma_f32_16x16x32_bf16 v[126:129], v[82:85], v[154:157], v[126:129]
	v_mfma_f32_16x16x32_bf16 v[122:125], v[94:97], v[154:157], v[122:125]
	v_mfma_f32_16x16x32_bf16 v[110:113], v[82:85], v[178:181], v[110:113]
	v_mfma_f32_16x16x32_bf16 v[106:109], v[94:97], v[178:181], v[106:109]
	v_mfma_f32_16x16x32_bf16 v[78:81], v[82:85], v[190:193], v[78:81]
	v_mfma_f32_16x16x32_bf16 v[74:77], v[94:97], v[190:193], v[74:77]
	v_mfma_f32_16x16x32_bf16 v[142:145], v[86:89], v[150:153], v[142:145]
	v_mfma_f32_16x16x32_bf16 v[138:141], v[102:105], v[150:153], v[138:141]
	v_mfma_f32_16x16x32_bf16 v[126:129], v[86:89], v[158:161], v[126:129]
	v_mfma_f32_16x16x32_bf16 v[122:125], v[102:105], v[158:161], v[122:125]
	v_mfma_f32_16x16x32_bf16 v[110:113], v[86:89], v[186:189], v[110:113]
	v_mfma_f32_16x16x32_bf16 v[106:109], v[102:105], v[186:189], v[106:109]
	v_mfma_f32_16x16x32_bf16 v[78:81], v[86:89], v[194:197], v[78:81]
	v_mfma_f32_16x16x32_bf16 v[74:77], v[102:105], v[194:197], v[74:77]
	v_mfma_f32_16x16x32_bf16 v[134:137], v[198:201], v[146:149], v[134:137]
	v_mfma_f32_16x16x32_bf16 v[130:133], v[212:215], v[146:149], v[130:133]
	v_mfma_f32_16x16x32_bf16 v[118:121], v[198:201], v[154:157], v[118:121]
	v_mfma_f32_16x16x32_bf16 v[114:117], v[212:215], v[154:157], v[114:117]
	v_mfma_f32_16x16x32_bf16 v[98:101], v[198:201], v[178:181], v[98:101]
	v_mfma_f32_16x16x32_bf16 v[90:93], v[212:215], v[178:181], v[90:93]
	v_mfma_f32_16x16x32_bf16 v[70:73], v[198:201], v[190:193], v[70:73]
	v_mfma_f32_16x16x32_bf16 v[66:69], v[212:215], v[190:193], v[66:69]
	v_mfma_f32_16x16x32_bf16 v[134:137], v[202:205], v[150:153], v[134:137]
	v_mfma_f32_16x16x32_bf16 v[130:133], v[216:219], v[150:153], v[130:133]
	v_mfma_f32_16x16x32_bf16 v[118:121], v[202:205], v[158:161], v[118:121]
	v_mfma_f32_16x16x32_bf16 v[114:117], v[216:219], v[158:161], v[114:117]
	v_mfma_f32_16x16x32_bf16 v[98:101], v[202:205], v[186:189], v[98:101]
	v_mfma_f32_16x16x32_bf16 v[90:93], v[216:219], v[186:189], v[90:93]
	v_mfma_f32_16x16x32_bf16 v[70:73], v[202:205], v[194:197], v[70:73]
	v_mfma_f32_16x16x32_bf16 v[66:69], v[216:219], v[194:197], v[66:69]
	s_barrier
	s_add_i32 s30, 0, 0x1c000
	s_add_i32 s2, s69, s37
	v_lshl_add_u64 v[182:183], v[182:183], 0, s[20:21]
	s_mov_b32 m0, s2
	global_load_lds_dwordx4 v[182:183], off
	v_lshl_add_u64 v[182:183], v[220:221], 0, s[20:21]
	s_add_i32 m0, s2, 0x2000
	s_nop 0
	global_load_lds_dwordx4 v[182:183], off
	s_mov_b32 m0, s47
	v_lshl_add_u64 v[182:183], v[222:223], 0, s[20:21]
	ds_read_b128 v[146:149], v209 offset:49152
	ds_read_b128 v[150:153], v209 offset:50176
	ds_read_b128 v[154:157], v209 offset:51200
	ds_read_b128 v[158:161], v209 offset:52224
	ds_read_b128 v[178:181], v209 offset:53248
	ds_read_b128 v[186:189], v209 offset:54272
	ds_read_b128 v[190:193], v209 offset:55296
	ds_read_b128 v[194:197], v209 offset:56320
	global_load_lds_dwordx4 v[182:183], off
	v_lshl_add_u64 v[182:183], v[224:225], 0, s[20:21]
	s_mov_b32 m0, s48
	s_nop 0
	global_load_lds_dwordx4 v[182:183], off
	s_add_u32 s2, s28, 0x80080
	s_addc_u32 s3, s29, 0
	s_add_i32 s28, s30, s37
	s_mov_b32 m0, s28
	s_nop 0
	global_load_lds_dwordx4 v164, s[2:3]
	s_add_i32 m0, s28, 0x2000
	s_nop 0
	global_load_lds_dwordx4 v168, s[2:3]
	s_waitcnt vmcnt(8)
	s_waitcnt lgkmcnt(0)
	s_barrier
	v_mfma_f32_16x16x32_bf16 v[62:65], v[82:85], v[146:149], v[62:65]
	v_mfma_f32_16x16x32_bf16 v[58:61], v[94:97], v[146:149], v[58:61]
	v_mfma_f32_16x16x32_bf16 v[46:49], v[82:85], v[154:157], v[46:49]
	v_mfma_f32_16x16x32_bf16 v[42:45], v[94:97], v[154:157], v[42:45]
	v_mfma_f32_16x16x32_bf16 v[30:33], v[82:85], v[178:181], v[30:33]
	v_mfma_f32_16x16x32_bf16 v[26:29], v[94:97], v[178:181], v[26:29]
	v_mfma_f32_16x16x32_bf16 v[14:17], v[82:85], v[190:193], v[14:17]
	v_mfma_f32_16x16x32_bf16 v[10:13], v[94:97], v[190:193], v[10:13]
	v_mfma_f32_16x16x32_bf16 v[62:65], v[86:89], v[150:153], v[62:65]
	v_mfma_f32_16x16x32_bf16 v[58:61], v[102:105], v[150:153], v[58:61]
	v_mfma_f32_16x16x32_bf16 v[46:49], v[86:89], v[158:161], v[46:49]
	v_mfma_f32_16x16x32_bf16 v[42:45], v[102:105], v[158:161], v[42:45]
	v_mfma_f32_16x16x32_bf16 v[30:33], v[86:89], v[186:189], v[30:33]
	v_mfma_f32_16x16x32_bf16 v[26:29], v[102:105], v[186:189], v[26:29]
	v_mfma_f32_16x16x32_bf16 v[14:17], v[86:89], v[194:197], v[14:17]
	v_mfma_f32_16x16x32_bf16 v[10:13], v[102:105], v[194:197], v[10:13]
	v_mfma_f32_16x16x32_bf16 v[54:57], v[198:201], v[146:149], v[54:57]
	v_mfma_f32_16x16x32_bf16 v[50:53], v[212:215], v[146:149], v[50:53]
	v_mfma_f32_16x16x32_bf16 v[38:41], v[198:201], v[154:157], v[38:41]
	v_mfma_f32_16x16x32_bf16 v[34:37], v[212:215], v[154:157], v[34:37]
	v_mfma_f32_16x16x32_bf16 v[22:25], v[198:201], v[178:181], v[22:25]
	v_mfma_f32_16x16x32_bf16 v[18:21], v[212:215], v[178:181], v[18:21]
	v_mfma_f32_16x16x32_bf16 v[6:9], v[198:201], v[190:193], v[6:9]
	v_mfma_f32_16x16x32_bf16 v[2:5], v[212:215], v[190:193], v[2:5]
	v_mfma_f32_16x16x32_bf16 v[54:57], v[202:205], v[150:153], v[54:57]
	v_mfma_f32_16x16x32_bf16 v[50:53], v[216:219], v[150:153], v[50:53]
	v_mfma_f32_16x16x32_bf16 v[38:41], v[202:205], v[158:161], v[38:41]
	v_mfma_f32_16x16x32_bf16 v[34:37], v[216:219], v[158:161], v[34:37]
	v_mfma_f32_16x16x32_bf16 v[22:25], v[202:205], v[186:189], v[22:25]
	v_mfma_f32_16x16x32_bf16 v[18:21], v[216:219], v[186:189], v[18:21]
	v_mfma_f32_16x16x32_bf16 v[6:9], v[202:205], v[194:197], v[6:9]
	v_mfma_f32_16x16x32_bf16 v[2:5], v[216:219], v[194:197], v[2:5]
	s_add_i32 s68, s68, 2
	s_add_u32 s53, s53, 0x100
	s_addc_u32 s63, s63, 0
	s_cmp_gt_u32 s68, 29
	s_mov_b64 s[2:3], s[8:9]
	s_barrier
	s_cbranch_scc0 .LBB0_696
	s_min_i32 s1, s52, 64
	s_ashr_i32 s1, s1, 3
	v_lshl_or_b32 v178, s0, 8, v207
	s_mul_hi_i32 s2, s1, 0xc000
	s_mul_i32 s1, s1, 0xc000
	s_add_u32 s0, s10, s1
	v_ashrrev_i32_e32 v179, 31, v178
	s_addc_u32 s1, s11, s2
	v_lshlrev_b64 v[198:199], 2, v[178:179]
	v_lshl_add_u32 v200, s52, 8, v1
	v_lshl_add_u64 v[82:83], s[0:1], 0, v[198:199]
	v_add_u32_e32 v94, 0xffffc000, v200
	v_ashrrev_i32_e32 v201, 31, v200
	v_cmp_gt_i32_e64 s[0:1], s46, v200
	v_add_co_u32_e32 v84, vcc, s46, v82
	s_nop 0
	v_cndmask_b32_e64 v95, 0, v201, s[0:1]
	v_cndmask_b32_e64 v94, v94, v200, s[0:1]
	v_mov_b32_e32 v152, s15
	v_mov_b32_e32 v153, s13
	v_mov_b32_e32 v154, s14
	v_mov_b32_e32 v155, s12
	v_addc_co_u32_e32 v85, vcc, 0, v83, vcc
	v_cndmask_b32_e64 v97, v152, v153, s[0:1]
	v_cndmask_b32_e64 v96, v154, v155, s[0:1]
	v_lshlrev_b64 v[94:95], 13, v[94:95]
	v_add_co_u32_e32 v82, vcc, s49, v82
	v_lshl_add_u64 v[94:95], v[96:97], 0, v[94:95]
	v_lshl_add_u64 v[146:147], v[94:95], 0, v[198:199]
	v_addc_co_u32_e32 v83, vcc, 0, v83, vcc
	global_load_dwordx4 v[86:89], v[84:85], off
	global_load_dwordx4 v[180:183], v[146:147], off
	global_load_dwordx4 v[186:189], v[82:83], off
	global_load_dwordx4 v[190:193], v[82:83], off offset:64
	global_load_dwordx4 v[194:197], v[82:83], off offset:512
	global_load_dwordx4 v[212:215], v[82:83], off offset:576
	v_lshl_add_u64 v[82:83], s[56:57], 0, v[198:199]
	global_load_dwordx4 v[216:219], v[82:83], off
	global_load_dwordx4 v[220:223], v[82:83], off offset:64
	global_load_dwordx4 v[224:227], v[82:83], off offset:512
	global_load_dwordx4 v[228:231], v[82:83], off offset:576
	global_load_dwordx4 v[232:235], v[146:147], off offset:64
	global_load_dwordx4 v[102:105], v[84:85], off offset:64
	global_load_dwordx4 v[94:97], v[84:85], off offset:512
	global_load_dwordx4 v[236:239], v[146:147], off offset:512
	global_load_dwordx4 v[240:243], v[146:147], off offset:576
	s_nop 0
	global_load_dwordx4 v[82:85], v[84:85], off offset:576
	v_or_b32_e32 v202, 16, v200
	v_add_u32_e32 v150, 0xffffc010, v200
	v_ashrrev_i32_e32 v203, 31, v202
	v_cmp_gt_i32_e32 vcc, s46, v202
	v_lshlrev_b64 v[146:147], 13, v[200:201]
	v_lshl_add_u64 v[146:147], s[66:67], 0, v[146:147]
	v_cndmask_b32_e32 v151, 0, v203, vcc
	v_cndmask_b32_e32 v150, v150, v202, vcc
	v_cndmask_b32_e32 v153, v152, v153, vcc
	v_cndmask_b32_e32 v152, v154, v155, vcc
	v_lshlrev_b64 v[150:151], 13, v[150:151]
	v_lshlrev_b64 v[148:149], 12, v[200:201]
	v_lshl_add_u64 v[204:205], v[146:147], 0, v[198:199]
	v_lshl_add_u64 v[146:147], v[152:153], 0, v[150:151]
	v_lshl_add_u64 v[148:149], s[88:89], 0, v[148:149]
	v_lshl_add_u64 v[146:147], v[146:147], 0, v[198:199]
	v_lshl_add_u64 v[244:245], v[178:179], 1, v[148:149]
	global_load_dwordx4 v[158:161], v[146:147], off
	global_load_dwordx4 v[154:157], v[146:147], off offset:64
	global_load_dwordx4 v[150:153], v[146:147], off offset:512
	s_nop 0
	global_load_dwordx4 v[146:149], v[146:147], off offset:576
	s_waitcnt vmcnt(0)
	v_pk_fma_f32 v[138:139], v[138:139], v[102:103], v[232:233]
	v_pk_fma_f32 v[144:145], v[144:145], v[88:89], v[182:183]
	v_pk_fma_f32 v[142:143], v[142:143], v[86:87], v[180:181]
	v_pk_add_f32 v[180:181], v[188:189], 1.0 op_sel_hi:[1,0]
	v_pk_add_f32 v[182:183], v[186:187], 1.0 op_sel_hi:[1,0]
	v_pk_add_f32 v[212:213], v[212:213], 1.0 op_sel_hi:[1,0]
	v_pk_add_f32 v[246:247], v[196:197], 1.0 op_sel_hi:[1,0]
	v_pk_add_f32 v[248:249], v[194:195], 1.0 op_sel_hi:[1,0]
	v_pk_mul_f32 v[194:195], v[218:219], v[180:181]
	v_pk_mul_f32 v[196:197], v[216:217], v[182:183]
	v_pk_mul_f32 v[180:181], v[228:229], v[212:213]
	v_mul_f32_e32 v212, v143, v143
	global_store_dwordx4 v[204:205], v[142:145], off
	v_fmac_f32_e32 v212, v142, v142
	v_pk_add_f32 v[188:189], v[190:191], 1.0 op_sel_hi:[1,0]
	v_pk_mul_f32 v[142:143], v[196:197], v[142:143]
	v_fmac_f32_e32 v212, v144, v144
	v_cvt_pk_bf16_f32 v142, v142, v143
	v_pk_add_f32 v[186:187], v[192:193], 1.0 op_sel_hi:[1,0]
	v_pk_mul_f32 v[192:193], v[220:221], v[188:189]
	v_fmac_f32_e32 v212, v145, v145
	v_pk_mul_f32 v[144:145], v[194:195], v[144:145]
	v_pk_fma_f32 v[140:141], v[140:141], v[104:105], v[234:235]
	v_cvt_pk_bf16_f32 v143, v144, v145
	global_store_dwordx2 v[244:245], v[142:143], off
	v_mul_f32_e32 v142, v139, v139
	global_store_dwordx4 v[204:205], v[138:141], off offset:64
	v_fmac_f32_e32 v142, v138, v138
	v_pk_mul_f32 v[190:191], v[222:223], v[186:187]
	v_pk_mul_f32 v[138:139], v[192:193], v[138:139]
	v_fmac_f32_e32 v142, v140, v140
	v_cvt_pk_bf16_f32 v138, v138, v139
	v_pk_fma_f32 v[134:135], v[134:135], v[94:95], v[236:237]
	v_fmac_f32_e32 v142, v141, v141
	v_pk_mul_f32 v[140:141], v[190:191], v[140:141]
	v_pk_fma_f32 v[136:137], v[136:137], v[96:97], v[238:239]
	v_cvt_pk_bf16_f32 v139, v140, v141
	global_store_dwordx2 v[244:245], v[138:139], off offset:32
	v_mul_f32_e32 v138, v135, v135
	v_fmac_f32_e32 v138, v134, v134
	v_pk_mul_f32 v[188:189], v[224:225], v[248:249]
	v_fmac_f32_e32 v138, v136, v136
	v_add_f32_e32 v142, v212, v142
	global_store_dwordx4 v[204:205], v[134:137], off offset:512
	v_fmac_f32_e32 v138, v137, v137
	v_add_f32_e32 v139, v142, v138
	v_pk_mul_f32 v[134:135], v[188:189], v[134:135]
	v_pk_mul_f32 v[186:187], v[226:227], v[246:247]
	v_cvt_pk_bf16_f32 v138, v134, v135
	v_pk_fma_f32 v[134:135], v[132:133], v[84:85], v[242:243]
	v_pk_fma_f32 v[132:133], v[130:131], v[82:83], v[240:241]
	v_xor_b32_e32 v131, 16, v211
	v_mul_f32_e32 v130, v133, v133
	v_fmac_f32_e32 v130, v132, v132
	v_fmac_f32_e32 v130, v134, v134
	v_fmac_f32_e32 v130, v135, v135
	v_add_f32_e32 v130, v139, v130
	v_and_b32_e32 v139, 64, v211
	v_add_u32_e32 v140, 64, v139
	v_cmp_lt_i32_e32 vcc, v131, v140
	v_pk_add_f32 v[214:215], v[214:215], 1.0 op_sel_hi:[1,0]
	v_pk_mul_f32 v[136:137], v[186:187], v[136:137]
	v_cndmask_b32_e32 v131, v211, v131, vcc
	v_lshlrev_b32_e32 v212, 2, v131
	ds_bpermute_b32 v131, v212, v130
	v_cvt_pk_bf16_f32 v139, v136, v137
	v_pk_mul_f32 v[182:183], v[230:231], v[214:215]
	global_store_dwordx2 v[244:245], v[138:139], off offset:256
	global_store_dwordx4 v[204:205], v[132:135], off offset:576
	s_waitcnt lgkmcnt(0)
	v_add_f32_e32 v130, v130, v131
	v_xor_b32_e32 v131, 32, v211
	v_cmp_lt_i32_e32 vcc, v131, v140
	v_pk_mul_f32 v[132:133], v[180:181], v[132:133]
	v_pk_mul_f32 v[134:135], v[182:183], v[134:135]
	v_cndmask_b32_e32 v131, v211, v131, vcc
	v_lshlrev_b32_e32 v213, 2, v131
	ds_bpermute_b32 v131, v213, v130
	v_cvt_pk_bf16_f32 v132, v132, v133
	v_cvt_pk_bf16_f32 v133, v134, v135
	global_store_dwordx2 v[244:245], v[132:133], off offset:288
	s_and_saveexec_b64 s[0:1], s[4:5]
	s_cbranch_execz .LBB0_699
	v_lshl_add_u64 v[132:133], v[200:201], 2, s[18:19]
	s_waitcnt lgkmcnt(0)
	v_add_f32_e32 v130, v130, v131
	global_atomic_add_f32 v[132:133], v130, off

.LBB0_791:
	s_andn2_b64 vcc, exec, s[2:3]
	s_cbranch_vccnz .LBB0_875
	v_readlane_b32 s2, v253, 12
	v_mov_b32_e32 v6, v184
	v_readlane_b32 s3, v253, 13
	s_and_b64 vcc, exec, s[2:3]
	v_readfirstlane_b32 s22, v6
	s_cbranch_vccnz .LBB0_808
	s_waitcnt lgkmcnt(0)
	v_lshlrev_b32_e32 v3, 4, v6
	v_add_u32_e32 v1, 0x2000, v3
	v_ashrrev_i32_e32 v0, 31, v1
	v_lshrrev_b32_e32 v0, 22, v0
	v_add_u32_e32 v0, v1, v0
	v_ashrrev_i32_e32 v0, 10, v0
	v_mul_i32_i24_e32 v2, 0x400, v0
	v_sub_u32_e32 v1, v1, v2
	v_lshrrev_b32_e32 v2, 4, v1
	v_bitop3_b32 v2, v2, v1, 32 bitop3:0x6c
	v_ashrrev_i32_e32 v1, 31, v2
	v_lshrrev_b32_e32 v1, 26, v1
	v_add_u32_e32 v4, v2, v1
	v_lshlrev_b32_e32 v5, 3, v0
	v_ashrrev_i32_e32 v1, 6, v4
	v_and_b32_e32 v5, -16, v5
	v_add_u32_e32 v5, v1, v5
	v_and_b32_e32 v7, 3, v1
	s_mov_b32 s4, 0xfffe0
	v_lshrrev_b32_e32 v8, 2, v5
	v_lshlrev_b32_e32 v9, 1, v5
	v_and_b32_e32 v4, 0xc0, v4
	v_and_or_b32 v7, v5, s4, v7
	v_and_b32_e32 v8, 4, v8
	v_and_b32_e32 v9, 24, v9
	v_sub_u32_e32 v2, v2, v4
	v_or3_b32 v7, v7, v8, v9
	v_lshlrev_b32_e32 v8, 5, v0
	v_ashrrev_i16_sdwa v2, v230, sext(v2) dst_sel:DWORD dst_unused:UNUSED_PAD src0_sel:DWORD src1_sel:BYTE_0
	v_and_b32_e32 v8, 32, v8
	v_bfe_i32 v2, v2, 0, 16
	v_add_lshl_u32 v4, v8, v2, 1
	v_lshl_add_u32 v144, v7, 12, v4
	v_lshl_add_u32 v146, v5, 12, v4
	v_bfe_i32 v4, v6, 27, 1
	v_lshrrev_b32_e32 v4, 22, v4
	v_add_u32_e32 v4, v3, v4
	v_and_b32_e32 v4, 0xfffffc00, v4
	v_sub_u32_e32 v3, v3, v4
	v_lshrrev_b32_e32 v4, 4, v3
	v_bitop3_b32 v5, v4, v3, 32 bitop3:0x6c
	v_ashrrev_i32_e32 v4, 31, v6
	v_lshrrev_b32_e32 v4, 26, v4
	v_ashrrev_i32_e32 v3, 31, v5
	v_add_u32_e32 v4, v6, v4
	v_lshrrev_b32_e32 v3, 26, v3
	v_ashrrev_i32_e32 v4, 6, v4
	v_add_u32_e32 v7, v5, v3
	v_lshlrev_b32_e32 v8, 3, v4
	v_ashrrev_i32_e32 v3, 6, v7
	v_and_b32_e32 v8, -16, v8
	v_add_u32_e32 v8, v3, v8
	s_lshl_b32 s2, s47, 25
	v_readlane_b32 s12, v253, 10
	v_and_b32_e32 v9, 3, v3
	v_lshrrev_b32_e32 v10, 2, v8
	v_lshlrev_b32_e32 v11, 1, v8
	v_and_b32_e32 v7, 0xc0, v7
	v_readlane_b32 s13, v253, 11
	s_add_u32 s23, s12, s2
	v_and_or_b32 v9, v8, s4, v9
	v_and_b32_e32 v10, 4, v10
	v_and_b32_e32 v11, 24, v11
	v_sub_u32_e32 v5, v5, v7
	s_addc_u32 s26, s13, 0
	s_ashr_i32 s2, s22, 6
	v_or3_b32 v9, v9, v10, v11
	v_lshlrev_b32_e32 v10, 5, v4
	v_ashrrev_i16_sdwa v5, v230, sext(v5) dst_sel:DWORD dst_unused:UNUSED_PAD src0_sel:DWORD src1_sel:BYTE_0
	s_lshl_b32 s27, s2, 10
	v_and_b32_e32 v10, 32, v10
	v_bfe_i32 v5, v5, 0, 16
	v_add_lshl_u32 v7, v10, v5, 1
	s_add_i32 s16, s27, 0
	v_readlane_b32 s12, v252, 16
	v_lshl_add_u32 v186, v9, 12, v7
	s_add_i32 m0, s16, 0x10000
	v_readlane_b32 s13, v252, 17
	s_ashr_i32 s3, s22, 8
	v_lshl_add_u32 v148, v8, 12, v7
	v_readlane_b32 s14, v252, 14
	v_readlane_b32 s15, v252, 15
	s_nop 0
	global_load_lds_dwordx4 v186, s[12:13]
	s_add_i32 m0, s16, 0x12000
	s_nop 0
	global_load_lds_dwordx4 v144, s[12:13]
	v_readlane_b32 s12, v252, 12
	v_readlane_b32 s13, v252, 13
	s_add_u32 s12, s23, s12
	s_addc_u32 s13, s26, s13
	s_mov_b32 m0, s16
	s_add_i32 s17, s16, 0x2000
	s_nop 0
	global_load_lds_dwordx4 v148, s[12:13]
	s_mov_b32 m0, s17
	s_nop 0
	global_load_lds_dwordx4 v146, s[12:13]
	s_add_i32 m0, s16, 0x14000
	s_nop 0
	global_load_lds_dwordx4 v186, s[14:15]
	s_add_i32 m0, s16, 0x16000
	s_nop 0
	global_load_lds_dwordx4 v144, s[14:15]
	s_add_u32 s14, s12, 0x80000
	s_addc_u32 s15, s13, 0
	s_add_i32 s30, s16, 0x4000
	s_mov_b32 m0, s30
	s_add_i32 s31, s16, 0x6000
	global_load_lds_dwordx4 v148, s[14:15]
	s_mov_b32 m0, s31
	s_cmp_lg_u32 s3, 1
	global_load_lds_dwordx4 v146, s[14:15]
	s_cbranch_scc1 .LBB0_795
	s_setprio 1
	s_barrier

.LBB0_802:
	s_ashr_i32 s15, s14, 31
	v_cmp_lt_i64_e32 vcc, s[18:19], v[190:191]
	s_lshl_b64 s[18:19], s[14:15], 20
	s_add_u32 s18, s23, s18
	s_addc_u32 s19, s26, s19
	s_and_b64 s[24:25], vcc, exec
	s_cselect_b32 s15, s19, s13
	s_cselect_b32 s45, s18, s12
	s_ashr_i32 s3, s2, 31
	s_lshl_b64 s[24:25], s[2:3], 20
	s_add_u32 s28, s73, s24
	s_addc_u32 s29, s36, s25
	s_and_b64 s[24:25], vcc, exec
	s_cselect_b32 s3, s29, s21
	s_cselect_b32 s52, s28, s20
	s_add_u32 s12, s12, 0x80080
	s_addc_u32 s13, s13, 0
	s_add_u32 s53, s20, 0x100
	v_mov_b32_e32 v0, 0
	s_addc_u32 s56, s21, 0
	s_mov_b32 s57, -2
	v_mov_b32_e32 v1, v0
	v_mov_b32_e32 v2, v0
	v_mov_b32_e32 v3, v0
	v_mov_b32_e32 v4, v0
	v_mov_b32_e32 v5, v0
	v_mov_b32_e32 v6, v0
	v_mov_b32_e32 v7, v0
	v_mov_b32_e32 v16, v0
	v_mov_b32_e32 v17, v0
	v_mov_b32_e32 v18, v0
	v_mov_b32_e32 v19, v0
	v_mov_b32_e32 v20, v0
	v_mov_b32_e32 v21, v0
	v_mov_b32_e32 v22, v0
	v_mov_b32_e32 v23, v0
	v_mov_b32_e32 v32, v0
	v_mov_b32_e32 v33, v0
	v_mov_b32_e32 v34, v0
	v_mov_b32_e32 v35, v0
	v_mov_b32_e32 v36, v0
	v_mov_b32_e32 v37, v0
	v_mov_b32_e32 v38, v0
	v_mov_b32_e32 v39, v0
	v_mov_b32_e32 v48, v0
	v_mov_b32_e32 v49, v0
	v_mov_b32_e32 v50, v0
	v_mov_b32_e32 v51, v0
	v_mov_b32_e32 v52, v0
	v_mov_b32_e32 v53, v0
	v_mov_b32_e32 v54, v0
	v_mov_b32_e32 v55, v0
	v_mov_b32_e32 v8, v0
	v_mov_b32_e32 v9, v0
	v_mov_b32_e32 v10, v0
	v_mov_b32_e32 v11, v0
	v_mov_b32_e32 v12, v0
	v_mov_b32_e32 v13, v0
	v_mov_b32_e32 v14, v0
	v_mov_b32_e32 v15, v0
	v_mov_b32_e32 v24, v0
	v_mov_b32_e32 v25, v0
	v_mov_b32_e32 v26, v0
	v_mov_b32_e32 v27, v0
	v_mov_b32_e32 v28, v0
	v_mov_b32_e32 v29, v0
	v_mov_b32_e32 v30, v0
	v_mov_b32_e32 v31, v0
	v_mov_b32_e32 v40, v0
	v_mov_b32_e32 v41, v0
	v_mov_b32_e32 v42, v0
	v_mov_b32_e32 v43, v0
	v_mov_b32_e32 v44, v0
	v_mov_b32_e32 v45, v0
	v_mov_b32_e32 v46, v0
	v_mov_b32_e32 v47, v0
	v_mov_b32_e32 v56, v0
	v_mov_b32_e32 v57, v0
	v_mov_b32_e32 v58, v0
	v_mov_b32_e32 v59, v0
	v_mov_b32_e32 v60, v0
	v_mov_b32_e32 v61, v0
	v_mov_b32_e32 v62, v0
	v_mov_b32_e32 v63, v0
	v_mov_b32_e32 v64, v0
	v_mov_b32_e32 v65, v0
	v_mov_b32_e32 v66, v0
	v_mov_b32_e32 v67, v0
	v_mov_b32_e32 v68, v0
	v_mov_b32_e32 v69, v0
	v_mov_b32_e32 v70, v0
	v_mov_b32_e32 v71, v0
	v_mov_b32_e32 v80, v0
	v_mov_b32_e32 v81, v0
	v_mov_b32_e32 v82, v0
	v_mov_b32_e32 v83, v0
	v_mov_b32_e32 v84, v0
	v_mov_b32_e32 v85, v0
	v_mov_b32_e32 v86, v0
	v_mov_b32_e32 v87, v0
	v_mov_b32_e32 v96, v0
	v_mov_b32_e32 v97, v0
	v_mov_b32_e32 v98, v0
	v_mov_b32_e32 v99, v0
	v_mov_b32_e32 v100, v0
	v_mov_b32_e32 v101, v0
	v_mov_b32_e32 v102, v0
	v_mov_b32_e32 v103, v0
	v_mov_b32_e32 v112, v0
	v_mov_b32_e32 v113, v0
	v_mov_b32_e32 v114, v0
	v_mov_b32_e32 v115, v0
	v_mov_b32_e32 v116, v0
	v_mov_b32_e32 v117, v0
	v_mov_b32_e32 v118, v0
	v_mov_b32_e32 v119, v0
	v_mov_b32_e32 v72, v0
	v_mov_b32_e32 v73, v0
	v_mov_b32_e32 v74, v0
	v_mov_b32_e32 v75, v0
	v_mov_b32_e32 v76, v0
	v_mov_b32_e32 v77, v0
	v_mov_b32_e32 v78, v0
	v_mov_b32_e32 v79, v0
	v_mov_b32_e32 v88, v0
	v_mov_b32_e32 v89, v0
	v_mov_b32_e32 v90, v0
	v_mov_b32_e32 v91, v0
	v_mov_b32_e32 v92, v0
	v_mov_b32_e32 v93, v0
	v_mov_b32_e32 v94, v0
	v_mov_b32_e32 v95, v0
	v_mov_b32_e32 v104, v0
	v_mov_b32_e32 v105, v0
	v_mov_b32_e32 v106, v0
	v_mov_b32_e32 v107, v0
	v_mov_b32_e32 v108, v0
	v_mov_b32_e32 v109, v0
	v_mov_b32_e32 v110, v0
	v_mov_b32_e32 v111, v0
	v_mov_b32_e32 v120, v0
	v_mov_b32_e32 v121, v0
	v_mov_b32_e32 v122, v0
	v_mov_b32_e32 v123, v0
	v_mov_b32_e32 v124, v0
	v_mov_b32_e32 v125, v0
	v_mov_b32_e32 v126, v0
	v_mov_b32_e32 v127, v0
	s_cmp_eq_u32 s98, 0
	s_cbranch_scc1 .LBB0_803
	s_add_u32 s4, s12, 0xfff80080
	s_addc_u32 s20, s13, -1
	s_add_i32 s58, 0, 0x10000
	v_add_u32_e32 v140, s58, v161
	ds_read_b128 v[128:131], v140
	ds_read_b128 v[132:135], v140 offset:1024
	ds_read_b128 v[136:139], v140 offset:2048
	ds_read_b128 v[140:143], v140 offset:3072
	s_cmp_eq_u32 s57, 28
	s_cselect_b32 s25, s15, s20
	s_cselect_b32 s24, s45, s4
	s_cselect_b32 s21, s3, s56
	s_cselect_b32 s20, s52, s53
	v_lshl_add_u64 v[158:159], s[12:13], 0, v[150:151]
	s_add_i32 m0, s16, 0xc000
	ds_read_b128 v[154:157], v163
	ds_read_b128 v[164:167], v163 offset:1024
	ds_read_b128 v[168:171], v163 offset:2048
	ds_read_b128 v[172:175], v163 offset:3072
	ds_read_b128 v[176:179], v163 offset:4096
	ds_read_b128 v[180:183], v163 offset:5120
	ds_read_b128 v[196:199], v163 offset:6144
	ds_read_b128 v[200:203], v163 offset:7168
	v_add_u32_e32 v216, 0x14000, v161
	ds_read_b128 v[204:207], v216
	ds_read_b128 v[208:211], v216 offset:1024
	ds_read_b128 v[212:215], v216 offset:2048
	ds_read_b128 v[216:219], v216 offset:3072
	global_load_lds_dwordx4 v150, s[12:13]
	v_lshl_add_u64 v[158:159], s[12:13], 0, v[152:153]
	s_add_i32 m0, s16, 0xe000
	s_nop 0
	global_load_lds_dwordx4 v152, s[12:13]
	s_waitcnt vmcnt(24)
	s_waitcnt lgkmcnt(0)
	s_barrier
	v_mfma_f32_16x16x32_bf16 v[124:127], v[128:131], v[154:157], v[124:127]
	v_mfma_f32_16x16x32_bf16 v[120:123], v[136:139], v[154:157], v[120:123]
	v_mfma_f32_16x16x32_bf16 v[108:111], v[128:131], v[168:171], v[108:111]
	v_mfma_f32_16x16x32_bf16 v[104:107], v[136:139], v[168:171], v[104:107]
	v_mfma_f32_16x16x32_bf16 v[92:95], v[128:131], v[176:179], v[92:95]
	v_mfma_f32_16x16x32_bf16 v[88:91], v[136:139], v[176:179], v[88:91]
	v_mfma_f32_16x16x32_bf16 v[76:79], v[128:131], v[196:199], v[76:79]
	v_mfma_f32_16x16x32_bf16 v[72:75], v[136:139], v[196:199], v[72:75]
	v_mfma_f32_16x16x32_bf16 v[124:127], v[132:135], v[164:167], v[124:127]
	v_mfma_f32_16x16x32_bf16 v[120:123], v[140:143], v[164:167], v[120:123]
	v_mfma_f32_16x16x32_bf16 v[108:111], v[132:135], v[172:175], v[108:111]
	v_mfma_f32_16x16x32_bf16 v[104:107], v[140:143], v[172:175], v[104:107]
	v_mfma_f32_16x16x32_bf16 v[92:95], v[132:135], v[180:183], v[92:95]
	v_mfma_f32_16x16x32_bf16 v[88:91], v[140:143], v[180:183], v[88:91]
	v_mfma_f32_16x16x32_bf16 v[76:79], v[132:135], v[200:203], v[76:79]
	v_mfma_f32_16x16x32_bf16 v[72:75], v[140:143], v[200:203], v[72:75]
	v_mfma_f32_16x16x32_bf16 v[116:119], v[204:207], v[154:157], v[116:119]
	v_mfma_f32_16x16x32_bf16 v[112:115], v[212:215], v[154:157], v[112:115]
	v_mfma_f32_16x16x32_bf16 v[100:103], v[204:207], v[168:171], v[100:103]
	v_mfma_f32_16x16x32_bf16 v[96:99], v[212:215], v[168:171], v[96:99]
	v_mfma_f32_16x16x32_bf16 v[84:87], v[204:207], v[176:179], v[84:87]
	v_mfma_f32_16x16x32_bf16 v[80:83], v[212:215], v[176:179], v[80:83]
	v_mfma_f32_16x16x32_bf16 v[68:71], v[204:207], v[196:199], v[68:71]
	v_mfma_f32_16x16x32_bf16 v[64:67], v[212:215], v[196:199], v[64:67]
	v_mfma_f32_16x16x32_bf16 v[116:119], v[208:211], v[164:167], v[116:119]
	v_mfma_f32_16x16x32_bf16 v[112:115], v[216:219], v[164:167], v[112:115]
	v_mfma_f32_16x16x32_bf16 v[100:103], v[208:211], v[172:175], v[100:103]
	v_mfma_f32_16x16x32_bf16 v[96:99], v[216:219], v[172:175], v[96:99]
	v_mfma_f32_16x16x32_bf16 v[84:87], v[208:211], v[180:183], v[84:87]
	v_mfma_f32_16x16x32_bf16 v[80:83], v[216:219], v[180:183], v[80:83]
	v_mfma_f32_16x16x32_bf16 v[68:71], v[208:211], v[200:203], v[68:71]
	v_mfma_f32_16x16x32_bf16 v[64:67], v[216:219], v[200:203], v[64:67]
	s_barrier
	s_add_i32 s4, 0, 0x14000
	s_add_i32 s58, s58, s27
	v_lshl_add_u64 v[158:159], s[20:21], 0, v[186:187]
	s_mov_b32 m0, s58
	v_lshl_add_u64 v[220:221], s[20:21], 0, v[144:145]
	global_load_lds_dwordx4 v186, s[20:21]
	s_add_i32 m0, s58, 0x2000
	s_nop 0
	global_load_lds_dwordx4 v144, s[20:21]
	s_mov_b32 m0, s16
	v_lshl_add_u64 v[222:223], s[24:25], 0, v[148:149]
	ds_read_b128 v[154:157], v163 offset:16384
	ds_read_b128 v[164:167], v163 offset:17408
	ds_read_b128 v[168:171], v163 offset:18432
	ds_read_b128 v[172:175], v163 offset:19456
	ds_read_b128 v[176:179], v163 offset:20480
	ds_read_b128 v[180:183], v163 offset:21504
	ds_read_b128 v[196:199], v163 offset:22528
	ds_read_b128 v[200:203], v163 offset:23552
	global_load_lds_dwordx4 v148, s[24:25]
	v_lshl_add_u64 v[224:225], s[24:25], 0, v[146:147]
	s_mov_b32 m0, s17
	s_nop 0
	global_load_lds_dwordx4 v146, s[24:25]
	s_waitcnt vmcnt(22)
	s_waitcnt lgkmcnt(0)
	s_barrier
	v_mfma_f32_16x16x32_bf16 v[60:63], v[128:131], v[154:157], v[60:63]
	v_mfma_f32_16x16x32_bf16 v[56:59], v[136:139], v[154:157], v[56:59]
	v_mfma_f32_16x16x32_bf16 v[44:47], v[128:131], v[168:171], v[44:47]
	v_mfma_f32_16x16x32_bf16 v[40:43], v[136:139], v[168:171], v[40:43]
	v_mfma_f32_16x16x32_bf16 v[28:31], v[128:131], v[176:179], v[28:31]
	v_mfma_f32_16x16x32_bf16 v[24:27], v[136:139], v[176:179], v[24:27]
	v_mfma_f32_16x16x32_bf16 v[12:15], v[128:131], v[196:199], v[12:15]
	v_mfma_f32_16x16x32_bf16 v[8:11], v[136:139], v[196:199], v[8:11]
	v_mfma_f32_16x16x32_bf16 v[60:63], v[132:135], v[164:167], v[60:63]
	v_mfma_f32_16x16x32_bf16 v[56:59], v[140:143], v[164:167], v[56:59]
	v_mfma_f32_16x16x32_bf16 v[44:47], v[132:135], v[172:175], v[44:47]
	v_mfma_f32_16x16x32_bf16 v[40:43], v[140:143], v[172:175], v[40:43]
	v_mfma_f32_16x16x32_bf16 v[28:31], v[132:135], v[180:183], v[28:31]
	v_mfma_f32_16x16x32_bf16 v[24:27], v[140:143], v[180:183], v[24:27]
	v_mfma_f32_16x16x32_bf16 v[12:15], v[132:135], v[200:203], v[12:15]
	v_mfma_f32_16x16x32_bf16 v[8:11], v[140:143], v[200:203], v[8:11]
	v_mfma_f32_16x16x32_bf16 v[52:55], v[204:207], v[154:157], v[52:55]
	v_mfma_f32_16x16x32_bf16 v[48:51], v[212:215], v[154:157], v[48:51]
	v_mfma_f32_16x16x32_bf16 v[36:39], v[204:207], v[168:171], v[36:39]
	v_mfma_f32_16x16x32_bf16 v[32:35], v[212:215], v[168:171], v[32:35]
	v_mfma_f32_16x16x32_bf16 v[20:23], v[204:207], v[176:179], v[20:23]
	v_mfma_f32_16x16x32_bf16 v[16:19], v[212:215], v[176:179], v[16:19]
	v_mfma_f32_16x16x32_bf16 v[4:7], v[204:207], v[196:199], v[4:7]
	v_mfma_f32_16x16x32_bf16 v[0:3], v[212:215], v[196:199], v[0:3]
	v_mfma_f32_16x16x32_bf16 v[52:55], v[208:211], v[164:167], v[52:55]
	v_mfma_f32_16x16x32_bf16 v[48:51], v[216:219], v[164:167], v[48:51]
	v_mfma_f32_16x16x32_bf16 v[36:39], v[208:211], v[172:175], v[36:39]
	v_mfma_f32_16x16x32_bf16 v[32:35], v[216:219], v[172:175], v[32:35]
	v_mfma_f32_16x16x32_bf16 v[20:23], v[208:211], v[180:183], v[20:23]
	v_mfma_f32_16x16x32_bf16 v[16:19], v[216:219], v[180:183], v[16:19]
	v_mfma_f32_16x16x32_bf16 v[4:7], v[208:211], v[200:203], v[4:7]
	v_mfma_f32_16x16x32_bf16 v[0:3], v[216:219], v[200:203], v[0:3]
	s_barrier
	s_add_u32 s58, s20, 0x80000
	s_addc_u32 s59, s21, 0
	s_add_i32 s4, s4, s27
	s_mov_b32 m0, s4
	s_nop 0
	global_load_lds_dwordx4 v186, s[58:59]
	s_add_i32 m0, s4, 0x2000
	s_nop 0
	global_load_lds_dwordx4 v144, s[58:59]
	s_add_i32 s4, 0, 0x18000
	v_add_u32_e32 v140, s4, v161
	ds_read_b128 v[128:131], v140
	ds_read_b128 v[132:135], v140 offset:1024
	ds_read_b128 v[136:139], v140 offset:2048
	ds_read_b128 v[140:143], v140 offset:3072
	s_add_u32 s24, s24, 0x80000
	s_addc_u32 s25, s25, 0
	s_mov_b32 m0, s30
	ds_read_b128 v[154:157], v163 offset:32768
	ds_read_b128 v[164:167], v163 offset:33792
	ds_read_b128 v[168:171], v163 offset:34816
	ds_read_b128 v[172:175], v163 offset:35840
	ds_read_b128 v[176:179], v163 offset:36864
	ds_read_b128 v[180:183], v163 offset:37888
	ds_read_b128 v[196:199], v163 offset:38912
	ds_read_b128 v[200:203], v163 offset:39936
	v_add_u32_e32 v216, 0x1c000, v161
	ds_read_b128 v[204:207], v216
	ds_read_b128 v[208:211], v216 offset:1024
	ds_read_b128 v[212:215], v216 offset:2048
	ds_read_b128 v[216:219], v216 offset:3072
	global_load_lds_dwordx4 v148, s[24:25]
	s_mov_b32 m0, s31
	s_nop 0
	global_load_lds_dwordx4 v146, s[24:25]
	s_waitcnt vmcnt(8)
	s_waitcnt lgkmcnt(0)
	s_barrier
	v_mfma_f32_16x16x32_bf16 v[124:127], v[128:131], v[154:157], v[124:127]
	v_mfma_f32_16x16x32_bf16 v[120:123], v[136:139], v[154:157], v[120:123]
	v_mfma_f32_16x16x32_bf16 v[108:111], v[128:131], v[168:171], v[108:111]
	v_mfma_f32_16x16x32_bf16 v[104:107], v[136:139], v[168:171], v[104:107]
	v_mfma_f32_16x16x32_bf16 v[92:95], v[128:131], v[176:179], v[92:95]
	v_mfma_f32_16x16x32_bf16 v[88:91], v[136:139], v[176:179], v[88:91]
	v_mfma_f32_16x16x32_bf16 v[76:79], v[128:131], v[196:199], v[76:79]
	v_mfma_f32_16x16x32_bf16 v[72:75], v[136:139], v[196:199], v[72:75]
	v_mfma_f32_16x16x32_bf16 v[124:127], v[132:135], v[164:167], v[124:127]
	v_mfma_f32_16x16x32_bf16 v[120:123], v[140:143], v[164:167], v[120:123]
	v_mfma_f32_16x16x32_bf16 v[108:111], v[132:135], v[172:175], v[108:111]
	v_mfma_f32_16x16x32_bf16 v[104:107], v[140:143], v[172:175], v[104:107]
	v_mfma_f32_16x16x32_bf16 v[92:95], v[132:135], v[180:183], v[92:95]
	v_mfma_f32_16x16x32_bf16 v[88:91], v[140:143], v[180:183], v[88:91]
	v_mfma_f32_16x16x32_bf16 v[76:79], v[132:135], v[200:203], v[76:79]
	v_mfma_f32_16x16x32_bf16 v[72:75], v[140:143], v[200:203], v[72:75]
	v_mfma_f32_16x16x32_bf16 v[116:119], v[204:207], v[154:157], v[116:119]
	v_mfma_f32_16x16x32_bf16 v[112:115], v[212:215], v[154:157], v[112:115]
	v_mfma_f32_16x16x32_bf16 v[100:103], v[204:207], v[168:171], v[100:103]
	v_mfma_f32_16x16x32_bf16 v[96:99], v[212:215], v[168:171], v[96:99]
	v_mfma_f32_16x16x32_bf16 v[84:87], v[204:207], v[176:179], v[84:87]
	v_mfma_f32_16x16x32_bf16 v[80:83], v[212:215], v[176:179], v[80:83]
	v_mfma_f32_16x16x32_bf16 v[68:71], v[204:207], v[196:199], v[68:71]
	v_mfma_f32_16x16x32_bf16 v[64:67], v[212:215], v[196:199], v[64:67]
	v_mfma_f32_16x16x32_bf16 v[116:119], v[208:211], v[164:167], v[116:119]
	v_mfma_f32_16x16x32_bf16 v[112:115], v[216:219], v[164:167], v[112:115]
	v_mfma_f32_16x16x32_bf16 v[100:103], v[208:211], v[172:175], v[100:103]
	v_mfma_f32_16x16x32_bf16 v[96:99], v[216:219], v[172:175], v[96:99]
	v_mfma_f32_16x16x32_bf16 v[84:87], v[208:211], v[180:183], v[84:87]
	v_mfma_f32_16x16x32_bf16 v[80:83], v[216:219], v[180:183], v[80:83]
	v_mfma_f32_16x16x32_bf16 v[68:71], v[208:211], v[200:203], v[68:71]
	v_mfma_f32_16x16x32_bf16 v[64:67], v[216:219], v[200:203], v[64:67]
	s_barrier
	s_add_i32 s24, 0, 0x1c000
	s_add_i32 s4, s4, s27
	v_lshl_add_u64 v[158:159], v[158:159], 0, s[0:1]
	s_mov_b32 m0, s4
	global_load_lds_dwordx4 v[158:159], off
	v_lshl_add_u64 v[158:159], v[220:221], 0, s[0:1]
	s_add_i32 m0, s4, 0x2000
	s_nop 0
	global_load_lds_dwordx4 v[158:159], off
	s_mov_b32 m0, s38
	v_lshl_add_u64 v[158:159], v[222:223], 0, s[0:1]
	ds_read_b128 v[154:157], v163 offset:49152
	ds_read_b128 v[164:167], v163 offset:50176
	ds_read_b128 v[168:171], v163 offset:51200
	ds_read_b128 v[172:175], v163 offset:52224
	ds_read_b128 v[176:179], v163 offset:53248
	ds_read_b128 v[180:183], v163 offset:54272
	ds_read_b128 v[196:199], v163 offset:55296
	ds_read_b128 v[200:203], v163 offset:56320
	global_load_lds_dwordx4 v[158:159], off
	v_lshl_add_u64 v[158:159], v[224:225], 0, s[0:1]
	s_mov_b32 m0, s39
	s_nop 0
	global_load_lds_dwordx4 v[158:159], off
	s_add_u32 s20, s20, 0x80080
	s_addc_u32 s21, s21, 0
	s_add_i32 s4, s24, s27
	s_mov_b32 m0, s4
	s_nop 0
	global_load_lds_dwordx4 v186, s[20:21]
	s_add_i32 m0, s4, 0x2000
	s_nop 0
	global_load_lds_dwordx4 v144, s[20:21]
	s_waitcnt vmcnt(8)
	s_waitcnt lgkmcnt(0)
	s_barrier
	v_mfma_f32_16x16x32_bf16 v[60:63], v[128:131], v[154:157], v[60:63]
	v_mfma_f32_16x16x32_bf16 v[56:59], v[136:139], v[154:157], v[56:59]
	v_mfma_f32_16x16x32_bf16 v[44:47], v[128:131], v[168:171], v[44:47]
	v_mfma_f32_16x16x32_bf16 v[40:43], v[136:139], v[168:171], v[40:43]
	v_mfma_f32_16x16x32_bf16 v[28:31], v[128:131], v[176:179], v[28:31]
	v_mfma_f32_16x16x32_bf16 v[24:27], v[136:139], v[176:179], v[24:27]
	v_mfma_f32_16x16x32_bf16 v[12:15], v[128:131], v[196:199], v[12:15]
	v_mfma_f32_16x16x32_bf16 v[8:11], v[136:139], v[196:199], v[8:11]
	v_mfma_f32_16x16x32_bf16 v[60:63], v[132:135], v[164:167], v[60:63]
	v_mfma_f32_16x16x32_bf16 v[56:59], v[140:143], v[164:167], v[56:59]
	v_mfma_f32_16x16x32_bf16 v[44:47], v[132:135], v[172:175], v[44:47]
	v_mfma_f32_16x16x32_bf16 v[40:43], v[140:143], v[172:175], v[40:43]
	v_mfma_f32_16x16x32_bf16 v[28:31], v[132:135], v[180:183], v[28:31]
	v_mfma_f32_16x16x32_bf16 v[24:27], v[140:143], v[180:183], v[24:27]
	v_mfma_f32_16x16x32_bf16 v[12:15], v[132:135], v[200:203], v[12:15]
	v_mfma_f32_16x16x32_bf16 v[8:11], v[140:143], v[200:203], v[8:11]
	v_mfma_f32_16x16x32_bf16 v[52:55], v[204:207], v[154:157], v[52:55]
	v_mfma_f32_16x16x32_bf16 v[48:51], v[212:215], v[154:157], v[48:51]
	v_mfma_f32_16x16x32_bf16 v[36:39], v[204:207], v[168:171], v[36:39]
	v_mfma_f32_16x16x32_bf16 v[32:35], v[212:215], v[168:171], v[32:35]
	v_mfma_f32_16x16x32_bf16 v[20:23], v[204:207], v[176:179], v[20:23]
	v_mfma_f32_16x16x32_bf16 v[16:19], v[212:215], v[176:179], v[16:19]
	v_mfma_f32_16x16x32_bf16 v[4:7], v[204:207], v[196:199], v[4:7]
	v_mfma_f32_16x16x32_bf16 v[0:3], v[212:215], v[196:199], v[0:3]
	v_mfma_f32_16x16x32_bf16 v[52:55], v[208:211], v[164:167], v[52:55]
	v_mfma_f32_16x16x32_bf16 v[48:51], v[216:219], v[164:167], v[48:51]
	v_mfma_f32_16x16x32_bf16 v[36:39], v[208:211], v[172:175], v[36:39]
	v_mfma_f32_16x16x32_bf16 v[32:35], v[216:219], v[172:175], v[32:35]
	v_mfma_f32_16x16x32_bf16 v[20:23], v[208:211], v[180:183], v[20:23]
	v_mfma_f32_16x16x32_bf16 v[16:19], v[216:219], v[180:183], v[16:19]
	v_mfma_f32_16x16x32_bf16 v[4:7], v[208:211], v[200:203], v[4:7]
	v_mfma_f32_16x16x32_bf16 v[0:3], v[216:219], v[200:203], v[0:3]
	s_add_i32 s57, s57, 2
	s_add_u32 s12, s12, 0x100
	s_addc_u32 s13, s13, 0
	s_add_u32 s53, s53, 0x100
	s_addc_u32 s56, s56, 0
	s_cmp_gt_u32 s57, 29
	s_barrier
	s_cbranch_scc1 .Lgemm_epi_2
.LBB0_803:
	s_add_u32 s4, s12, 0xfff80080
	s_addc_u32 s20, s13, -1
	s_add_i32 s58, 0, 0x10000
	v_add_u32_e32 v140, s58, v161
	ds_read_b128 v[128:131], v140
	ds_read_b128 v[132:135], v140 offset:1024
	ds_read_b128 v[136:139], v140 offset:2048
	ds_read_b128 v[140:143], v140 offset:3072
	s_cmp_eq_u32 s57, 28
	s_cselect_b32 s25, s15, s20
	s_cselect_b32 s24, s45, s4
	s_cselect_b32 s21, s3, s56
	s_cselect_b32 s20, s52, s53
	v_lshl_add_u64 v[158:159], s[12:13], 0, v[150:151]
	s_add_i32 m0, s16, 0xc000
	ds_read_b128 v[154:157], v163
	ds_read_b128 v[164:167], v163 offset:1024
	ds_read_b128 v[168:171], v163 offset:2048
	ds_read_b128 v[172:175], v163 offset:3072
	ds_read_b128 v[176:179], v163 offset:4096
	ds_read_b128 v[180:183], v163 offset:5120
	ds_read_b128 v[196:199], v163 offset:6144
	ds_read_b128 v[200:203], v163 offset:7168
	v_add_u32_e32 v216, 0x14000, v161
	ds_read_b128 v[204:207], v216
	ds_read_b128 v[208:211], v216 offset:1024
	ds_read_b128 v[212:215], v216 offset:2048
	ds_read_b128 v[216:219], v216 offset:3072
	global_load_lds_dwordx4 v150, s[12:13]
	v_lshl_add_u64 v[158:159], s[12:13], 0, v[152:153]
	s_add_i32 m0, s16, 0xe000
	s_nop 0
	global_load_lds_dwordx4 v152, s[12:13]
	s_waitcnt vmcnt(8)
	s_waitcnt lgkmcnt(0)
	s_barrier
	v_mfma_f32_16x16x32_bf16 v[124:127], v[128:131], v[154:157], v[124:127]
	v_mfma_f32_16x16x32_bf16 v[120:123], v[136:139], v[154:157], v[120:123]
	v_mfma_f32_16x16x32_bf16 v[108:111], v[128:131], v[168:171], v[108:111]
	v_mfma_f32_16x16x32_bf16 v[104:107], v[136:139], v[168:171], v[104:107]
	v_mfma_f32_16x16x32_bf16 v[92:95], v[128:131], v[176:179], v[92:95]
	v_mfma_f32_16x16x32_bf16 v[88:91], v[136:139], v[176:179], v[88:91]
	v_mfma_f32_16x16x32_bf16 v[76:79], v[128:131], v[196:199], v[76:79]
	v_mfma_f32_16x16x32_bf16 v[72:75], v[136:139], v[196:199], v[72:75]
	v_mfma_f32_16x16x32_bf16 v[124:127], v[132:135], v[164:167], v[124:127]
	v_mfma_f32_16x16x32_bf16 v[120:123], v[140:143], v[164:167], v[120:123]
	v_mfma_f32_16x16x32_bf16 v[108:111], v[132:135], v[172:175], v[108:111]
	v_mfma_f32_16x16x32_bf16 v[104:107], v[140:143], v[172:175], v[104:107]
	v_mfma_f32_16x16x32_bf16 v[92:95], v[132:135], v[180:183], v[92:95]
	v_mfma_f32_16x16x32_bf16 v[88:91], v[140:143], v[180:183], v[88:91]
	v_mfma_f32_16x16x32_bf16 v[76:79], v[132:135], v[200:203], v[76:79]
	v_mfma_f32_16x16x32_bf16 v[72:75], v[140:143], v[200:203], v[72:75]
	v_mfma_f32_16x16x32_bf16 v[116:119], v[204:207], v[154:157], v[116:119]
	v_mfma_f32_16x16x32_bf16 v[112:115], v[212:215], v[154:157], v[112:115]
	v_mfma_f32_16x16x32_bf16 v[100:103], v[204:207], v[168:171], v[100:103]
	v_mfma_f32_16x16x32_bf16 v[96:99], v[212:215], v[168:171], v[96:99]
	v_mfma_f32_16x16x32_bf16 v[84:87], v[204:207], v[176:179], v[84:87]
	v_mfma_f32_16x16x32_bf16 v[80:83], v[212:215], v[176:179], v[80:83]
	v_mfma_f32_16x16x32_bf16 v[68:71], v[204:207], v[196:199], v[68:71]
	v_mfma_f32_16x16x32_bf16 v[64:67], v[212:215], v[196:199], v[64:67]
	v_mfma_f32_16x16x32_bf16 v[116:119], v[208:211], v[164:167], v[116:119]
	v_mfma_f32_16x16x32_bf16 v[112:115], v[216:219], v[164:167], v[112:115]
	v_mfma_f32_16x16x32_bf16 v[100:103], v[208:211], v[172:175], v[100:103]
	v_mfma_f32_16x16x32_bf16 v[96:99], v[216:219], v[172:175], v[96:99]
	v_mfma_f32_16x16x32_bf16 v[84:87], v[208:211], v[180:183], v[84:87]
	v_mfma_f32_16x16x32_bf16 v[80:83], v[216:219], v[180:183], v[80:83]
	v_mfma_f32_16x16x32_bf16 v[68:71], v[208:211], v[200:203], v[68:71]
	v_mfma_f32_16x16x32_bf16 v[64:67], v[216:219], v[200:203], v[64:67]
	s_barrier
	s_add_i32 s4, 0, 0x14000
	s_add_i32 s58, s58, s27
	v_lshl_add_u64 v[158:159], s[20:21], 0, v[186:187]
	s_mov_b32 m0, s58
	v_lshl_add_u64 v[220:221], s[20:21], 0, v[144:145]
	global_load_lds_dwordx4 v186, s[20:21]
	s_add_i32 m0, s58, 0x2000
	s_nop 0
	global_load_lds_dwordx4 v144, s[20:21]
	s_mov_b32 m0, s16
	v_lshl_add_u64 v[222:223], s[24:25], 0, v[148:149]
	ds_read_b128 v[154:157], v163 offset:16384
	ds_read_b128 v[164:167], v163 offset:17408
	ds_read_b128 v[168:171], v163 offset:18432
	ds_read_b128 v[172:175], v163 offset:19456
	ds_read_b128 v[176:179], v163 offset:20480
	ds_read_b128 v[180:183], v163 offset:21504
	ds_read_b128 v[196:199], v163 offset:22528
	ds_read_b128 v[200:203], v163 offset:23552
	global_load_lds_dwordx4 v148, s[24:25]
	v_lshl_add_u64 v[224:225], s[24:25], 0, v[146:147]
	s_mov_b32 m0, s17
	s_nop 0
	global_load_lds_dwordx4 v146, s[24:25]
	s_waitcnt vmcnt(6)
	s_waitcnt lgkmcnt(0)
	s_barrier
	v_mfma_f32_16x16x32_bf16 v[60:63], v[128:131], v[154:157], v[60:63]
	v_mfma_f32_16x16x32_bf16 v[56:59], v[136:139], v[154:157], v[56:59]
	v_mfma_f32_16x16x32_bf16 v[44:47], v[128:131], v[168:171], v[44:47]
	v_mfma_f32_16x16x32_bf16 v[40:43], v[136:139], v[168:171], v[40:43]
	v_mfma_f32_16x16x32_bf16 v[28:31], v[128:131], v[176:179], v[28:31]
	v_mfma_f32_16x16x32_bf16 v[24:27], v[136:139], v[176:179], v[24:27]
	v_mfma_f32_16x16x32_bf16 v[12:15], v[128:131], v[196:199], v[12:15]
	v_mfma_f32_16x16x32_bf16 v[8:11], v[136:139], v[196:199], v[8:11]
	v_mfma_f32_16x16x32_bf16 v[60:63], v[132:135], v[164:167], v[60:63]
	v_mfma_f32_16x16x32_bf16 v[56:59], v[140:143], v[164:167], v[56:59]
	v_mfma_f32_16x16x32_bf16 v[44:47], v[132:135], v[172:175], v[44:47]
	v_mfma_f32_16x16x32_bf16 v[40:43], v[140:143], v[172:175], v[40:43]
	v_mfma_f32_16x16x32_bf16 v[28:31], v[132:135], v[180:183], v[28:31]
	v_mfma_f32_16x16x32_bf16 v[24:27], v[140:143], v[180:183], v[24:27]
	v_mfma_f32_16x16x32_bf16 v[12:15], v[132:135], v[200:203], v[12:15]
	v_mfma_f32_16x16x32_bf16 v[8:11], v[140:143], v[200:203], v[8:11]
	v_mfma_f32_16x16x32_bf16 v[52:55], v[204:207], v[154:157], v[52:55]
	v_mfma_f32_16x16x32_bf16 v[48:51], v[212:215], v[154:157], v[48:51]
	v_mfma_f32_16x16x32_bf16 v[36:39], v[204:207], v[168:171], v[36:39]
	v_mfma_f32_16x16x32_bf16 v[32:35], v[212:215], v[168:171], v[32:35]
	v_mfma_f32_16x16x32_bf16 v[20:23], v[204:207], v[176:179], v[20:23]
	v_mfma_f32_16x16x32_bf16 v[16:19], v[212:215], v[176:179], v[16:19]
	v_mfma_f32_16x16x32_bf16 v[4:7], v[204:207], v[196:199], v[4:7]
	v_mfma_f32_16x16x32_bf16 v[0:3], v[212:215], v[196:199], v[0:3]
	v_mfma_f32_16x16x32_bf16 v[52:55], v[208:211], v[164:167], v[52:55]
	v_mfma_f32_16x16x32_bf16 v[48:51], v[216:219], v[164:167], v[48:51]
	v_mfma_f32_16x16x32_bf16 v[36:39], v[208:211], v[172:175], v[36:39]
	v_mfma_f32_16x16x32_bf16 v[32:35], v[216:219], v[172:175], v[32:35]
	v_mfma_f32_16x16x32_bf16 v[20:23], v[208:211], v[180:183], v[20:23]
	v_mfma_f32_16x16x32_bf16 v[16:19], v[216:219], v[180:183], v[16:19]
	v_mfma_f32_16x16x32_bf16 v[4:7], v[208:211], v[200:203], v[4:7]
	v_mfma_f32_16x16x32_bf16 v[0:3], v[216:219], v[200:203], v[0:3]
	s_barrier
	s_add_u32 s58, s20, 0x80000
	s_addc_u32 s59, s21, 0
	s_add_i32 s4, s4, s27
	s_mov_b32 m0, s4
	s_nop 0
	global_load_lds_dwordx4 v186, s[58:59]
	s_add_i32 m0, s4, 0x2000
	s_nop 0
	global_load_lds_dwordx4 v144, s[58:59]
	s_add_i32 s4, 0, 0x18000
	v_add_u32_e32 v140, s4, v161
	ds_read_b128 v[128:131], v140
	ds_read_b128 v[132:135], v140 offset:1024
	ds_read_b128 v[136:139], v140 offset:2048
	ds_read_b128 v[140:143], v140 offset:3072
	s_add_u32 s24, s24, 0x80000
	s_addc_u32 s25, s25, 0
	s_mov_b32 m0, s30
	ds_read_b128 v[154:157], v163 offset:32768
	ds_read_b128 v[164:167], v163 offset:33792
	ds_read_b128 v[168:171], v163 offset:34816
	ds_read_b128 v[172:175], v163 offset:35840
	ds_read_b128 v[176:179], v163 offset:36864
	ds_read_b128 v[180:183], v163 offset:37888
	ds_read_b128 v[196:199], v163 offset:38912
	ds_read_b128 v[200:203], v163 offset:39936
	v_add_u32_e32 v216, 0x1c000, v161
	ds_read_b128 v[204:207], v216
	ds_read_b128 v[208:211], v216 offset:1024
	ds_read_b128 v[212:215], v216 offset:2048
	ds_read_b128 v[216:219], v216 offset:3072
	global_load_lds_dwordx4 v148, s[24:25]
	s_mov_b32 m0, s31
	s_nop 0
	global_load_lds_dwordx4 v146, s[24:25]
	s_waitcnt vmcnt(8)
	s_waitcnt lgkmcnt(0)
	s_barrier
	v_mfma_f32_16x16x32_bf16 v[124:127], v[128:131], v[154:157], v[124:127]
	v_mfma_f32_16x16x32_bf16 v[120:123], v[136:139], v[154:157], v[120:123]
	v_mfma_f32_16x16x32_bf16 v[108:111], v[128:131], v[168:171], v[108:111]
	v_mfma_f32_16x16x32_bf16 v[104:107], v[136:139], v[168:171], v[104:107]
	v_mfma_f32_16x16x32_bf16 v[92:95], v[128:131], v[176:179], v[92:95]
	v_mfma_f32_16x16x32_bf16 v[88:91], v[136:139], v[176:179], v[88:91]
	v_mfma_f32_16x16x32_bf16 v[76:79], v[128:131], v[196:199], v[76:79]
	v_mfma_f32_16x16x32_bf16 v[72:75], v[136:139], v[196:199], v[72:75]
	v_mfma_f32_16x16x32_bf16 v[124:127], v[132:135], v[164:167], v[124:127]
	v_mfma_f32_16x16x32_bf16 v[120:123], v[140:143], v[164:167], v[120:123]
	v_mfma_f32_16x16x32_bf16 v[108:111], v[132:135], v[172:175], v[108:111]
	v_mfma_f32_16x16x32_bf16 v[104:107], v[140:143], v[172:175], v[104:107]
	v_mfma_f32_16x16x32_bf16 v[92:95], v[132:135], v[180:183], v[92:95]
	v_mfma_f32_16x16x32_bf16 v[88:91], v[140:143], v[180:183], v[88:91]
	v_mfma_f32_16x16x32_bf16 v[76:79], v[132:135], v[200:203], v[76:79]
	v_mfma_f32_16x16x32_bf16 v[72:75], v[140:143], v[200:203], v[72:75]
	v_mfma_f32_16x16x32_bf16 v[116:119], v[204:207], v[154:157], v[116:119]
	v_mfma_f32_16x16x32_bf16 v[112:115], v[212:215], v[154:157], v[112:115]
	v_mfma_f32_16x16x32_bf16 v[100:103], v[204:207], v[168:171], v[100:103]
	v_mfma_f32_16x16x32_bf16 v[96:99], v[212:215], v[168:171], v[96:99]
	v_mfma_f32_16x16x32_bf16 v[84:87], v[204:207], v[176:179], v[84:87]
	v_mfma_f32_16x16x32_bf16 v[80:83], v[212:215], v[176:179], v[80:83]
	v_mfma_f32_16x16x32_bf16 v[68:71], v[204:207], v[196:199], v[68:71]
	v_mfma_f32_16x16x32_bf16 v[64:67], v[212:215], v[196:199], v[64:67]
	v_mfma_f32_16x16x32_bf16 v[116:119], v[208:211], v[164:167], v[116:119]
	v_mfma_f32_16x16x32_bf16 v[112:115], v[216:219], v[164:167], v[112:115]
	v_mfma_f32_16x16x32_bf16 v[100:103], v[208:211], v[172:175], v[100:103]
	v_mfma_f32_16x16x32_bf16 v[96:99], v[216:219], v[172:175], v[96:99]
	v_mfma_f32_16x16x32_bf16 v[84:87], v[208:211], v[180:183], v[84:87]
	v_mfma_f32_16x16x32_bf16 v[80:83], v[216:219], v[180:183], v[80:83]
	v_mfma_f32_16x16x32_bf16 v[68:71], v[208:211], v[200:203], v[68:71]
	v_mfma_f32_16x16x32_bf16 v[64:67], v[216:219], v[200:203], v[64:67]
	s_barrier
	s_add_i32 s24, 0, 0x1c000
	s_add_i32 s4, s4, s27
	v_lshl_add_u64 v[158:159], v[158:159], 0, s[0:1]
	s_mov_b32 m0, s4
	global_load_lds_dwordx4 v[158:159], off
	v_lshl_add_u64 v[158:159], v[220:221], 0, s[0:1]
	s_add_i32 m0, s4, 0x2000
	s_nop 0
	global_load_lds_dwordx4 v[158:159], off
	s_mov_b32 m0, s38
	v_lshl_add_u64 v[158:159], v[222:223], 0, s[0:1]
	ds_read_b128 v[154:157], v163 offset:49152
	ds_read_b128 v[164:167], v163 offset:50176
	ds_read_b128 v[168:171], v163 offset:51200
	ds_read_b128 v[172:175], v163 offset:52224
	ds_read_b128 v[176:179], v163 offset:53248
	ds_read_b128 v[180:183], v163 offset:54272
	ds_read_b128 v[196:199], v163 offset:55296
	ds_read_b128 v[200:203], v163 offset:56320
	global_load_lds_dwordx4 v[158:159], off
	v_lshl_add_u64 v[158:159], v[224:225], 0, s[0:1]
	s_mov_b32 m0, s39
	s_nop 0
	global_load_lds_dwordx4 v[158:159], off
	s_add_u32 s20, s20, 0x80080
	s_addc_u32 s21, s21, 0
	s_add_i32 s4, s24, s27
	s_mov_b32 m0, s4
	s_nop 0
	global_load_lds_dwordx4 v186, s[20:21]
	s_add_i32 m0, s4, 0x2000
	s_nop 0
	global_load_lds_dwordx4 v144, s[20:21]
	s_waitcnt vmcnt(8)
	s_waitcnt lgkmcnt(0)
	s_barrier
	v_mfma_f32_16x16x32_bf16 v[60:63], v[128:131], v[154:157], v[60:63]
	v_mfma_f32_16x16x32_bf16 v[56:59], v[136:139], v[154:157], v[56:59]
	v_mfma_f32_16x16x32_bf16 v[44:47], v[128:131], v[168:171], v[44:47]
	v_mfma_f32_16x16x32_bf16 v[40:43], v[136:139], v[168:171], v[40:43]
	v_mfma_f32_16x16x32_bf16 v[28:31], v[128:131], v[176:179], v[28:31]
	v_mfma_f32_16x16x32_bf16 v[24:27], v[136:139], v[176:179], v[24:27]
	v_mfma_f32_16x16x32_bf16 v[12:15], v[128:131], v[196:199], v[12:15]
	v_mfma_f32_16x16x32_bf16 v[8:11], v[136:139], v[196:199], v[8:11]
	v_mfma_f32_16x16x32_bf16 v[60:63], v[132:135], v[164:167], v[60:63]
	v_mfma_f32_16x16x32_bf16 v[56:59], v[140:143], v[164:167], v[56:59]
	v_mfma_f32_16x16x32_bf16 v[44:47], v[132:135], v[172:175], v[44:47]
	v_mfma_f32_16x16x32_bf16 v[40:43], v[140:143], v[172:175], v[40:43]
	v_mfma_f32_16x16x32_bf16 v[28:31], v[132:135], v[180:183], v[28:31]
	v_mfma_f32_16x16x32_bf16 v[24:27], v[140:143], v[180:183], v[24:27]
	v_mfma_f32_16x16x32_bf16 v[12:15], v[132:135], v[200:203], v[12:15]
	v_mfma_f32_16x16x32_bf16 v[8:11], v[140:143], v[200:203], v[8:11]
	v_mfma_f32_16x16x32_bf16 v[52:55], v[204:207], v[154:157], v[52:55]
	v_mfma_f32_16x16x32_bf16 v[48:51], v[212:215], v[154:157], v[48:51]
	v_mfma_f32_16x16x32_bf16 v[36:39], v[204:207], v[168:171], v[36:39]
	v_mfma_f32_16x16x32_bf16 v[32:35], v[212:215], v[168:171], v[32:35]
	v_mfma_f32_16x16x32_bf16 v[20:23], v[204:207], v[176:179], v[20:23]
	v_mfma_f32_16x16x32_bf16 v[16:19], v[212:215], v[176:179], v[16:19]
	v_mfma_f32_16x16x32_bf16 v[4:7], v[204:207], v[196:199], v[4:7]
	v_mfma_f32_16x16x32_bf16 v[0:3], v[212:215], v[196:199], v[0:3]
	v_mfma_f32_16x16x32_bf16 v[52:55], v[208:211], v[164:167], v[52:55]
	v_mfma_f32_16x16x32_bf16 v[48:51], v[216:219], v[164:167], v[48:51]
	v_mfma_f32_16x16x32_bf16 v[36:39], v[208:211], v[172:175], v[36:39]
	v_mfma_f32_16x16x32_bf16 v[32:35], v[216:219], v[172:175], v[32:35]
	v_mfma_f32_16x16x32_bf16 v[20:23], v[208:211], v[180:183], v[20:23]
	v_mfma_f32_16x16x32_bf16 v[16:19], v[216:219], v[180:183], v[16:19]
	v_mfma_f32_16x16x32_bf16 v[4:7], v[208:211], v[200:203], v[4:7]
	v_mfma_f32_16x16x32_bf16 v[0:3], v[216:219], v[200:203], v[0:3]
	s_add_i32 s57, s57, 2
	s_add_u32 s12, s12, 0x100
	s_addc_u32 s13, s13, 0
	s_add_u32 s53, s53, 0x100
	s_addc_u32 s56, s56, 0
	s_cmp_gt_u32 s57, 29
	s_barrier
	s_cbranch_scc0 .LBB0_803

.LBB0_807:
	s_setprio 0
	v_readlane_b32 s30, v252, 35
	v_readlane_b32 s31, v252, 36
	s_barrier

.LBB0_875:
	v_readlane_b32 s12, v253, 6
	v_readlane_b32 s13, v253, 7
	v_readlane_b32 s14, v253, 8
	v_readlane_b32 s15, v253, 9
	s_cmp_le_i32 s12, s16
	s_cselect_b64 s[14:15], -1, 0
	s_cmp_lt_i32 s16, s13
	s_cselect_b64 s[40:41], -1, 0
	s_and_b64 s[2:3], s[14:15], s[40:41]
	s_andn2_b64 vcc, exec, s[2:3]
	s_cbranch_vccnz .LBB0_1019
	v_readlane_b32 s12, v253, 63
	v_readlane_b32 s13, v252, 0
	s_lshl_b32 s35, s47, 13
	s_mov_b64 s[2:3], -1
	v_cndmask_b32_e64 v0, 0, 1, s[12:13]
	s_and_b64 vcc, exec, s[30:31]
	v_cmp_ne_u32_e64 s[42:43], 1, v0
	s_cbranch_vccz .LBB0_926
	v_mov_b32_e32 v6, v184
	s_and_b64 vcc, exec, s[42:43]
	v_readfirstlane_b32 s26, v6
	s_cbranch_vccnz .LBB0_925
	v_lshlrev_b32_e32 v4, 4, v6
	v_add_u32_e32 v1, 0x2000, v4
	v_ashrrev_i32_e32 v0, 31, v1
	v_lshrrev_b32_e32 v0, 22, v0
	v_add_u32_e32 v0, v1, v0
	v_ashrrev_i32_e32 v0, 10, v0
	v_lshlrev_b32_e32 v2, 5, v0
	s_waitcnt lgkmcnt(0)
	v_and_b32_e32 v3, 32, v2
	v_mul_i32_i24_e32 v2, 0x400, v0
	v_sub_u32_e32 v1, v1, v2
	v_lshrrev_b32_e32 v2, 4, v1
	v_bitop3_b32 v2, v2, v1, 32 bitop3:0x6c
	v_ashrrev_i32_e32 v1, 31, v2
	v_lshrrev_b32_e32 v1, 26, v1
	v_add_u32_e32 v5, v2, v1
	v_ashrrev_i32_e32 v1, 6, v5
	v_and_b32_e32 v5, 0xc0, v5
	v_sub_u32_e32 v2, v2, v5
	v_ashrrev_i16_sdwa v2, v230, sext(v2) dst_sel:DWORD dst_unused:UNUSED_PAD src0_sel:DWORD src1_sel:BYTE_0
	v_lshlrev_b32_e32 v5, 3, v0
	v_bfe_i32 v2, v2, 0, 16
	v_and_b32_e32 v5, 0x3fff0, v5
	v_add_u32_e32 v3, v3, v2
	v_add_lshl_u32 v5, v1, v5, 14
	v_lshl_add_u32 v144, v3, 1, v5
	v_ashrrev_i32_e32 v3, 31, v6
	v_lshrrev_b32_e32 v3, 26, v3
	v_add_u32_e32 v3, v6, v3
	v_ashrrev_i32_e32 v3, 6, v3
	v_lshlrev_b32_e32 v5, 5, v3
	v_and_b32_e32 v7, 32, v5
	v_bfe_i32 v5, v6, 27, 1
	v_lshrrev_b32_e32 v5, 22, v5
	v_add_u32_e32 v5, v4, v5
	v_and_b32_e32 v5, 0xfffffc00, v5
	v_sub_u32_e32 v4, v4, v5
	v_lshrrev_b32_e32 v5, 4, v4
	v_bitop3_b32 v5, v5, v4, 32 bitop3:0x6c
	v_ashrrev_i32_e32 v4, 31, v5
	v_lshrrev_b32_e32 v4, 26, v4
	v_add_u32_e32 v8, v5, v4
	v_ashrrev_i32_e32 v4, 6, v8
	v_and_b32_e32 v8, 0xc0, v8
	v_sub_u32_e32 v5, v5, v8
	s_ashr_i32 s2, s26, 6
	v_ashrrev_i16_sdwa v5, v230, sext(v5) dst_sel:DWORD dst_unused:UNUSED_PAD src0_sel:DWORD src1_sel:BYTE_0
	v_lshlrev_b32_e32 v8, 3, v3
	s_lshl_b32 s27, s2, 10
	v_bfe_i32 v5, v5, 0, 16
	v_and_b32_e32 v8, 0x3fff0, v8
	v_add_u32_e32 v7, v7, v5
	v_add_lshl_u32 v8, v4, v8, 14
	s_add_i32 s22, s27, 0
	v_readlane_b32 s12, v252, 29
	v_lshl_add_u32 v146, v7, 1, v8
	s_add_i32 m0, s22, 0x10000
	v_readlane_b32 s13, v252, 30
	s_add_i32 s23, s22, 0x2000
	s_add_i32 s30, s22, 0x4000
	s_add_i32 s31, s22, 0x6000
	s_ashr_i32 s3, s26, 8
	s_nop 0
	global_load_lds_dwordx4 v146, s[12:13]
	s_add_i32 m0, s22, 0x12000
	s_nop 0
	global_load_lds_dwordx4 v144, s[12:13]
	v_readlane_b32 s12, v252, 25
	s_mov_b32 m0, s22
	v_readlane_b32 s13, v252, 26
	s_nop 4
	global_load_lds_dwordx4 v146, s[12:13]
	s_mov_b32 m0, s23
	s_nop 0
	global_load_lds_dwordx4 v144, s[12:13]
	v_readlane_b32 s12, v252, 23
	s_add_i32 m0, s22, 0x14000
	v_readlane_b32 s13, v252, 24
	s_nop 4
	global_load_lds_dwordx4 v146, s[12:13]
	s_add_i32 m0, s22, 0x16000
	s_cmp_lg_u32 s3, 1
	global_load_lds_dwordx4 v144, s[12:13]
	v_readlane_b32 s12, v252, 27
	s_mov_b32 m0, s30
	v_readlane_b32 s13, v252, 28
	s_nop 4
	global_load_lds_dwordx4 v146, s[12:13]
	s_mov_b32 m0, s31
	s_nop 0
	global_load_lds_dwordx4 v144, s[12:13]
	s_cbranch_scc1 .LBB0_880
	s_setprio 1
	s_barrier

.LBB0_889:
	s_add_u32 s4, s12, 0xffe00080
	s_addc_u32 s20, s13, -1
	s_add_i32 s58, 0, 0x10000
	v_add_u32_e32 v124, s58, v161
	ds_read_b128 v[104:107], v124
	ds_read_b128 v[108:111], v124 offset:1024
	ds_read_b128 v[116:119], v124 offset:2048
	ds_read_b128 v[124:127], v124 offset:3072
	s_cmpk_eq_i32 vcc_hi, 0x7c
	s_cselect_b32 s25, s29, s20
	s_cselect_b32 s24, s57, s4
	s_cselect_b32 s21, s19, vcc_lo
	s_cselect_b32 s20, s68, s69
	s_add_i32 m0, s22, 0xc000
	ds_read_b128 v[152:155], v163
	ds_read_b128 v[156:159], v163 offset:1024
	ds_read_b128 v[164:167], v163 offset:2048
	ds_read_b128 v[168:171], v163 offset:3072
	ds_read_b128 v[172:175], v163 offset:4096
	ds_read_b128 v[176:179], v163 offset:5120
	ds_read_b128 v[180:183], v163 offset:6144
	ds_read_b128 v[196:199], v163 offset:7168
	v_add_u32_e32 v212, 0x14000, v161
	ds_read_b128 v[200:203], v212
	ds_read_b128 v[204:207], v212 offset:1024
	ds_read_b128 v[208:211], v212 offset:2048
	ds_read_b128 v[212:215], v212 offset:3072
	global_load_lds_dwordx4 v148, s[12:13]
	s_add_i32 m0, s22, 0xe000
	s_nop 0
	global_load_lds_dwordx4 v150, s[12:13]
	s_waitcnt vmcnt(8)
	s_waitcnt lgkmcnt(0)
	s_barrier
	v_mfma_f32_16x16x32_bf16 v[140:143], v[104:107], v[152:155], v[140:143]
	v_mfma_f32_16x16x32_bf16 v[136:139], v[116:119], v[152:155], v[136:139]
	v_mfma_f32_16x16x32_bf16 v[120:123], v[104:107], v[164:167], v[120:123]
	v_mfma_f32_16x16x32_bf16 v[112:115], v[116:119], v[164:167], v[112:115]
	v_mfma_f32_16x16x32_bf16 v[92:95], v[104:107], v[172:175], v[92:95]
	v_mfma_f32_16x16x32_bf16 v[88:91], v[116:119], v[172:175], v[88:91]
	v_mfma_f32_16x16x32_bf16 v[76:79], v[104:107], v[180:183], v[76:79]
	v_mfma_f32_16x16x32_bf16 v[72:75], v[116:119], v[180:183], v[72:75]
	v_mfma_f32_16x16x32_bf16 v[140:143], v[108:111], v[156:159], v[140:143]
	v_mfma_f32_16x16x32_bf16 v[136:139], v[124:127], v[156:159], v[136:139]
	v_mfma_f32_16x16x32_bf16 v[120:123], v[108:111], v[168:171], v[120:123]
	v_mfma_f32_16x16x32_bf16 v[112:115], v[124:127], v[168:171], v[112:115]
	v_mfma_f32_16x16x32_bf16 v[92:95], v[108:111], v[176:179], v[92:95]
	v_mfma_f32_16x16x32_bf16 v[88:91], v[124:127], v[176:179], v[88:91]
	v_mfma_f32_16x16x32_bf16 v[76:79], v[108:111], v[196:199], v[76:79]
	v_mfma_f32_16x16x32_bf16 v[72:75], v[124:127], v[196:199], v[72:75]
	v_mfma_f32_16x16x32_bf16 v[132:135], v[200:203], v[152:155], v[132:135]
	v_mfma_f32_16x16x32_bf16 v[128:131], v[208:211], v[152:155], v[128:131]
	v_mfma_f32_16x16x32_bf16 v[100:103], v[200:203], v[164:167], v[100:103]
	v_mfma_f32_16x16x32_bf16 v[96:99], v[208:211], v[164:167], v[96:99]
	v_mfma_f32_16x16x32_bf16 v[84:87], v[200:203], v[172:175], v[84:87]
	v_mfma_f32_16x16x32_bf16 v[80:83], v[208:211], v[172:175], v[80:83]
	v_mfma_f32_16x16x32_bf16 v[68:71], v[200:203], v[180:183], v[68:71]
	v_mfma_f32_16x16x32_bf16 v[64:67], v[208:211], v[180:183], v[64:67]
	v_mfma_f32_16x16x32_bf16 v[132:135], v[204:207], v[156:159], v[132:135]
	v_mfma_f32_16x16x32_bf16 v[128:131], v[212:215], v[156:159], v[128:131]
	v_mfma_f32_16x16x32_bf16 v[100:103], v[204:207], v[168:171], v[100:103]
	v_mfma_f32_16x16x32_bf16 v[96:99], v[212:215], v[168:171], v[96:99]
	v_mfma_f32_16x16x32_bf16 v[84:87], v[204:207], v[176:179], v[84:87]
	v_mfma_f32_16x16x32_bf16 v[80:83], v[212:215], v[176:179], v[80:83]
	v_mfma_f32_16x16x32_bf16 v[68:71], v[204:207], v[196:199], v[68:71]
	v_mfma_f32_16x16x32_bf16 v[64:67], v[212:215], v[196:199], v[64:67]
	s_barrier
	s_add_i32 s4, 0, 0x14000
	s_add_i32 s58, s58, s27
	v_lshl_add_u64 v[216:217], s[20:21], 0, v[146:147]
	s_mov_b32 m0, s58
	global_load_lds_dwordx4 v146, s[20:21]
	v_lshl_add_u64 v[218:219], s[20:21], 0, v[144:145]
	s_add_i32 m0, s58, 0x2000
	s_nop 0
	global_load_lds_dwordx4 v144, s[20:21]
	s_mov_b32 m0, s22
	v_lshl_add_u64 v[220:221], s[24:25], 0, v[146:147]
	ds_read_b128 v[152:155], v163 offset:16384
	ds_read_b128 v[156:159], v163 offset:17408
	ds_read_b128 v[164:167], v163 offset:18432
	ds_read_b128 v[168:171], v163 offset:19456
	ds_read_b128 v[172:175], v163 offset:20480
	ds_read_b128 v[176:179], v163 offset:21504
	ds_read_b128 v[180:183], v163 offset:22528
	ds_read_b128 v[196:199], v163 offset:23552
	global_load_lds_dwordx4 v146, s[24:25]
	v_lshl_add_u64 v[222:223], s[24:25], 0, v[144:145]
	s_mov_b32 m0, s23
	s_nop 0
	global_load_lds_dwordx4 v144, s[24:25]
	s_waitcnt vmcnt(6)
	s_waitcnt lgkmcnt(0)
	s_barrier
	v_mfma_f32_16x16x32_bf16 v[60:63], v[104:107], v[152:155], v[60:63]
	v_mfma_f32_16x16x32_bf16 v[56:59], v[116:119], v[152:155], v[56:59]
	v_mfma_f32_16x16x32_bf16 v[44:47], v[104:107], v[164:167], v[44:47]
	v_mfma_f32_16x16x32_bf16 v[40:43], v[116:119], v[164:167], v[40:43]
	v_mfma_f32_16x16x32_bf16 v[28:31], v[104:107], v[172:175], v[28:31]
	v_mfma_f32_16x16x32_bf16 v[24:27], v[116:119], v[172:175], v[24:27]
	v_mfma_f32_16x16x32_bf16 v[12:15], v[104:107], v[180:183], v[12:15]
	v_mfma_f32_16x16x32_bf16 v[8:11], v[116:119], v[180:183], v[8:11]
	v_mfma_f32_16x16x32_bf16 v[60:63], v[108:111], v[156:159], v[60:63]
	v_mfma_f32_16x16x32_bf16 v[56:59], v[124:127], v[156:159], v[56:59]
	v_mfma_f32_16x16x32_bf16 v[44:47], v[108:111], v[168:171], v[44:47]
	v_mfma_f32_16x16x32_bf16 v[40:43], v[124:127], v[168:171], v[40:43]
	v_mfma_f32_16x16x32_bf16 v[28:31], v[108:111], v[176:179], v[28:31]
	v_mfma_f32_16x16x32_bf16 v[24:27], v[124:127], v[176:179], v[24:27]
	v_mfma_f32_16x16x32_bf16 v[12:15], v[108:111], v[196:199], v[12:15]
	v_mfma_f32_16x16x32_bf16 v[8:11], v[124:127], v[196:199], v[8:11]
	v_mfma_f32_16x16x32_bf16 v[52:55], v[200:203], v[152:155], v[52:55]
	v_mfma_f32_16x16x32_bf16 v[48:51], v[208:211], v[152:155], v[48:51]
	v_mfma_f32_16x16x32_bf16 v[36:39], v[200:203], v[164:167], v[36:39]
	v_mfma_f32_16x16x32_bf16 v[32:35], v[208:211], v[164:167], v[32:35]
	v_mfma_f32_16x16x32_bf16 v[20:23], v[200:203], v[172:175], v[20:23]
	v_mfma_f32_16x16x32_bf16 v[16:19], v[208:211], v[172:175], v[16:19]
	v_mfma_f32_16x16x32_bf16 v[4:7], v[200:203], v[180:183], v[4:7]
	v_mfma_f32_16x16x32_bf16 v[0:3], v[208:211], v[180:183], v[0:3]
	v_mfma_f32_16x16x32_bf16 v[52:55], v[204:207], v[156:159], v[52:55]
	v_mfma_f32_16x16x32_bf16 v[48:51], v[212:215], v[156:159], v[48:51]
	v_mfma_f32_16x16x32_bf16 v[36:39], v[204:207], v[168:171], v[36:39]
	v_mfma_f32_16x16x32_bf16 v[32:35], v[212:215], v[168:171], v[32:35]
	v_mfma_f32_16x16x32_bf16 v[20:23], v[204:207], v[176:179], v[20:23]
	v_mfma_f32_16x16x32_bf16 v[16:19], v[212:215], v[176:179], v[16:19]
	v_mfma_f32_16x16x32_bf16 v[4:7], v[204:207], v[196:199], v[4:7]
	v_mfma_f32_16x16x32_bf16 v[0:3], v[212:215], v[196:199], v[0:3]
	s_barrier
	s_add_u32 s58, s20, 0x200000
	s_addc_u32 s59, s21, 0
	s_add_i32 s4, s4, s27
	s_mov_b32 m0, s4
	s_nop 0
	global_load_lds_dwordx4 v146, s[58:59]
	s_add_i32 m0, s4, 0x2000
	s_nop 0
	global_load_lds_dwordx4 v144, s[58:59]
	s_add_i32 s4, 0, 0x18000
	v_add_u32_e32 v124, s4, v161
	ds_read_b128 v[104:107], v124
	ds_read_b128 v[108:111], v124 offset:1024
	ds_read_b128 v[116:119], v124 offset:2048
	ds_read_b128 v[124:127], v124 offset:3072
	s_add_u32 s24, s24, 0x200000
	s_addc_u32 s25, s25, 0
	s_mov_b32 m0, s30
	ds_read_b128 v[152:155], v163 offset:32768
	ds_read_b128 v[156:159], v163 offset:33792
	ds_read_b128 v[164:167], v163 offset:34816
	ds_read_b128 v[168:171], v163 offset:35840
	ds_read_b128 v[172:175], v163 offset:36864
	ds_read_b128 v[176:179], v163 offset:37888
	ds_read_b128 v[180:183], v163 offset:38912
	ds_read_b128 v[196:199], v163 offset:39936
	v_add_u32_e32 v212, 0x1c000, v161
	ds_read_b128 v[200:203], v212
	ds_read_b128 v[204:207], v212 offset:1024
	ds_read_b128 v[208:211], v212 offset:2048
	ds_read_b128 v[212:215], v212 offset:3072
	global_load_lds_dwordx4 v146, s[24:25]
	s_mov_b32 m0, s31
	s_nop 0
	global_load_lds_dwordx4 v144, s[24:25]
	s_waitcnt vmcnt(8)
	s_waitcnt lgkmcnt(0)
	s_barrier
	v_mfma_f32_16x16x32_bf16 v[140:143], v[104:107], v[152:155], v[140:143]
	v_mfma_f32_16x16x32_bf16 v[136:139], v[116:119], v[152:155], v[136:139]
	v_mfma_f32_16x16x32_bf16 v[120:123], v[104:107], v[164:167], v[120:123]
	v_mfma_f32_16x16x32_bf16 v[112:115], v[116:119], v[164:167], v[112:115]
	v_mfma_f32_16x16x32_bf16 v[92:95], v[104:107], v[172:175], v[92:95]
	v_mfma_f32_16x16x32_bf16 v[88:91], v[116:119], v[172:175], v[88:91]
	v_mfma_f32_16x16x32_bf16 v[76:79], v[104:107], v[180:183], v[76:79]
	v_mfma_f32_16x16x32_bf16 v[72:75], v[116:119], v[180:183], v[72:75]
	v_mfma_f32_16x16x32_bf16 v[140:143], v[108:111], v[156:159], v[140:143]
	v_mfma_f32_16x16x32_bf16 v[136:139], v[124:127], v[156:159], v[136:139]
	v_mfma_f32_16x16x32_bf16 v[120:123], v[108:111], v[168:171], v[120:123]
	v_mfma_f32_16x16x32_bf16 v[112:115], v[124:127], v[168:171], v[112:115]
	v_mfma_f32_16x16x32_bf16 v[92:95], v[108:111], v[176:179], v[92:95]
	v_mfma_f32_16x16x32_bf16 v[88:91], v[124:127], v[176:179], v[88:91]
	v_mfma_f32_16x16x32_bf16 v[76:79], v[108:111], v[196:199], v[76:79]
	v_mfma_f32_16x16x32_bf16 v[72:75], v[124:127], v[196:199], v[72:75]
	v_mfma_f32_16x16x32_bf16 v[132:135], v[200:203], v[152:155], v[132:135]
	v_mfma_f32_16x16x32_bf16 v[128:131], v[208:211], v[152:155], v[128:131]
	v_mfma_f32_16x16x32_bf16 v[100:103], v[200:203], v[164:167], v[100:103]
	v_mfma_f32_16x16x32_bf16 v[96:99], v[208:211], v[164:167], v[96:99]
	v_mfma_f32_16x16x32_bf16 v[84:87], v[200:203], v[172:175], v[84:87]
	v_mfma_f32_16x16x32_bf16 v[80:83], v[208:211], v[172:175], v[80:83]
	v_mfma_f32_16x16x32_bf16 v[68:71], v[200:203], v[180:183], v[68:71]
	v_mfma_f32_16x16x32_bf16 v[64:67], v[208:211], v[180:183], v[64:67]
	v_mfma_f32_16x16x32_bf16 v[132:135], v[204:207], v[156:159], v[132:135]
	v_mfma_f32_16x16x32_bf16 v[128:131], v[212:215], v[156:159], v[128:131]
	v_mfma_f32_16x16x32_bf16 v[100:103], v[204:207], v[168:171], v[100:103]
	v_mfma_f32_16x16x32_bf16 v[96:99], v[212:215], v[168:171], v[96:99]
	v_mfma_f32_16x16x32_bf16 v[84:87], v[204:207], v[176:179], v[84:87]
	v_mfma_f32_16x16x32_bf16 v[80:83], v[212:215], v[176:179], v[80:83]
	v_mfma_f32_16x16x32_bf16 v[68:71], v[204:207], v[196:199], v[68:71]
	v_mfma_f32_16x16x32_bf16 v[64:67], v[212:215], v[196:199], v[64:67]
	s_barrier
	s_add_i32 s24, 0, 0x1c000
	s_add_i32 s4, s4, s27
	v_lshl_add_u64 v[216:217], v[216:217], 0, s[0:1]
	s_mov_b32 m0, s4
	global_load_lds_dwordx4 v[216:217], off
	v_lshl_add_u64 v[216:217], v[218:219], 0, s[0:1]
	s_add_i32 m0, s4, 0x2000
	s_nop 0
	global_load_lds_dwordx4 v[216:217], off
	s_mov_b32 m0, s16
	v_lshl_add_u64 v[216:217], v[220:221], 0, s[0:1]
	ds_read_b128 v[152:155], v163 offset:49152
	ds_read_b128 v[156:159], v163 offset:50176
	ds_read_b128 v[164:167], v163 offset:51200
	ds_read_b128 v[168:171], v163 offset:52224
	ds_read_b128 v[172:175], v163 offset:53248
	ds_read_b128 v[176:179], v163 offset:54272
	ds_read_b128 v[180:183], v163 offset:55296
	ds_read_b128 v[196:199], v163 offset:56320
	global_load_lds_dwordx4 v[216:217], off
	v_lshl_add_u64 v[216:217], v[222:223], 0, s[0:1]
	s_mov_b32 m0, s17
	s_nop 0
	global_load_lds_dwordx4 v[216:217], off
	s_add_u32 s20, s20, 0x200080
	s_addc_u32 s21, s21, 0
	s_add_i32 s4, s24, s27
	s_mov_b32 m0, s4
	s_nop 0
	global_load_lds_dwordx4 v146, s[20:21]
	s_add_i32 m0, s4, 0x2000
	s_nop 0
	global_load_lds_dwordx4 v144, s[20:21]
	s_waitcnt vmcnt(8)
	s_waitcnt lgkmcnt(0)
	s_barrier
	v_mfma_f32_16x16x32_bf16 v[60:63], v[104:107], v[152:155], v[60:63]
	v_mfma_f32_16x16x32_bf16 v[56:59], v[116:119], v[152:155], v[56:59]
	v_mfma_f32_16x16x32_bf16 v[44:47], v[104:107], v[164:167], v[44:47]
	v_mfma_f32_16x16x32_bf16 v[40:43], v[116:119], v[164:167], v[40:43]
	v_mfma_f32_16x16x32_bf16 v[28:31], v[104:107], v[172:175], v[28:31]
	v_mfma_f32_16x16x32_bf16 v[24:27], v[116:119], v[172:175], v[24:27]
	v_mfma_f32_16x16x32_bf16 v[12:15], v[104:107], v[180:183], v[12:15]
	v_mfma_f32_16x16x32_bf16 v[8:11], v[116:119], v[180:183], v[8:11]
	v_mfma_f32_16x16x32_bf16 v[60:63], v[108:111], v[156:159], v[60:63]
	v_mfma_f32_16x16x32_bf16 v[56:59], v[124:127], v[156:159], v[56:59]
	v_mfma_f32_16x16x32_bf16 v[44:47], v[108:111], v[168:171], v[44:47]
	v_mfma_f32_16x16x32_bf16 v[40:43], v[124:127], v[168:171], v[40:43]
	v_mfma_f32_16x16x32_bf16 v[28:31], v[108:111], v[176:179], v[28:31]
	v_mfma_f32_16x16x32_bf16 v[24:27], v[124:127], v[176:179], v[24:27]
	v_mfma_f32_16x16x32_bf16 v[12:15], v[108:111], v[196:199], v[12:15]
	v_mfma_f32_16x16x32_bf16 v[8:11], v[124:127], v[196:199], v[8:11]
	v_mfma_f32_16x16x32_bf16 v[52:55], v[200:203], v[152:155], v[52:55]
	v_mfma_f32_16x16x32_bf16 v[48:51], v[208:211], v[152:155], v[48:51]
	v_mfma_f32_16x16x32_bf16 v[36:39], v[200:203], v[164:167], v[36:39]
	v_mfma_f32_16x16x32_bf16 v[32:35], v[208:211], v[164:167], v[32:35]
	v_mfma_f32_16x16x32_bf16 v[20:23], v[200:203], v[172:175], v[20:23]
	v_mfma_f32_16x16x32_bf16 v[16:19], v[208:211], v[172:175], v[16:19]
	v_mfma_f32_16x16x32_bf16 v[4:7], v[200:203], v[180:183], v[4:7]
	v_mfma_f32_16x16x32_bf16 v[0:3], v[208:211], v[180:183], v[0:3]
	v_mfma_f32_16x16x32_bf16 v[52:55], v[204:207], v[156:159], v[52:55]
	v_mfma_f32_16x16x32_bf16 v[48:51], v[212:215], v[156:159], v[48:51]
	v_mfma_f32_16x16x32_bf16 v[36:39], v[204:207], v[168:171], v[36:39]
	v_mfma_f32_16x16x32_bf16 v[32:35], v[212:215], v[168:171], v[32:35]
	v_mfma_f32_16x16x32_bf16 v[20:23], v[204:207], v[176:179], v[20:23]
	v_mfma_f32_16x16x32_bf16 v[16:19], v[212:215], v[176:179], v[16:19]
	v_mfma_f32_16x16x32_bf16 v[4:7], v[204:207], v[196:199], v[4:7]
	v_mfma_f32_16x16x32_bf16 v[0:3], v[212:215], v[196:199], v[0:3]
	s_add_i32 vcc_hi, vcc_hi, 2
	s_add_u32 s12, s12, 0x100
	s_addc_u32 s13, s13, 0
	s_add_u32 s69, s69, 0x100
	s_addc_u32 vcc_lo, vcc_lo, 0
	s_cmpk_gt_u32 vcc_hi, 0x7d
	s_barrier
	s_cbranch_scc0 .LBB0_889
	s_lshl_b32 s4, s56, 8
	s_add_i32 s4, s4, s35
	s_min_i32 s12, s4, 0x4000
	s_ashr_i32 s12, s12, 11
	s_mul_hi_i32 s13, s12, 0xc000
	s_mul_i32 s12, s12, 0xc000
	v_lshl_or_b32 v154, s53, 8, v162
	s_add_u32 s12, s8, s12
	s_addc_u32 s13, s9, s13
	v_ashrrev_i32_e32 v155, 31, v154
	v_lshl_add_u64 v[104:105], v[154:155], 2, s[12:13]
	global_load_dwordx4 v[124:127], v[104:105], off
	global_load_dwordx4 v[116:119], v[104:105], off offset:64
	global_load_dwordx4 v[108:111], v[104:105], off offset:512
	s_nop 0
	global_load_dwordx4 v[104:107], v[104:105], off offset:576
	v_add_u32_e32 v152, s4, v160
	s_movk_i32 s4, 0x3fff
	v_cmp_lt_i32_e32 vcc, s4, v152
	s_and_saveexec_b64 s[12:13], vcc
	s_xor_b64 s[12:13], exec, s[12:13]
	v_add_u32_e32 v186, 0xffffc000, v152
	v_lshlrev_b64 v[156:157], 13, v[186:187]
	v_mov_b32_e32 v153, v187
	v_lshl_add_u64 v[158:159], s[10:11], 0, v[156:157]
	v_lshlrev_b64 v[156:157], 13, v[152:153]
	s_andn2_saveexec_b64 s[12:13], s[12:13]
	v_ashrrev_i32_e32 v153, 31, v152
	v_lshlrev_b64 v[156:157], 13, v[152:153]
	v_lshl_add_u64 v[158:159], s[66:67], 0, v[156:157]
	s_or_b64 exec, exec, s[12:13]
	v_lshlrev_b64 v[154:155], 2, v[154:155]
	v_lshl_add_u64 v[158:159], v[158:159], 0, v[154:155]
	global_load_dwordx4 v[164:167], v[158:159], off
	v_lshl_add_u64 v[156:157], s[66:67], 0, v[156:157]
	v_lshl_add_u64 v[156:157], v[156:157], 0, v[154:155]
	s_movk_i32 s4, 0x3fef
	v_cmp_lt_i32_e32 vcc, s4, v152
	s_waitcnt vmcnt(0)
	v_pk_fma_f32 v[142:143], v[142:143], v[126:127], v[166:167]
	v_pk_fma_f32 v[140:141], v[140:141], v[124:125], v[164:165]
	global_store_dwordx4 v[156:157], v[140:143], off
	global_load_dwordx4 v[140:143], v[158:159], off offset:64
	s_waitcnt vmcnt(0)
	v_pk_fma_f32 v[138:139], v[138:139], v[118:119], v[142:143]
	v_pk_fma_f32 v[136:137], v[136:137], v[116:117], v[140:141]
	global_store_dwordx4 v[156:157], v[136:139], off offset:64
	global_load_dwordx4 v[136:139], v[158:159], off offset:512
	s_waitcnt vmcnt(0)
	v_pk_fma_f32 v[134:135], v[134:135], v[110:111], v[138:139]
	v_pk_fma_f32 v[132:133], v[132:133], v[108:109], v[136:137]
	global_store_dwordx4 v[156:157], v[132:135], off offset:512
	global_load_dwordx4 v[134:137], v[158:159], off offset:576
	s_waitcnt vmcnt(0)
	v_pk_fma_f32 v[130:131], v[130:131], v[106:107], v[136:137]
	v_or_b32_e32 v132, 16, v152
	v_pk_fma_f32 v[128:129], v[128:129], v[104:105], v[134:135]
	global_store_dwordx4 v[156:157], v[128:131], off offset:576
	s_and_saveexec_b64 s[12:13], vcc
	s_xor_b64 s[12:13], exec, s[12:13]
	v_add_u32_e32 v186, 0xffffc010, v152
	v_lshlrev_b64 v[128:129], 13, v[186:187]
	v_mov_b32_e32 v133, v187
	v_lshl_add_u64 v[130:131], s[10:11], 0, v[128:129]
	v_lshlrev_b64 v[128:129], 13, v[132:133]
	s_andn2_saveexec_b64 s[12:13], s[12:13]
	v_ashrrev_i32_e32 v133, 31, v132
	v_lshlrev_b64 v[128:129], 13, v[132:133]
	v_lshl_add_u64 v[130:131], s[66:67], 0, v[128:129]
	s_or_b64 exec, exec, s[12:13]
	v_lshl_add_u64 v[134:135], v[130:131], 0, v[154:155]
	global_load_dwordx4 v[130:133], v[134:135], off
	v_lshl_add_u64 v[128:129], s[66:67], 0, v[128:129]
	v_lshl_add_u64 v[128:129], v[128:129], 0, v[154:155]
	s_movk_i32 s4, 0x3fdf
	v_cmp_lt_i32_e32 vcc, s4, v152
	s_waitcnt vmcnt(0)
	v_pk_fma_f32 v[122:123], v[122:123], v[126:127], v[132:133]
	v_pk_fma_f32 v[120:121], v[120:121], v[124:125], v[130:131]
	global_store_dwordx4 v[128:129], v[120:123], off
	global_load_dwordx4 v[120:123], v[134:135], off offset:64
	s_waitcnt vmcnt(0)
	v_pk_fma_f32 v[114:115], v[114:115], v[118:119], v[122:123]
	v_pk_fma_f32 v[112:113], v[112:113], v[116:117], v[120:121]
	global_store_dwordx4 v[128:129], v[112:115], off offset:64
	global_load_dwordx4 v[112:115], v[134:135], off offset:512
	s_waitcnt vmcnt(0)
	v_pk_fma_f32 v[102:103], v[102:103], v[110:111], v[114:115]
	v_pk_fma_f32 v[100:101], v[100:101], v[108:109], v[112:113]
	global_store_dwordx4 v[128:129], v[100:103], off offset:512
	global_load_dwordx4 v[112:115], v[134:135], off offset:576
	s_waitcnt vmcnt(0)
	v_pk_fma_f32 v[98:99], v[98:99], v[106:107], v[114:115]
	v_or_b32_e32 v100, 32, v152
	v_pk_fma_f32 v[96:97], v[96:97], v[104:105], v[112:113]
	global_store_dwordx4 v[128:129], v[96:99], off offset:576
	s_and_saveexec_b64 s[12:13], vcc
	s_xor_b64 s[12:13], exec, s[12:13]
	v_add_u32_e32 v186, 0xffffc020, v152
	v_lshlrev_b64 v[96:97], 13, v[186:187]
	v_mov_b32_e32 v101, v187
	v_lshl_add_u64 v[98:99], s[10:11], 0, v[96:97]
	v_lshlrev_b64 v[96:97], 13, v[100:101]
	s_andn2_saveexec_b64 s[12:13], s[12:13]
	v_ashrrev_i32_e32 v101, 31, v100
	v_lshlrev_b64 v[96:97], 13, v[100:101]
	v_lshl_add_u64 v[98:99], s[66:67], 0, v[96:97]
	s_or_b64 exec, exec, s[12:13]
	v_lshl_add_u64 v[102:103], v[98:99], 0, v[154:155]
	global_load_dwordx4 v[98:101], v[102:103], off
	v_lshl_add_u64 v[96:97], s[66:67], 0, v[96:97]
	v_lshl_add_u64 v[96:97], v[96:97], 0, v[154:155]
	s_movk_i32 s4, 0x3fcf
	v_cmp_lt_i32_e32 vcc, s4, v152
	s_waitcnt vmcnt(0)
	v_pk_fma_f32 v[94:95], v[94:95], v[126:127], v[100:101]
	v_pk_fma_f32 v[92:93], v[92:93], v[124:125], v[98:99]
	global_store_dwordx4 v[96:97], v[92:95], off
	global_load_dwordx4 v[92:95], v[102:103], off offset:64
	s_waitcnt vmcnt(0)
	v_pk_fma_f32 v[90:91], v[90:91], v[118:119], v[94:95]
	v_pk_fma_f32 v[88:89], v[88:89], v[116:117], v[92:93]
	global_store_dwordx4 v[96:97], v[88:91], off offset:64
	global_load_dwordx4 v[88:91], v[102:103], off offset:512
	s_waitcnt vmcnt(0)
	v_pk_fma_f32 v[86:87], v[86:87], v[110:111], v[90:91]
	v_pk_fma_f32 v[84:85], v[84:85], v[108:109], v[88:89]
	global_store_dwordx4 v[96:97], v[84:87], off offset:512
	global_load_dwordx4 v[86:89], v[102:103], off offset:576
	s_waitcnt vmcnt(0)
	v_pk_fma_f32 v[82:83], v[82:83], v[106:107], v[88:89]
	v_or_b32_e32 v84, 48, v152
	v_pk_fma_f32 v[80:81], v[80:81], v[104:105], v[86:87]
	global_store_dwordx4 v[96:97], v[80:83], off offset:576
	s_and_saveexec_b64 s[12:13], vcc
	s_xor_b64 s[12:13], exec, s[12:13]
	v_add_u32_e32 v186, 0xffffc030, v152
	v_lshlrev_b64 v[80:81], 13, v[186:187]
	v_mov_b32_e32 v85, v187
	v_lshl_add_u64 v[82:83], s[10:11], 0, v[80:81]
	v_lshlrev_b64 v[80:81], 13, v[84:85]
	s_andn2_saveexec_b64 s[12:13], s[12:13]
	v_ashrrev_i32_e32 v85, 31, v84
	v_lshlrev_b64 v[80:81], 13, v[84:85]
	v_lshl_add_u64 v[82:83], s[66:67], 0, v[80:81]
	s_or_b64 exec, exec, s[12:13]
	v_lshl_add_u64 v[86:87], v[82:83], 0, v[154:155]
	global_load_dwordx4 v[82:85], v[86:87], off
	v_lshl_add_u64 v[80:81], s[66:67], 0, v[80:81]
	v_lshl_add_u64 v[80:81], v[80:81], 0, v[154:155]
	s_movk_i32 s4, 0x3f7f
	v_cmp_lt_i32_e32 vcc, s4, v152
	s_waitcnt vmcnt(0)
	v_pk_fma_f32 v[78:79], v[78:79], v[126:127], v[84:85]
	v_pk_fma_f32 v[76:77], v[76:77], v[124:125], v[82:83]
	global_store_dwordx4 v[80:81], v[76:79], off
	global_load_dwordx4 v[76:79], v[86:87], off offset:64
	s_waitcnt vmcnt(0)
	v_pk_fma_f32 v[74:75], v[74:75], v[118:119], v[78:79]
	v_pk_fma_f32 v[72:73], v[72:73], v[116:117], v[76:77]
	global_store_dwordx4 v[80:81], v[72:75], off offset:64
	global_load_dwordx4 v[72:75], v[86:87], off offset:512
	s_waitcnt vmcnt(0)
	v_pk_fma_f32 v[70:71], v[70:71], v[110:111], v[74:75]
	v_pk_fma_f32 v[68:69], v[68:69], v[108:109], v[72:73]
	global_store_dwordx4 v[80:81], v[68:71], off offset:512
	global_load_dwordx4 v[70:73], v[86:87], off offset:576
	s_waitcnt vmcnt(0)
	v_pk_fma_f32 v[66:67], v[66:67], v[106:107], v[72:73]
	v_add_u32_e32 v68, 0x80, v152
	v_pk_fma_f32 v[64:65], v[64:65], v[104:105], v[70:71]
	global_store_dwordx4 v[80:81], v[64:67], off offset:576
	s_and_saveexec_b64 s[12:13], vcc
	s_xor_b64 s[12:13], exec, s[12:13]
	v_add_u32_e32 v186, 0xffffc080, v152
	v_lshlrev_b64 v[64:65], 13, v[186:187]
	v_mov_b32_e32 v69, v187
	v_lshl_add_u64 v[66:67], s[10:11], 0, v[64:65]
	v_lshlrev_b64 v[64:65], 13, v[68:69]
	s_andn2_saveexec_b64 s[12:13], s[12:13]
	v_ashrrev_i32_e32 v69, 31, v68
	v_lshlrev_b64 v[64:65], 13, v[68:69]
	v_lshl_add_u64 v[66:67], s[66:67], 0, v[64:65]
	s_or_b64 exec, exec, s[12:13]
	v_lshl_add_u64 v[70:71], v[66:67], 0, v[154:155]
	global_load_dwordx4 v[66:69], v[70:71], off
	v_lshl_add_u64 v[64:65], s[66:67], 0, v[64:65]
	v_lshl_add_u64 v[64:65], v[64:65], 0, v[154:155]
	s_movk_i32 s4, 0x3f6f
	v_cmp_lt_i32_e32 vcc, s4, v152
	s_waitcnt vmcnt(0)
	v_pk_fma_f32 v[62:63], v[62:63], v[126:127], v[68:69]
	v_pk_fma_f32 v[60:61], v[60:61], v[124:125], v[66:67]
	global_store_dwordx4 v[64:65], v[60:63], off
	global_load_dwordx4 v[60:63], v[70:71], off offset:64
	s_waitcnt vmcnt(0)
	v_pk_fma_f32 v[58:59], v[58:59], v[118:119], v[62:63]
	v_pk_fma_f32 v[56:57], v[56:57], v[116:117], v[60:61]
	global_store_dwordx4 v[64:65], v[56:59], off offset:64
	global_load_dwordx4 v[56:59], v[70:71], off offset:512
	s_waitcnt vmcnt(0)
	v_pk_fma_f32 v[54:55], v[54:55], v[110:111], v[58:59]
	v_pk_fma_f32 v[52:53], v[52:53], v[108:109], v[56:57]
	global_store_dwordx4 v[64:65], v[52:55], off offset:512
	global_load_dwordx4 v[54:57], v[70:71], off offset:576
	s_waitcnt vmcnt(0)
	v_pk_fma_f32 v[50:51], v[50:51], v[106:107], v[56:57]
	v_add_u32_e32 v52, 0x90, v152
	v_pk_fma_f32 v[48:49], v[48:49], v[104:105], v[54:55]
	global_store_dwordx4 v[64:65], v[48:51], off offset:576
	s_and_saveexec_b64 s[12:13], vcc
	s_xor_b64 s[12:13], exec, s[12:13]
	v_add_u32_e32 v186, 0xffffc090, v152
	v_lshlrev_b64 v[48:49], 13, v[186:187]
	v_mov_b32_e32 v53, v187
	v_lshl_add_u64 v[50:51], s[10:11], 0, v[48:49]
	v_lshlrev_b64 v[48:49], 13, v[52:53]
	s_andn2_saveexec_b64 s[12:13], s[12:13]
	v_ashrrev_i32_e32 v53, 31, v52
	v_lshlrev_b64 v[48:49], 13, v[52:53]
	v_lshl_add_u64 v[50:51], s[66:67], 0, v[48:49]
	s_or_b64 exec, exec, s[12:13]
	v_lshl_add_u64 v[54:55], v[50:51], 0, v[154:155]
	global_load_dwordx4 v[50:53], v[54:55], off
	v_lshl_add_u64 v[48:49], s[66:67], 0, v[48:49]
	v_lshl_add_u64 v[48:49], v[48:49], 0, v[154:155]
	s_movk_i32 s4, 0x3f5f
	v_cmp_lt_i32_e32 vcc, s4, v152
	s_waitcnt vmcnt(0)
	v_pk_fma_f32 v[46:47], v[46:47], v[126:127], v[52:53]
	v_pk_fma_f32 v[44:45], v[44:45], v[124:125], v[50:51]
	global_store_dwordx4 v[48:49], v[44:47], off
	global_load_dwordx4 v[44:47], v[54:55], off offset:64
	s_waitcnt vmcnt(0)
	v_pk_fma_f32 v[42:43], v[42:43], v[118:119], v[46:47]
	v_pk_fma_f32 v[40:41], v[40:41], v[116:117], v[44:45]
	global_store_dwordx4 v[48:49], v[40:43], off offset:64
	global_load_dwordx4 v[40:43], v[54:55], off offset:512
	s_waitcnt vmcnt(0)
	v_pk_fma_f32 v[38:39], v[38:39], v[110:111], v[42:43]
	v_pk_fma_f32 v[36:37], v[36:37], v[108:109], v[40:41]
	global_store_dwordx4 v[48:49], v[36:39], off offset:512
	global_load_dwordx4 v[38:41], v[54:55], off offset:576
	s_waitcnt vmcnt(0)
	v_pk_fma_f32 v[34:35], v[34:35], v[106:107], v[40:41]
	v_add_u32_e32 v36, 0xa0, v152
	v_pk_fma_f32 v[32:33], v[32:33], v[104:105], v[38:39]
	global_store_dwordx4 v[48:49], v[32:35], off offset:576
	s_and_saveexec_b64 s[12:13], vcc
	s_xor_b64 s[12:13], exec, s[12:13]
	v_add_u32_e32 v186, 0xffffc0a0, v152
	v_lshlrev_b64 v[32:33], 13, v[186:187]
	v_mov_b32_e32 v37, v187
	v_lshl_add_u64 v[34:35], s[10:11], 0, v[32:33]
	v_lshlrev_b64 v[32:33], 13, v[36:37]
	s_andn2_saveexec_b64 s[12:13], s[12:13]
	v_ashrrev_i32_e32 v37, 31, v36
	v_lshlrev_b64 v[32:33], 13, v[36:37]
	v_lshl_add_u64 v[34:35], s[66:67], 0, v[32:33]
	s_or_b64 exec, exec, s[12:13]
	v_lshl_add_u64 v[38:39], v[34:35], 0, v[154:155]
	global_load_dwordx4 v[34:37], v[38:39], off
	v_lshl_add_u64 v[32:33], s[66:67], 0, v[32:33]
	v_lshl_add_u64 v[32:33], v[32:33], 0, v[154:155]
	s_movk_i32 s4, 0x3f4f
	v_cmp_lt_i32_e32 vcc, s4, v152
	s_waitcnt vmcnt(0)
	v_pk_fma_f32 v[30:31], v[30:31], v[126:127], v[36:37]
	v_pk_fma_f32 v[28:29], v[28:29], v[124:125], v[34:35]
	global_store_dwordx4 v[32:33], v[28:31], off
	global_load_dwordx4 v[28:31], v[38:39], off offset:64
	s_waitcnt vmcnt(0)
	v_pk_fma_f32 v[26:27], v[26:27], v[118:119], v[30:31]
	v_pk_fma_f32 v[24:25], v[24:25], v[116:117], v[28:29]
	global_store_dwordx4 v[32:33], v[24:27], off offset:64
	global_load_dwordx4 v[24:27], v[38:39], off offset:512
	s_waitcnt vmcnt(0)
	v_pk_fma_f32 v[22:23], v[22:23], v[110:111], v[26:27]
	v_pk_fma_f32 v[20:21], v[20:21], v[108:109], v[24:25]
	global_store_dwordx4 v[32:33], v[20:23], off offset:512
	global_load_dwordx4 v[22:25], v[38:39], off offset:576
	s_waitcnt vmcnt(0)
	v_pk_fma_f32 v[18:19], v[18:19], v[106:107], v[24:25]
	v_add_u32_e32 v20, 0xb0, v152
	v_pk_fma_f32 v[16:17], v[16:17], v[104:105], v[22:23]
	global_store_dwordx4 v[32:33], v[16:19], off offset:576
	s_and_saveexec_b64 s[12:13], vcc
	s_xor_b64 s[12:13], exec, s[12:13]
	v_add_u32_e32 v186, 0xffffc0b0, v152
	v_lshlrev_b64 v[16:17], 13, v[186:187]
	v_mov_b32_e32 v21, v187
	v_lshl_add_u64 v[16:17], s[10:11], 0, v[16:17]
	v_lshlrev_b64 v[18:19], 13, v[20:21]
	s_andn2_saveexec_b64 s[12:13], s[12:13]
	s_cbranch_execz .LBB0_881
	v_ashrrev_i32_e32 v21, 31, v20
	v_lshlrev_b64 v[18:19], 13, v[20:21]
	v_lshl_add_u64 v[16:17], s[66:67], 0, v[18:19]
	s_branch .LBB0_881

.LBB0_926:
	s_andn2_b64 vcc, exec, s[2:3]
	s_cbranch_vccnz .LBB0_1018
	v_mov_b32_e32 v1, v184
	s_and_b64 vcc, exec, s[42:43]
	v_readfirstlane_b32 s16, v1
	s_cbranch_vccnz .LBB0_1018
	v_lshlrev_b32_e32 v5, 4, v1
	v_add_u32_e32 v2, 0x2000, v5
	v_ashrrev_i32_e32 v0, 31, v2
	v_lshrrev_b32_e32 v0, 22, v0
	v_add_u32_e32 v0, v2, v0
	v_ashrrev_i32_e32 v0, 10, v0
	s_waitcnt lgkmcnt(0)
	v_lshlrev_b32_e32 v3, 5, v0
	v_and_b32_e32 v4, 32, v3
	v_mul_i32_i24_e32 v3, 0x400, v0
	v_sub_u32_e32 v2, v2, v3
	v_lshrrev_b32_e32 v3, 4, v2
	v_bitop3_b32 v3, v3, v2, 32 bitop3:0x6c
	v_ashrrev_i32_e32 v2, 31, v3
	v_lshrrev_b32_e32 v2, 26, v2
	v_add_u32_e32 v6, v3, v2
	v_ashrrev_i32_e32 v2, 6, v6
	v_and_b32_e32 v6, 0xc0, v6
	v_sub_u32_e32 v3, v3, v6
	v_ashrrev_i16_sdwa v3, v230, sext(v3) dst_sel:DWORD dst_unused:UNUSED_PAD src0_sel:DWORD src1_sel:BYTE_0
	v_lshlrev_b32_e32 v6, 3, v0
	v_bfe_i32 v3, v3, 0, 16
	v_and_b32_e32 v6, 0x3fff0, v6
	v_add_u32_e32 v4, v4, v3
	v_add_lshl_u32 v6, v2, v6, 14
	v_lshl_add_u32 v128, v4, 1, v6
	v_ashrrev_i32_e32 v4, 31, v1
	v_lshrrev_b32_e32 v4, 26, v4
	v_add_u32_e32 v4, v1, v4
	v_ashrrev_i32_e32 v4, 6, v4
	v_lshlrev_b32_e32 v6, 5, v4
	v_and_b32_e32 v7, 32, v6
	v_bfe_i32 v6, v1, 27, 1
	v_lshrrev_b32_e32 v6, 22, v6
	v_add_u32_e32 v6, v5, v6
	v_and_b32_e32 v6, 0xfffffc00, v6
	v_sub_u32_e32 v5, v5, v6
	v_lshrrev_b32_e32 v6, 4, v5
	v_bitop3_b32 v6, v6, v5, 32 bitop3:0x6c
	v_ashrrev_i32_e32 v5, 31, v6
	v_lshrrev_b32_e32 v5, 26, v5
	v_add_u32_e32 v8, v6, v5
	v_ashrrev_i32_e32 v5, 6, v8
	v_and_b32_e32 v8, 0xc0, v8
	v_sub_u32_e32 v6, v6, v8
	s_ashr_i32 s2, s16, 6
	v_ashrrev_i16_sdwa v6, v230, sext(v6) dst_sel:DWORD dst_unused:UNUSED_PAD src0_sel:DWORD src1_sel:BYTE_0
	v_lshlrev_b32_e32 v8, 3, v4
	s_lshl_b32 s17, s2, 10
	v_bfe_i32 v6, v6, 0, 16
	v_and_b32_e32 v8, 0x3fff0, v8
	v_add_u32_e32 v7, v7, v6
	v_add_lshl_u32 v8, v5, v8, 14
	s_add_i32 s23, s17, 0
	v_readlane_b32 s12, v252, 29
	v_lshl_add_u32 v186, v7, 1, v8
	s_add_i32 m0, s23, 0x10000
	v_readlane_b32 s13, v252, 30
	s_add_i32 s30, s23, 0x2000
	s_add_i32 s31, s23, 0x4000
	s_add_i32 s52, s23, 0x6000
	s_ashr_i32 s3, s16, 8
	s_nop 0
	global_load_lds_dwordx4 v186, s[12:13]
	s_add_i32 m0, s23, 0x12000
	s_nop 0
	global_load_lds_dwordx4 v128, s[12:13]
	v_readlane_b32 s12, v252, 25
	s_mov_b32 m0, s23
	v_readlane_b32 s13, v252, 26
	s_nop 4
	global_load_lds_dwordx4 v186, s[12:13]
	s_mov_b32 m0, s30
	s_nop 0
	global_load_lds_dwordx4 v128, s[12:13]
	v_readlane_b32 s12, v252, 23
	s_add_i32 m0, s23, 0x14000
	v_readlane_b32 s13, v252, 24
	s_nop 4
	global_load_lds_dwordx4 v186, s[12:13]
	s_add_i32 m0, s23, 0x16000
	s_cmp_lg_u32 s3, 1
	global_load_lds_dwordx4 v128, s[12:13]
	v_readlane_b32 s12, v252, 27
	s_mov_b32 m0, s31
	v_readlane_b32 s13, v252, 28
	s_nop 4
	global_load_lds_dwordx4 v186, s[12:13]
	s_mov_b32 m0, s52
	s_nop 0
	global_load_lds_dwordx4 v128, s[12:13]
	s_cbranch_scc1 .LBB0_930
	s_setprio 1
	s_barrier

.LBB0_940:
	s_add_u32 s24, s2, vcc_lo
	s_addc_u32 s25, s3, vcc_hi
	s_add_u32 s24, s24, 0x100
	s_addc_u32 s25, s25, 0
	s_add_u32 s61, s19, vcc_lo
	s_addc_u32 s62, s4, vcc_hi
	s_add_i32 s63, 0, 0x10000
	v_add_u32_e32 v152, s63, v138
	ds_read_b128 v[140:143], v152
	ds_read_b128 v[144:147], v152 offset:1024
	ds_read_b128 v[148:151], v152 offset:2048
	ds_read_b128 v[152:155], v152 offset:3072
	s_cmpk_eq_i32 vcc_lo, 0x3f00
	s_cselect_b32 s27, s39, s25
	s_cselect_b32 s26, s58, s24
	s_cselect_b32 s25, s29, s62
	s_cselect_b32 s24, s59, s61
	v_lshl_add_u64 v[182:183], v[134:135], 0, vcc
	s_add_i32 m0, s23, 0xc000
	ds_read_b128 v[156:159], v139
	ds_read_b128 v[162:165], v139 offset:1024
	ds_read_b128 v[166:169], v139 offset:2048
	ds_read_b128 v[170:173], v139 offset:3072
	ds_read_b128 v[174:177], v139 offset:4096
	ds_read_b128 v[178:181], v139 offset:5120
	ds_read_b128 v[196:199], v139 offset:6144
	ds_read_b128 v[200:203], v139 offset:7168
	global_load_lds_dwordx4 v[182:183], off
	v_lshl_add_u64 v[182:183], v[136:137], 0, vcc
	s_add_i32 m0, s23, 0xe000
	s_nop 0
	global_load_lds_dwordx4 v[182:183], off
	v_add_u32_e32 v216, 0x14000, v138
	ds_read_b128 v[204:207], v216
	ds_read_b128 v[208:211], v216 offset:1024
	ds_read_b128 v[212:215], v216 offset:2048
	ds_read_b128 v[216:219], v216 offset:3072
	s_waitcnt vmcnt(8)
	s_waitcnt lgkmcnt(0)
	s_barrier
	v_mfma_f32_16x16x32_bf16 v[124:127], v[140:143], v[156:159], v[124:127]
	v_mfma_f32_16x16x32_bf16 v[120:123], v[148:151], v[156:159], v[120:123]
	v_mfma_f32_16x16x32_bf16 v[108:111], v[140:143], v[166:169], v[108:111]
	v_mfma_f32_16x16x32_bf16 v[104:107], v[148:151], v[166:169], v[104:107]
	v_mfma_f32_16x16x32_bf16 v[92:95], v[140:143], v[174:177], v[92:95]
	v_mfma_f32_16x16x32_bf16 v[88:91], v[148:151], v[174:177], v[88:91]
	v_mfma_f32_16x16x32_bf16 v[76:79], v[140:143], v[196:199], v[76:79]
	v_mfma_f32_16x16x32_bf16 v[72:75], v[148:151], v[196:199], v[72:75]
	v_mfma_f32_16x16x32_bf16 v[124:127], v[144:147], v[162:165], v[124:127]
	v_mfma_f32_16x16x32_bf16 v[120:123], v[152:155], v[162:165], v[120:123]
	v_mfma_f32_16x16x32_bf16 v[108:111], v[144:147], v[170:173], v[108:111]
	v_mfma_f32_16x16x32_bf16 v[104:107], v[152:155], v[170:173], v[104:107]
	v_mfma_f32_16x16x32_bf16 v[92:95], v[144:147], v[178:181], v[92:95]
	v_mfma_f32_16x16x32_bf16 v[88:91], v[152:155], v[178:181], v[88:91]
	v_mfma_f32_16x16x32_bf16 v[76:79], v[144:147], v[200:203], v[76:79]
	v_mfma_f32_16x16x32_bf16 v[72:75], v[152:155], v[200:203], v[72:75]
	v_mfma_f32_16x16x32_bf16 v[116:119], v[204:207], v[156:159], v[116:119]
	v_mfma_f32_16x16x32_bf16 v[112:115], v[212:215], v[156:159], v[112:115]
	v_mfma_f32_16x16x32_bf16 v[100:103], v[204:207], v[166:169], v[100:103]
	v_mfma_f32_16x16x32_bf16 v[96:99], v[212:215], v[166:169], v[96:99]
	v_mfma_f32_16x16x32_bf16 v[84:87], v[204:207], v[174:177], v[84:87]
	v_mfma_f32_16x16x32_bf16 v[80:83], v[212:215], v[174:177], v[80:83]
	v_mfma_f32_16x16x32_bf16 v[68:71], v[204:207], v[196:199], v[68:71]
	v_mfma_f32_16x16x32_bf16 v[64:67], v[212:215], v[196:199], v[64:67]
	v_mfma_f32_16x16x32_bf16 v[116:119], v[208:211], v[162:165], v[116:119]
	v_mfma_f32_16x16x32_bf16 v[112:115], v[216:219], v[162:165], v[112:115]
	v_mfma_f32_16x16x32_bf16 v[100:103], v[208:211], v[170:173], v[100:103]
	v_mfma_f32_16x16x32_bf16 v[96:99], v[216:219], v[170:173], v[96:99]
	v_mfma_f32_16x16x32_bf16 v[84:87], v[208:211], v[178:181], v[84:87]
	v_mfma_f32_16x16x32_bf16 v[80:83], v[216:219], v[178:181], v[80:83]
	v_mfma_f32_16x16x32_bf16 v[68:71], v[208:211], v[200:203], v[68:71]
	v_mfma_f32_16x16x32_bf16 v[64:67], v[216:219], v[200:203], v[64:67]
	s_barrier
	s_add_i32 s61, 0, 0x14000
	s_add_i32 s62, s63, s17
	v_lshl_add_u64 v[182:183], s[24:25], 0, v[186:187]
	s_mov_b32 m0, s62
	global_load_lds_dwordx4 v186, s[24:25]
	v_lshl_add_u64 v[220:221], s[24:25], 0, v[128:129]
	s_add_i32 m0, s62, 0x2000
	s_nop 0
	global_load_lds_dwordx4 v128, s[24:25]
	s_mov_b32 m0, s23
	v_lshl_add_u64 v[222:223], s[26:27], 0, v[186:187]
	ds_read_b128 v[156:159], v139 offset:16384
	ds_read_b128 v[162:165], v139 offset:17408
	ds_read_b128 v[166:169], v139 offset:18432
	ds_read_b128 v[170:173], v139 offset:19456
	ds_read_b128 v[174:177], v139 offset:20480
	ds_read_b128 v[178:181], v139 offset:21504
	ds_read_b128 v[196:199], v139 offset:22528
	ds_read_b128 v[200:203], v139 offset:23552
	global_load_lds_dwordx4 v186, s[26:27]
	v_lshl_add_u64 v[224:225], s[26:27], 0, v[128:129]
	s_mov_b32 m0, s30
	s_nop 0
	global_load_lds_dwordx4 v128, s[26:27]
	s_waitcnt vmcnt(6)
	s_waitcnt lgkmcnt(0)
	s_barrier
	v_mfma_f32_16x16x32_bf16 v[60:63], v[140:143], v[156:159], v[60:63]
	v_mfma_f32_16x16x32_bf16 v[56:59], v[148:151], v[156:159], v[56:59]
	v_mfma_f32_16x16x32_bf16 v[44:47], v[140:143], v[166:169], v[44:47]
	v_mfma_f32_16x16x32_bf16 v[40:43], v[148:151], v[166:169], v[40:43]
	v_mfma_f32_16x16x32_bf16 v[32:35], v[140:143], v[174:177], v[32:35]
	v_mfma_f32_16x16x32_bf16 v[24:27], v[148:151], v[174:177], v[24:27]
	v_mfma_f32_16x16x32_bf16 v[16:19], v[140:143], v[196:199], v[16:19]
	v_mfma_f32_16x16x32_bf16 v[8:11], v[148:151], v[196:199], v[8:11]
	v_mfma_f32_16x16x32_bf16 v[60:63], v[144:147], v[162:165], v[60:63]
	v_mfma_f32_16x16x32_bf16 v[56:59], v[152:155], v[162:165], v[56:59]
	v_mfma_f32_16x16x32_bf16 v[44:47], v[144:147], v[170:173], v[44:47]
	v_mfma_f32_16x16x32_bf16 v[40:43], v[152:155], v[170:173], v[40:43]
	v_mfma_f32_16x16x32_bf16 v[32:35], v[144:147], v[178:181], v[32:35]
	v_mfma_f32_16x16x32_bf16 v[24:27], v[152:155], v[178:181], v[24:27]
	v_mfma_f32_16x16x32_bf16 v[16:19], v[144:147], v[200:203], v[16:19]
	v_mfma_f32_16x16x32_bf16 v[8:11], v[152:155], v[200:203], v[8:11]
	v_mfma_f32_16x16x32_bf16 v[52:55], v[204:207], v[156:159], v[52:55]
	v_mfma_f32_16x16x32_bf16 v[48:51], v[212:215], v[156:159], v[48:51]
	v_mfma_f32_16x16x32_bf16 v[36:39], v[204:207], v[166:169], v[36:39]
	v_mfma_f32_16x16x32_bf16 v[28:31], v[212:215], v[166:169], v[28:31]
	v_mfma_f32_16x16x32_bf16 v[20:23], v[204:207], v[174:177], v[20:23]
	v_mfma_f32_16x16x32_bf16 v[12:15], v[212:215], v[174:177], v[12:15]
	v_mfma_f32_16x16x32_bf16 v[4:7], v[204:207], v[196:199], v[4:7]
	v_mfma_f32_16x16x32_bf16 v[0:3], v[212:215], v[196:199], v[0:3]
	v_mfma_f32_16x16x32_bf16 v[52:55], v[208:211], v[162:165], v[52:55]
	v_mfma_f32_16x16x32_bf16 v[48:51], v[216:219], v[162:165], v[48:51]
	v_mfma_f32_16x16x32_bf16 v[36:39], v[208:211], v[170:173], v[36:39]
	v_mfma_f32_16x16x32_bf16 v[28:31], v[216:219], v[170:173], v[28:31]
	v_mfma_f32_16x16x32_bf16 v[20:23], v[208:211], v[178:181], v[20:23]
	v_mfma_f32_16x16x32_bf16 v[12:15], v[216:219], v[178:181], v[12:15]
	v_mfma_f32_16x16x32_bf16 v[4:7], v[208:211], v[200:203], v[4:7]
	v_mfma_f32_16x16x32_bf16 v[0:3], v[216:219], v[200:203], v[0:3]
	s_barrier
	s_add_u32 s62, s24, 0x200000
	s_addc_u32 s63, s25, 0
	s_add_i32 s61, s61, s17
	s_mov_b32 m0, s61
	s_nop 0
	global_load_lds_dwordx4 v186, s[62:63]
	s_add_i32 m0, s61, 0x2000
	s_nop 0
	global_load_lds_dwordx4 v128, s[62:63]
	s_add_i32 s61, 0, 0x18000
	v_add_u32_e32 v152, s61, v138
	ds_read_b128 v[140:143], v152
	ds_read_b128 v[144:147], v152 offset:1024
	ds_read_b128 v[148:151], v152 offset:2048
	ds_read_b128 v[152:155], v152 offset:3072
	s_add_u32 s26, s26, 0x200000
	s_addc_u32 s27, s27, 0
	s_mov_b32 m0, s31
	ds_read_b128 v[156:159], v139 offset:32768
	ds_read_b128 v[162:165], v139 offset:33792
	ds_read_b128 v[166:169], v139 offset:34816
	ds_read_b128 v[170:173], v139 offset:35840
	ds_read_b128 v[174:177], v139 offset:36864
	ds_read_b128 v[178:181], v139 offset:37888
	ds_read_b128 v[196:199], v139 offset:38912
	ds_read_b128 v[200:203], v139 offset:39936
	v_add_u32_e32 v216, 0x1c000, v138
	ds_read_b128 v[204:207], v216
	ds_read_b128 v[208:211], v216 offset:1024
	ds_read_b128 v[212:215], v216 offset:2048
	ds_read_b128 v[216:219], v216 offset:3072
	global_load_lds_dwordx4 v186, s[26:27]
	s_mov_b32 m0, s52
	s_nop 0
	global_load_lds_dwordx4 v128, s[26:27]
	s_waitcnt vmcnt(8)
	s_waitcnt lgkmcnt(0)
	s_barrier
	v_mfma_f32_16x16x32_bf16 v[124:127], v[140:143], v[156:159], v[124:127]
	v_mfma_f32_16x16x32_bf16 v[120:123], v[148:151], v[156:159], v[120:123]
	v_mfma_f32_16x16x32_bf16 v[108:111], v[140:143], v[166:169], v[108:111]
	v_mfma_f32_16x16x32_bf16 v[104:107], v[148:151], v[166:169], v[104:107]
	v_mfma_f32_16x16x32_bf16 v[92:95], v[140:143], v[174:177], v[92:95]
	v_mfma_f32_16x16x32_bf16 v[88:91], v[148:151], v[174:177], v[88:91]
	v_mfma_f32_16x16x32_bf16 v[76:79], v[140:143], v[196:199], v[76:79]
	v_mfma_f32_16x16x32_bf16 v[72:75], v[148:151], v[196:199], v[72:75]
	v_mfma_f32_16x16x32_bf16 v[124:127], v[144:147], v[162:165], v[124:127]
	v_mfma_f32_16x16x32_bf16 v[120:123], v[152:155], v[162:165], v[120:123]
	v_mfma_f32_16x16x32_bf16 v[108:111], v[144:147], v[170:173], v[108:111]
	v_mfma_f32_16x16x32_bf16 v[104:107], v[152:155], v[170:173], v[104:107]
	v_mfma_f32_16x16x32_bf16 v[92:95], v[144:147], v[178:181], v[92:95]
	v_mfma_f32_16x16x32_bf16 v[88:91], v[152:155], v[178:181], v[88:91]
	v_mfma_f32_16x16x32_bf16 v[76:79], v[144:147], v[200:203], v[76:79]
	v_mfma_f32_16x16x32_bf16 v[72:75], v[152:155], v[200:203], v[72:75]
	v_mfma_f32_16x16x32_bf16 v[116:119], v[204:207], v[156:159], v[116:119]
	v_mfma_f32_16x16x32_bf16 v[112:115], v[212:215], v[156:159], v[112:115]
	v_mfma_f32_16x16x32_bf16 v[100:103], v[204:207], v[166:169], v[100:103]
	v_mfma_f32_16x16x32_bf16 v[96:99], v[212:215], v[166:169], v[96:99]
	v_mfma_f32_16x16x32_bf16 v[84:87], v[204:207], v[174:177], v[84:87]
	v_mfma_f32_16x16x32_bf16 v[80:83], v[212:215], v[174:177], v[80:83]
	v_mfma_f32_16x16x32_bf16 v[68:71], v[204:207], v[196:199], v[68:71]
	v_mfma_f32_16x16x32_bf16 v[64:67], v[212:215], v[196:199], v[64:67]
	v_mfma_f32_16x16x32_bf16 v[116:119], v[208:211], v[162:165], v[116:119]
	v_mfma_f32_16x16x32_bf16 v[112:115], v[216:219], v[162:165], v[112:115]
	v_mfma_f32_16x16x32_bf16 v[100:103], v[208:211], v[170:173], v[100:103]
	v_mfma_f32_16x16x32_bf16 v[96:99], v[216:219], v[170:173], v[96:99]
	v_mfma_f32_16x16x32_bf16 v[84:87], v[208:211], v[178:181], v[84:87]
	v_mfma_f32_16x16x32_bf16 v[80:83], v[216:219], v[178:181], v[80:83]
	v_mfma_f32_16x16x32_bf16 v[68:71], v[208:211], v[200:203], v[68:71]
	v_mfma_f32_16x16x32_bf16 v[64:67], v[216:219], v[200:203], v[64:67]
	s_barrier
	s_add_i32 s26, 0, 0x1c000
	s_add_i32 s27, s61, s17
	v_lshl_add_u64 v[182:183], v[182:183], 0, s[0:1]
	s_mov_b32 m0, s27
	global_load_lds_dwordx4 v[182:183], off
	v_lshl_add_u64 v[182:183], v[220:221], 0, s[0:1]
	s_add_i32 m0, s27, 0x2000
	s_nop 0
	global_load_lds_dwordx4 v[182:183], off
	s_mov_b32 m0, s53
	v_lshl_add_u64 v[182:183], v[222:223], 0, s[0:1]
	ds_read_b128 v[156:159], v139 offset:49152
	ds_read_b128 v[162:165], v139 offset:50176
	ds_read_b128 v[166:169], v139 offset:51200
	ds_read_b128 v[170:173], v139 offset:52224
	ds_read_b128 v[174:177], v139 offset:53248
	ds_read_b128 v[178:181], v139 offset:54272
	ds_read_b128 v[196:199], v139 offset:55296
	ds_read_b128 v[200:203], v139 offset:56320
	global_load_lds_dwordx4 v[182:183], off
	v_lshl_add_u64 v[182:183], v[224:225], 0, s[0:1]
	s_mov_b32 m0, s68
	s_nop 0
	global_load_lds_dwordx4 v[182:183], off
	s_add_u32 s24, s24, 0x200080
	s_addc_u32 s25, s25, 0
	s_add_i32 s26, s26, s17
	s_mov_b32 m0, s26
	s_nop 0
	global_load_lds_dwordx4 v186, s[24:25]
	s_add_i32 m0, s26, 0x2000
	s_nop 0
	global_load_lds_dwordx4 v128, s[24:25]
	s_waitcnt vmcnt(8)
	s_waitcnt lgkmcnt(0)
	s_barrier
	v_mfma_f32_16x16x32_bf16 v[60:63], v[140:143], v[156:159], v[60:63]
	v_mfma_f32_16x16x32_bf16 v[56:59], v[148:151], v[156:159], v[56:59]
	v_mfma_f32_16x16x32_bf16 v[44:47], v[140:143], v[166:169], v[44:47]
	v_mfma_f32_16x16x32_bf16 v[40:43], v[148:151], v[166:169], v[40:43]
	v_mfma_f32_16x16x32_bf16 v[32:35], v[140:143], v[174:177], v[32:35]
	v_mfma_f32_16x16x32_bf16 v[24:27], v[148:151], v[174:177], v[24:27]
	v_mfma_f32_16x16x32_bf16 v[16:19], v[140:143], v[196:199], v[16:19]
	v_mfma_f32_16x16x32_bf16 v[8:11], v[148:151], v[196:199], v[8:11]
	v_mfma_f32_16x16x32_bf16 v[60:63], v[144:147], v[162:165], v[60:63]
	v_mfma_f32_16x16x32_bf16 v[56:59], v[152:155], v[162:165], v[56:59]
	v_mfma_f32_16x16x32_bf16 v[44:47], v[144:147], v[170:173], v[44:47]
	v_mfma_f32_16x16x32_bf16 v[40:43], v[152:155], v[170:173], v[40:43]
	v_mfma_f32_16x16x32_bf16 v[32:35], v[144:147], v[178:181], v[32:35]
	v_mfma_f32_16x16x32_bf16 v[24:27], v[152:155], v[178:181], v[24:27]
	v_mfma_f32_16x16x32_bf16 v[16:19], v[144:147], v[200:203], v[16:19]
	v_mfma_f32_16x16x32_bf16 v[8:11], v[152:155], v[200:203], v[8:11]
	v_mfma_f32_16x16x32_bf16 v[52:55], v[204:207], v[156:159], v[52:55]
	v_mfma_f32_16x16x32_bf16 v[48:51], v[212:215], v[156:159], v[48:51]
	v_mfma_f32_16x16x32_bf16 v[36:39], v[204:207], v[166:169], v[36:39]
	v_mfma_f32_16x16x32_bf16 v[28:31], v[212:215], v[166:169], v[28:31]
	v_mfma_f32_16x16x32_bf16 v[20:23], v[204:207], v[174:177], v[20:23]
	v_mfma_f32_16x16x32_bf16 v[12:15], v[212:215], v[174:177], v[12:15]
	v_mfma_f32_16x16x32_bf16 v[4:7], v[204:207], v[196:199], v[4:7]
	v_mfma_f32_16x16x32_bf16 v[0:3], v[212:215], v[196:199], v[0:3]
	v_mfma_f32_16x16x32_bf16 v[52:55], v[208:211], v[162:165], v[52:55]
	v_mfma_f32_16x16x32_bf16 v[48:51], v[216:219], v[162:165], v[48:51]
	v_mfma_f32_16x16x32_bf16 v[36:39], v[208:211], v[170:173], v[36:39]
	v_mfma_f32_16x16x32_bf16 v[28:31], v[216:219], v[170:173], v[28:31]
	v_mfma_f32_16x16x32_bf16 v[20:23], v[208:211], v[178:181], v[20:23]
	v_mfma_f32_16x16x32_bf16 v[12:15], v[216:219], v[178:181], v[12:15]
	v_mfma_f32_16x16x32_bf16 v[4:7], v[208:211], v[200:203], v[4:7]
	v_mfma_f32_16x16x32_bf16 v[0:3], v[216:219], v[200:203], v[0:3]
	s_add_i32 s60, s60, 2
	s_add_u32 vcc_lo, vcc_lo, 0x100
	s_addc_u32 vcc_hi, vcc_hi, 0
	s_cmpk_gt_u32 s60, 0x7d
	s_barrier
	s_cbranch_scc0 .LBB0_940
	s_add_u32 s24, s19, 0xffffff00
	s_addc_u32 s25, s4, -1
	s_andn2_b64 vcc, exec, s[44:45]
	s_cbranch_vccnz .LBB0_931
	v_mov_b32_e32 v0, 0
	s_mov_b32 s18, s28
	s_mov_b32 s56, s38
	s_mov_b64 s[2:3], s[20:21]
	s_mov_b32 s69, s57
	v_mov_b32_e32 v1, v0
	v_mov_b32_e32 v2, v0
	v_mov_b32_e32 v3, v0
	v_mov_b32_e32 v4, v0
	v_mov_b32_e32 v5, v0
	v_mov_b32_e32 v6, v0
	v_mov_b32_e32 v7, v0
	v_mov_b32_e32 v12, v0
	v_mov_b32_e32 v13, v0
	v_mov_b32_e32 v14, v0
	v_mov_b32_e32 v15, v0
	v_mov_b32_e32 v20, v0
	v_mov_b32_e32 v21, v0
	v_mov_b32_e32 v22, v0
	v_mov_b32_e32 v23, v0
	v_mov_b32_e32 v28, v0
	v_mov_b32_e32 v29, v0
	v_mov_b32_e32 v30, v0
	v_mov_b32_e32 v31, v0
	v_mov_b32_e32 v36, v0
	v_mov_b32_e32 v37, v0
	v_mov_b32_e32 v38, v0
	v_mov_b32_e32 v39, v0
	v_mov_b32_e32 v48, v0
	v_mov_b32_e32 v49, v0
	v_mov_b32_e32 v50, v0
	v_mov_b32_e32 v51, v0
	v_mov_b32_e32 v52, v0
	v_mov_b32_e32 v53, v0
	v_mov_b32_e32 v54, v0
	v_mov_b32_e32 v55, v0
	v_mov_b32_e32 v8, v0
	v_mov_b32_e32 v9, v0
	v_mov_b32_e32 v10, v0
	v_mov_b32_e32 v11, v0
	v_mov_b32_e32 v16, v0
	v_mov_b32_e32 v17, v0
	v_mov_b32_e32 v18, v0
	v_mov_b32_e32 v19, v0
	v_mov_b32_e32 v24, v0
	v_mov_b32_e32 v25, v0
	v_mov_b32_e32 v26, v0
	v_mov_b32_e32 v27, v0
	v_mov_b32_e32 v32, v0
	v_mov_b32_e32 v33, v0
	v_mov_b32_e32 v34, v0
	v_mov_b32_e32 v35, v0
	v_mov_b32_e32 v40, v0
	v_mov_b32_e32 v41, v0
	v_mov_b32_e32 v42, v0
	v_mov_b32_e32 v43, v0
	v_mov_b32_e32 v44, v0
	v_mov_b32_e32 v45, v0
	v_mov_b32_e32 v46, v0
	v_mov_b32_e32 v47, v0
	v_mov_b32_e32 v56, v0
	v_mov_b32_e32 v57, v0
	v_mov_b32_e32 v58, v0
	v_mov_b32_e32 v59, v0
	v_mov_b32_e32 v60, v0
	v_mov_b32_e32 v61, v0
	v_mov_b32_e32 v62, v0
	v_mov_b32_e32 v63, v0
	v_mov_b32_e32 v64, v0
	v_mov_b32_e32 v65, v0
	v_mov_b32_e32 v66, v0
	v_mov_b32_e32 v67, v0
	v_mov_b32_e32 v68, v0
	v_mov_b32_e32 v69, v0
	v_mov_b32_e32 v70, v0
	v_mov_b32_e32 v71, v0
	v_mov_b32_e32 v80, v0
	v_mov_b32_e32 v81, v0
	v_mov_b32_e32 v82, v0
	v_mov_b32_e32 v83, v0
	v_mov_b32_e32 v84, v0
	v_mov_b32_e32 v85, v0
	v_mov_b32_e32 v86, v0
	v_mov_b32_e32 v87, v0
	v_mov_b32_e32 v96, v0
	v_mov_b32_e32 v97, v0
	v_mov_b32_e32 v98, v0
	v_mov_b32_e32 v99, v0
	v_mov_b32_e32 v100, v0
	v_mov_b32_e32 v101, v0
	v_mov_b32_e32 v102, v0
	v_mov_b32_e32 v103, v0
	v_mov_b32_e32 v112, v0
	v_mov_b32_e32 v113, v0
	v_mov_b32_e32 v114, v0
	v_mov_b32_e32 v115, v0
	v_mov_b32_e32 v116, v0
	v_mov_b32_e32 v117, v0
	v_mov_b32_e32 v118, v0
	v_mov_b32_e32 v119, v0
	v_mov_b32_e32 v72, v0
	v_mov_b32_e32 v73, v0
	v_mov_b32_e32 v74, v0
	v_mov_b32_e32 v75, v0
	v_mov_b32_e32 v76, v0
	v_mov_b32_e32 v77, v0
	v_mov_b32_e32 v78, v0
	v_mov_b32_e32 v79, v0
	v_mov_b32_e32 v88, v0
	v_mov_b32_e32 v89, v0
	v_mov_b32_e32 v90, v0
	v_mov_b32_e32 v91, v0
	v_mov_b32_e32 v92, v0
	v_mov_b32_e32 v93, v0
	v_mov_b32_e32 v94, v0
	v_mov_b32_e32 v95, v0
	v_mov_b32_e32 v104, v0
	v_mov_b32_e32 v105, v0
	v_mov_b32_e32 v106, v0
	v_mov_b32_e32 v107, v0
	v_mov_b32_e32 v108, v0
	v_mov_b32_e32 v109, v0
	v_mov_b32_e32 v110, v0
	v_mov_b32_e32 v111, v0
	v_mov_b32_e32 v120, v0
	v_mov_b32_e32 v121, v0
	v_mov_b32_e32 v122, v0
	v_mov_b32_e32 v123, v0
	v_mov_b32_e32 v124, v0
	v_mov_b32_e32 v125, v0
	v_mov_b32_e32 v126, v0
	v_mov_b32_e32 v127, v0
	s_andn2_b64 vcc, exec, s[42:43]
	s_cbranch_vccnz .LBB0_932

.LBB0_945:
	s_setprio 0
	s_lshl_b32 s12, s56, 8
	s_add_i32 s12, s12, s35
	s_lshl_b32 s2, s22, 5
	s_min_i32 s3, s12, 0x4000
	s_lshl_b32 s4, s18, 8
	s_ashr_i32 s3, s3, 11
	s_or_b32 s2, s4, s2
	v_add_u32_e32 v198, s12, v233
	v_lshl_or_b32 v226, v160, 2, s2
	s_mul_hi_i32 s4, s3, 0xc000
	s_mul_i32 s3, s3, 0xc000
	v_ashrrev_i32_e32 v199, 31, v198
	s_add_u32 s2, s8, s3
	v_ashrrev_i32_e32 v227, 31, v226
	v_lshlrev_b64 v[144:145], 13, v[198:199]
	s_addc_u32 s3, s9, s4
	v_lshlrev_b64 v[196:197], 2, v[226:227]
	v_lshl_add_u64 v[144:145], s[66:67], 0, v[144:145]
	v_lshl_add_u64 v[128:129], s[2:3], 0, v[196:197]
	v_lshl_add_u64 v[200:201], v[144:145], 0, v[196:197]
	s_barrier
	global_load_dwordx4 v[140:143], v[128:129], off
	global_load_dwordx4 v[136:139], v[128:129], off offset:64
	global_load_dwordx4 v[132:135], v[128:129], off offset:512
	s_nop 0
	global_load_dwordx4 v[128:131], v[128:129], off offset:576
	s_nop 0
	global_load_dwordx4 v[204:207], v[200:201], off
	global_load_dwordx4 v[208:211], v[200:201], off offset:64
	global_load_dwordx4 v[180:183], v[200:201], off offset:512
	global_load_dwordx4 v[176:179], v[200:201], off offset:576
	v_and_b32_e32 v162, 64, v231
	v_xor_b32_e32 v161, 16, v231
	v_add_u32_e32 v162, 64, v162
	v_cmp_lt_i32_e32 vcc, v161, v162
	v_or_b32_e32 v144, 16, v198
	v_cmp_eq_u32_e64 s[42:43], 0, v160
	v_cndmask_b32_e32 v161, v231, v161, vcc
	v_lshlrev_b32_e32 v186, 2, v161
	v_xor_b32_e32 v161, 32, v231
	v_cmp_lt_i32_e32 vcc, v161, v162
	v_or_b32_e32 v160, 32, v198
	v_ashrrev_i32_e32 v145, 31, v144
	v_cndmask_b32_e32 v161, v231, v161, vcc
	v_lshlrev_b32_e32 v235, 2, v161
	v_ashrrev_i32_e32 v161, 31, v160
	v_lshlrev_b64 v[144:145], 13, v[144:145]
	v_lshlrev_b64 v[160:161], 13, v[160:161]
	v_lshl_add_u64 v[144:145], s[66:67], 0, v[144:145]
	v_lshl_add_u64 v[160:161], s[66:67], 0, v[160:161]
	v_lshl_add_u64 v[144:145], v[144:145], 0, v[196:197]
	v_lshl_add_u64 v[160:161], v[160:161], 0, v[196:197]
	global_load_dwordx4 v[156:159], v[144:145], off
	global_load_dwordx4 v[152:155], v[144:145], off offset:64
	global_load_dwordx4 v[148:151], v[144:145], off offset:512
	s_nop 0
	global_load_dwordx4 v[144:147], v[144:145], off offset:576
	s_nop 0
	global_load_dwordx4 v[172:175], v[160:161], off
	global_load_dwordx4 v[168:171], v[160:161], off offset:64
	global_load_dwordx4 v[164:167], v[160:161], off offset:512
	s_nop 0
	global_load_dwordx4 v[160:163], v[160:161], off offset:576
	s_lshl_b32 s2, s22, 2
	s_add_i32 s13, s2, 0
	v_lshl_add_u32 v236, v233, 4, s13
	s_waitcnt vmcnt(0)
	v_pk_fma_f32 v[204:205], v[124:125], v[140:141], v[204:205]
	v_pk_fma_f32 v[208:209], v[120:121], v[136:137], v[208:209]
	v_mul_f32_e32 v124, v205, v205
	v_mul_f32_e32 v120, v209, v209
	v_pk_fma_f32 v[180:181], v[116:117], v[132:133], v[180:181]
	v_pk_fma_f32 v[202:203], v[126:127], v[142:143], v[206:207]
	v_fmac_f32_e32 v124, v204, v204
	v_pk_fma_f32 v[206:207], v[122:123], v[138:139], v[210:211]
	v_fmac_f32_e32 v120, v208, v208
	v_mul_f32_e32 v116, v181, v181
	v_pk_fma_f32 v[216:217], v[112:113], v[128:129], v[176:177]
	v_fmac_f32_e32 v124, v202, v202
	v_fmac_f32_e32 v120, v206, v206
	v_pk_fma_f32 v[182:183], v[118:119], v[134:135], v[182:183]
	v_fmac_f32_e32 v116, v180, v180
	v_mul_f32_e32 v112, v217, v217
	v_fmac_f32_e32 v124, v203, v203
	v_fmac_f32_e32 v120, v207, v207
	v_fmac_f32_e32 v116, v182, v182
	v_pk_fma_f32 v[212:213], v[114:115], v[130:131], v[178:179]
	v_fmac_f32_e32 v112, v216, v216
	v_add_f32_e32 v120, v124, v120
	v_fmac_f32_e32 v116, v183, v183
	v_fmac_f32_e32 v112, v212, v212
	v_add_f32_e32 v116, v120, v116
	v_fmac_f32_e32 v112, v213, v213
	v_add_f32_e32 v112, v116, v112
	ds_bpermute_b32 v113, v186, v112
	s_waitcnt lgkmcnt(0)
	v_add_f32_e32 v112, v112, v113
	ds_bpermute_b32 v113, v235, v112
	s_and_saveexec_b64 s[2:3], s[42:43]
	v_readlane_b32 s19, v252, 38
	s_cbranch_execz .LBB0_947
	s_waitcnt lgkmcnt(0)
	v_add_f32_e32 v112, v112, v113
	ds_write_b32 v236, v112
